# v15 without the swiglu SS prefetch and without the 3-mask count passes
# baseline (speedup 1.0000x reference)
.LBB0_255:
	v_lshl_add_u32 v146, s6, 8, v1
	v_ashrrev_i32_e32 v147, 31, v146
	v_lshlrev_b64 v[156:157], 6, v[146:147]
	v_lshl_add_u64 v[168:169], s[8:9], 0, v[156:157]
	global_load_dwordx4 v[156:159], v[168:169], off
	global_load_dwordx4 v[160:163], v[168:169], off offset:16
	global_load_dwordx4 v[164:167], v[168:169], off offset:32
	s_nop 0
	global_load_dwordx4 v[168:171], v[168:169], off offset:48
	v_mov_b32_e32 v174, v126
	v_mov_b32_e32 v175, v122
	v_mov_b32_e32 v122, v127
	v_mov_b32_e32 v126, v128
	v_mov_b32_e32 v127, v124
	v_mov_b32_e32 v124, v129
	v_mov_b32_e32 v128, v118
	v_mov_b32_e32 v129, v114
	v_mov_b32_e32 v114, v119
	v_lshl_or_b32 v172, s7, 7, v148
	v_ashrrev_i32_e32 v173, 31, v172
	s_waitcnt vmcnt(0)
	v_mov_b32_e32 v118, v157
	v_mov_b32_e32 v119, v158
	v_mov_b32_e32 v157, v159
	v_mov_b32_e32 v158, v161
	v_mov_b32_e32 v159, v162
	v_mov_b32_e32 v161, v163
	v_pk_add_f32 v[118:119], v[118:119], v[156:157]
	v_pk_add_f32 v[156:157], v[158:159], v[160:161]
	v_pk_add_f32 v[118:119], v[118:119], v[118:119] op_sel:[0,1] op_sel_hi:[1,0]
	v_pk_add_f32 v[156:157], v[156:157], v[156:157] op_sel:[0,1] op_sel_hi:[1,0]
	v_add_f32_e32 v162, v164, v165
	v_add_f32_e32 v164, v166, v167
	v_mov_b32_e32 v163, v170
	v_mov_b32_e32 v165, v171
	v_mov_b32_e32 v119, v168
	v_mov_b32_e32 v157, v169
	v_pk_add_f32 v[158:159], v[162:163], v[164:165]
	v_pk_add_f32 v[118:119], v[118:119], v[156:157]
	s_nop 0
	v_pk_add_f32 v[118:119], v[118:119], v[158:159]
	s_nop 0
	v_add_f32_e32 v118, v118, v119
	v_fmamk_f32 v118, v118, 0x3a800000, v152
	v_mul_f32_e32 v119, 0x4f800000, v118
	v_cmp_gt_f32_e32 vcc, s49, v118
	s_nop 1
	v_cndmask_b32_e32 v147, v118, v119, vcc
	v_sqrt_f32_e32 v156, v147
	v_mov_b32_e32 v118, v120
	v_mov_b32_e32 v119, v116
	v_mov_b32_e32 v116, v121
	v_add_u32_e32 v120, -1, v156
	v_add_u32_e32 v121, 1, v156
	v_fma_f32 v157, -v120, v156, v147
	v_fma_f32 v158, -v121, v156, v147
	v_cmp_ge_f32_e64 s[6:7], 0, v157
	s_nop 1
	v_cndmask_b32_e64 v120, v156, v120, s[6:7]
	v_cmp_lt_f32_e64 s[6:7], 0, v158
	s_nop 1
	v_cndmask_b32_e64 v120, v120, v121, s[6:7]
	v_mul_f32_e32 v121, 0x37800000, v120
	v_cndmask_b32_e32 v120, v120, v121, vcc
	v_cmp_class_f32_e32 vcc, v147, v153
	s_nop 1
	v_cndmask_b32_e32 v120, v120, v147, vcc
	v_div_scale_f32 v121, s[6:7], v120, v120, 1.0
	v_rcp_f32_e32 v147, v121
	v_div_scale_f32 v156, vcc, 1.0, v120, 1.0
	v_fma_f32 v157, -v121, v147, 1.0
	v_fmac_f32_e32 v147, v157, v147
	v_mul_f32_e32 v157, v156, v147
	v_fma_f32 v158, -v121, v157, v156
	v_fmac_f32_e32 v157, v158, v147
	v_fma_f32 v121, -v121, v157, v156
	v_div_fmas_f32 v121, v121, v147, v157
	v_div_fixup_f32 v120, v121, v120, 1.0
	v_pk_mul_f32 v[156:157], v[174:175], v[120:121] op_sel_hi:[1,0]
	v_pk_mul_f32 v[122:123], v[122:123], v[120:121] op_sel_hi:[1,0]
	v_pk_mul_f32 v[114:115], v[114:115], v[120:121] op_sel_hi:[1,0]
	v_pk_mul_f32 v[118:119], v[118:119], v[120:121] op_sel_hi:[1,0]
	v_pk_mul_f32 v[126:127], v[126:127], v[120:121] op_sel_hi:[1,0]
	v_pk_mul_f32 v[124:125], v[124:125], v[120:121] op_sel_hi:[1,0]
	v_pk_mul_f32 v[128:129], v[128:129], v[120:121] op_sel_hi:[1,0]
	v_pk_mul_f32 v[116:117], v[116:117], v[120:121] op_sel_hi:[1,0]
	v_mul_f32_e32 v120, 0xbfb8aa3b, v157
	v_mul_f32_e32 v121, 0xbfb8aa3b, v123
	v_mul_f32_e32 v160, 0xbfb8aa3b, v115
	v_mul_f32_e32 v161, 0xbfb8aa3b, v119
	v_mul_f32_e32 v147, 0xbfb8aa3b, v127
	v_mul_f32_e32 v158, 0xbfb8aa3b, v125
	v_mul_f32_e32 v159, 0xbfb8aa3b, v129
	v_mul_f32_e32 v162, 0xbfb8aa3b, v117
	v_exp_f32_e32 v120, v120
	v_exp_f32_e32 v121, v121
	v_exp_f32_e32 v160, v160
	v_exp_f32_e32 v161, v161
	v_exp_f32_e32 v147, v147
	v_exp_f32_e32 v158, v158
	v_exp_f32_e32 v159, v159
	v_exp_f32_e32 v162, v162
	v_add_f32_e32 v120, 1.0, v120
	v_add_f32_e32 v121, 1.0, v121
	v_add_f32_e32 v160, 1.0, v160
	v_add_f32_e32 v161, 1.0, v161
	v_add_f32_e32 v147, 1.0, v147
	v_add_f32_e32 v158, 1.0, v158
	v_add_f32_e32 v159, 1.0, v159
	v_add_f32_e32 v162, 1.0, v162
	v_rcp_f32_e32 v120, v120
	v_rcp_f32_e32 v121, v121
	v_rcp_f32_e32 v160, v160
	v_rcp_f32_e32 v161, v161
	v_rcp_f32_e32 v147, v147
	v_rcp_f32_e32 v158, v158
	v_rcp_f32_e32 v159, v159
	v_rcp_f32_e32 v162, v162
	v_mul_f32_e32 v120, v157, v120
	v_mul_f32_e32 v121, v123, v121
	v_mul_f32_e32 v115, v115, v160
	v_mul_f32_e32 v119, v119, v161
	v_mul_f32_e32 v123, v127, v147
	v_mul_f32_e32 v125, v125, v158
	v_mul_f32_e32 v127, v129, v159
	v_mul_f32_e32 v117, v117, v162
	v_mul_f32_e32 v120, v156, v120
	v_mul_f32_e32 v121, v122, v121
	v_mul_f32_e32 v114, v114, v115
	v_mul_f32_e32 v115, v118, v119
	v_mul_f32_e32 v122, v126, v123
	v_mul_f32_e32 v123, v124, v125
	v_mul_f32_e32 v124, v128, v127
	v_mul_f32_e32 v116, v116, v117
	v_cvt_pk_bf16_f32 v118, v120, v121
	v_cvt_pk_bf16_f32 v119, v122, v123
	v_cvt_pk_bf16_f32 v120, v124, v114
	v_cvt_pk_bf16_f32 v121, v115, v116
	v_mov_b64_e32 v[114:115], s[10:11]
	v_mad_i64_i32 v[122:123], s[6:7], v146, s50, v[114:115]
	v_lshlrev_b64 v[116:117], 1, v[172:173]
	v_lshl_add_u64 v[122:123], v[122:123], 0, v[116:117]
	global_store_dwordx4 v[122:123], v[118:121], off nt
	s_nop 1
	v_or_b32_e32 v118, 16, v146
	v_ashrrev_i32_e32 v119, 31, v118
	v_lshlrev_b64 v[120:121], 6, v[118:119]
	v_lshl_add_u64 v[128:129], s[8:9], 0, v[120:121]
	global_load_dwordx4 v[120:123], v[128:129], off
	global_load_dwordx4 v[124:127], v[128:129], off offset:16
	global_load_dwordx4 v[156:159], v[128:129], off offset:32
	global_load_dwordx4 v[160:163], v[128:129], off offset:48
	v_mov_b32_e32 v128, v110
	v_mov_b32_e32 v110, v112
	v_mov_b32_e32 v112, v98
	v_mov_b32_e32 v129, v106
	v_mov_b32_e32 v106, v111
	v_mov_b32_e32 v111, v108
	v_mov_b32_e32 v108, v113
	v_mov_b32_e32 v113, v102
	s_waitcnt vmcnt(3)
	v_mov_b32_e32 v164, v121
	v_mov_b32_e32 v165, v122
	v_mov_b32_e32 v121, v123
	s_waitcnt vmcnt(2)
	v_mov_b32_e32 v122, v125
	v_mov_b32_e32 v123, v126
	v_mov_b32_e32 v125, v127
	v_pk_add_f32 v[120:121], v[164:165], v[120:121]
	v_pk_add_f32 v[122:123], v[122:123], v[124:125]
	v_pk_add_f32 v[120:121], v[120:121], v[120:121] op_sel:[0,1] op_sel_hi:[1,0]
	v_pk_add_f32 v[122:123], v[122:123], v[122:123] op_sel:[0,1] op_sel_hi:[1,0]
	s_waitcnt vmcnt(1)
	v_add_f32_e32 v126, v156, v157
	v_add_f32_e32 v156, v158, v159
	s_waitcnt vmcnt(0)
	v_mov_b32_e32 v127, v162
	v_mov_b32_e32 v157, v163
	v_mov_b32_e32 v121, v160
	v_mov_b32_e32 v123, v161
	v_pk_add_f32 v[124:125], v[126:127], v[156:157]
	v_pk_add_f32 v[120:121], v[120:121], v[122:123]
	s_nop 0
	v_pk_add_f32 v[120:121], v[120:121], v[124:125]
	s_nop 0
	v_add_f32_e32 v98, v120, v121
	v_fmamk_f32 v98, v98, 0x3a800000, v152
	v_mul_f32_e32 v102, 0x4f800000, v98
	v_cmp_gt_f32_e32 vcc, s49, v98
	s_nop 1
	v_cndmask_b32_e32 v119, v98, v102, vcc
	v_sqrt_f32_e32 v120, v119
	v_mov_b32_e32 v98, v100
	v_mov_b32_e32 v102, v99
	v_mov_b32_e32 v99, v104
	v_add_u32_e32 v100, -1, v120
	v_add_u32_e32 v104, 1, v120
	v_fma_f32 v121, -v100, v120, v119
	v_fma_f32 v122, -v104, v120, v119
	v_cmp_ge_f32_e64 s[6:7], 0, v121
	s_nop 1
	v_cndmask_b32_e64 v100, v120, v100, s[6:7]
	v_cmp_lt_f32_e64 s[6:7], 0, v122
	s_nop 1
	v_cndmask_b32_e64 v100, v100, v104, s[6:7]
	v_mul_f32_e32 v104, 0x37800000, v100
	v_cndmask_b32_e32 v100, v100, v104, vcc
	v_cmp_class_f32_e32 vcc, v119, v153
	v_mov_b32_e32 v104, v101
	s_nop 0
	v_cndmask_b32_e32 v100, v100, v119, vcc
	v_div_scale_f32 v119, s[6:7], v100, v100, 1.0
	v_rcp_f32_e32 v120, v119
	v_div_scale_f32 v101, vcc, 1.0, v100, 1.0
	v_fma_f32 v121, -v119, v120, 1.0
	v_fmac_f32_e32 v120, v121, v120
	v_mul_f32_e32 v121, v101, v120
	v_fma_f32 v122, -v119, v121, v101
	v_fmac_f32_e32 v121, v122, v120
	v_fma_f32 v101, -v119, v121, v101
	v_div_fmas_f32 v101, v101, v120, v121
	v_div_fixup_f32 v100, v101, v100, 1.0
	v_pk_mul_f32 v[106:107], v[106:107], v[100:101] op_sel_hi:[1,0]
	v_pk_mul_f32 v[110:111], v[110:111], v[100:101] op_sel_hi:[1,0]
	v_pk_mul_f32 v[108:109], v[108:109], v[100:101] op_sel_hi:[1,0]
	v_pk_mul_f32 v[120:121], v[128:129], v[100:101] op_sel_hi:[1,0]
	v_pk_mul_f32 v[112:113], v[112:113], v[100:101] op_sel_hi:[1,0]
	v_pk_mul_f32 v[102:103], v[102:103], v[100:101] op_sel_hi:[1,0]
	v_pk_mul_f32 v[98:99], v[98:99], v[100:101] op_sel_hi:[1,0]
	v_pk_mul_f32 v[100:101], v[104:105], v[100:101] op_sel_hi:[1,0]
	v_mul_f32_e32 v105, 0xbfb8aa3b, v107
	v_mul_f32_e32 v119, 0xbfb8aa3b, v111
	v_mul_f32_e32 v122, 0xbfb8aa3b, v109
	v_exp_f32_e32 v105, v105
	v_exp_f32_e32 v119, v119
	v_exp_f32_e32 v122, v122
	v_mul_f32_e32 v124, 0xbfb8aa3b, v103
	v_mul_f32_e32 v125, 0xbfb8aa3b, v99
	v_mul_f32_e32 v126, 0xbfb8aa3b, v101
	v_exp_f32_e32 v124, v124
	v_exp_f32_e32 v125, v125
	v_add_f32_e32 v105, 1.0, v105
	v_add_f32_e32 v119, 1.0, v119
	v_add_f32_e32 v122, 1.0, v122
	v_mul_f32_e32 v104, 0xbfb8aa3b, v121
	v_mul_f32_e32 v123, 0xbfb8aa3b, v113
	v_exp_f32_e32 v126, v126
	v_rcp_f32_e32 v105, v105
	v_rcp_f32_e32 v119, v119
	v_rcp_f32_e32 v122, v122
	v_exp_f32_e32 v104, v104
	v_exp_f32_e32 v123, v123
	v_add_f32_e32 v124, 1.0, v124
	v_add_f32_e32 v125, 1.0, v125
	v_add_f32_e32 v126, 1.0, v126
	v_rcp_f32_e32 v124, v124
	v_rcp_f32_e32 v125, v125
	v_mul_f32_e32 v105, v107, v105
	v_mul_f32_e32 v107, v111, v119
	v_mul_f32_e32 v109, v109, v122
	v_add_f32_e32 v104, 1.0, v104
	v_add_f32_e32 v123, 1.0, v123
	v_mul_f32_e32 v105, v106, v105
	v_mul_f32_e32 v106, v110, v107
	v_mul_f32_e32 v107, v108, v109
	v_rcp_f32_e32 v109, v126
	v_rcp_f32_e32 v104, v104
	v_rcp_f32_e32 v123, v123
	v_mul_f32_e32 v103, v103, v124
	v_mul_f32_e32 v99, v99, v125
	v_mul_f32_e32 v102, v102, v103
	v_mul_f32_e32 v103, v98, v99
	v_mul_f32_e32 v98, v101, v109
	v_mul_f32_e32 v104, v121, v104
	v_mul_f32_e32 v111, v113, v123
	v_mul_f32_e32 v101, v100, v98
	v_mul_f32_e32 v104, v120, v104
	v_mul_f32_e32 v108, v112, v111
	v_cvt_pk_bf16_f32 v98, v104, v105
	v_cvt_pk_bf16_f32 v99, v106, v107
	v_cvt_pk_bf16_f32 v100, v108, v102
	v_cvt_pk_bf16_f32 v101, v103, v101
	v_mad_i64_i32 v[102:103], s[6:7], v118, s50, v[114:115]
	v_lshl_add_u64 v[102:103], v[102:103], 0, v[116:117]
	global_store_dwordx4 v[102:103], v[98:101], off nt
	s_nop 1
	v_or_b32_e32 v98, 32, v146
	v_ashrrev_i32_e32 v99, 31, v98
	v_lshlrev_b64 v[100:101], 6, v[98:99]
	v_lshl_add_u64 v[112:113], s[8:9], 0, v[100:101]
	global_load_dwordx4 v[100:103], v[112:113], off
	global_load_dwordx4 v[104:107], v[112:113], off offset:16
	global_load_dwordx4 v[108:111], v[112:113], off offset:32
	global_load_dwordx4 v[118:121], v[112:113], off offset:48
	v_mov_b32_e32 v112, v94
	v_mov_b32_e32 v94, v96
	v_mov_b32_e32 v96, v82
	v_mov_b32_e32 v113, v90
	v_mov_b32_e32 v90, v95
	v_mov_b32_e32 v95, v92
	v_mov_b32_e32 v92, v97
	v_mov_b32_e32 v97, v86
	s_waitcnt vmcnt(3)
	v_mov_b32_e32 v122, v101
	v_mov_b32_e32 v123, v102
	v_mov_b32_e32 v101, v103
	s_waitcnt vmcnt(2)
	v_mov_b32_e32 v102, v105
	v_mov_b32_e32 v103, v106
	v_mov_b32_e32 v105, v107
	v_pk_add_f32 v[100:101], v[122:123], v[100:101]
	v_pk_add_f32 v[102:103], v[102:103], v[104:105]
	v_pk_add_f32 v[100:101], v[100:101], v[100:101] op_sel:[0,1] op_sel_hi:[1,0]
	v_pk_add_f32 v[102:103], v[102:103], v[102:103] op_sel:[0,1] op_sel_hi:[1,0]
	s_waitcnt vmcnt(1)
	v_add_f32_e32 v106, v108, v109
	v_add_f32_e32 v108, v110, v111
	s_waitcnt vmcnt(0)
	v_mov_b32_e32 v107, v120
	v_mov_b32_e32 v109, v121
	v_mov_b32_e32 v101, v118
	v_mov_b32_e32 v103, v119
	v_pk_add_f32 v[104:105], v[106:107], v[108:109]
	v_pk_add_f32 v[100:101], v[100:101], v[102:103]
	s_nop 0
	v_pk_add_f32 v[100:101], v[100:101], v[104:105]
	s_nop 0
	v_add_f32_e32 v82, v100, v101
	v_fmamk_f32 v82, v82, 0x3a800000, v152
	v_mul_f32_e32 v86, 0x4f800000, v82
	v_cmp_gt_f32_e32 vcc, s49, v82
	s_nop 1
	v_cndmask_b32_e32 v99, v82, v86, vcc
	v_sqrt_f32_e32 v100, v99
	v_mov_b32_e32 v82, v84
	v_mov_b32_e32 v86, v83
	v_mov_b32_e32 v83, v88
	v_add_u32_e32 v84, -1, v100
	v_add_u32_e32 v88, 1, v100
	v_fma_f32 v101, -v84, v100, v99
	v_fma_f32 v102, -v88, v100, v99
	v_cmp_ge_f32_e64 s[6:7], 0, v101
	s_nop 1
	v_cndmask_b32_e64 v84, v100, v84, s[6:7]
	v_cmp_lt_f32_e64 s[6:7], 0, v102
	s_nop 1
	v_cndmask_b32_e64 v84, v84, v88, s[6:7]
	v_mul_f32_e32 v88, 0x37800000, v84
	v_cndmask_b32_e32 v84, v84, v88, vcc
	v_cmp_class_f32_e32 vcc, v99, v153
	v_mov_b32_e32 v88, v85
	s_nop 0
	v_cndmask_b32_e32 v84, v84, v99, vcc
	v_div_scale_f32 v99, s[6:7], v84, v84, 1.0
	v_rcp_f32_e32 v100, v99
	v_div_scale_f32 v85, vcc, 1.0, v84, 1.0
	v_fma_f32 v101, -v99, v100, 1.0
	v_fmac_f32_e32 v100, v101, v100
	v_mul_f32_e32 v101, v85, v100
	v_fma_f32 v102, -v99, v101, v85
	v_fmac_f32_e32 v101, v102, v100
	v_fma_f32 v85, -v99, v101, v85
	v_div_fmas_f32 v85, v85, v100, v101
	v_div_fixup_f32 v84, v85, v84, 1.0
	v_pk_mul_f32 v[90:91], v[90:91], v[84:85] op_sel_hi:[1,0]
	v_pk_mul_f32 v[94:95], v[94:95], v[84:85] op_sel_hi:[1,0]
	v_pk_mul_f32 v[92:93], v[92:93], v[84:85] op_sel_hi:[1,0]
	v_pk_mul_f32 v[100:101], v[112:113], v[84:85] op_sel_hi:[1,0]
	v_pk_mul_f32 v[96:97], v[96:97], v[84:85] op_sel_hi:[1,0]
	v_pk_mul_f32 v[86:87], v[86:87], v[84:85] op_sel_hi:[1,0]
	v_pk_mul_f32 v[82:83], v[82:83], v[84:85] op_sel_hi:[1,0]
	v_pk_mul_f32 v[84:85], v[88:89], v[84:85] op_sel_hi:[1,0]
	v_mul_f32_e32 v89, 0xbfb8aa3b, v91
	v_mul_f32_e32 v99, 0xbfb8aa3b, v95
	v_mul_f32_e32 v102, 0xbfb8aa3b, v93
	v_exp_f32_e32 v89, v89
	v_exp_f32_e32 v99, v99
	v_exp_f32_e32 v102, v102
	v_mul_f32_e32 v104, 0xbfb8aa3b, v87
	v_add_f32_e32 v89, 1.0, v89
	v_add_f32_e32 v99, 1.0, v99
	v_add_f32_e32 v102, 1.0, v102
	v_rcp_f32_e32 v89, v89
	v_rcp_f32_e32 v99, v99
	v_rcp_f32_e32 v102, v102
	v_mul_f32_e32 v105, 0xbfb8aa3b, v83
	v_mul_f32_e32 v89, v91, v89
	v_mul_f32_e32 v91, v95, v99
	v_mul_f32_e32 v93, v93, v102
	v_exp_f32_e32 v104, v104
	v_exp_f32_e32 v105, v105
	v_mul_f32_e32 v89, v90, v89
	v_mul_f32_e32 v90, v94, v91
	v_mul_f32_e32 v91, v92, v93
	v_mul_f32_e32 v93, 0xbfb8aa3b, v85
	v_mul_f32_e32 v88, 0xbfb8aa3b, v101
	v_mul_f32_e32 v103, 0xbfb8aa3b, v97
	v_exp_f32_e32 v93, v93
	v_exp_f32_e32 v88, v88
	v_exp_f32_e32 v103, v103
	v_add_f32_e32 v104, 1.0, v104
	v_add_f32_e32 v94, 1.0, v105
	v_rcp_f32_e32 v104, v104
	v_rcp_f32_e32 v94, v94
	v_add_f32_e32 v93, 1.0, v93
	v_add_f32_e32 v88, 1.0, v88
	v_add_f32_e32 v103, 1.0, v103
	v_rcp_f32_e32 v93, v93
	v_rcp_f32_e32 v88, v88
	v_rcp_f32_e32 v103, v103
	v_mul_f32_e32 v87, v87, v104
	v_mul_f32_e32 v83, v83, v94
	v_mul_f32_e32 v86, v86, v87
	v_mul_f32_e32 v87, v82, v83
	v_mul_f32_e32 v82, v85, v93
	v_mul_f32_e32 v88, v101, v88
	v_mul_f32_e32 v95, v97, v103
	v_mul_f32_e32 v85, v84, v82
	v_mul_f32_e32 v88, v100, v88
	v_mul_f32_e32 v92, v96, v95
	v_cvt_pk_bf16_f32 v82, v88, v89
	v_cvt_pk_bf16_f32 v83, v90, v91
	v_cvt_pk_bf16_f32 v84, v92, v86
	v_cvt_pk_bf16_f32 v85, v87, v85
	v_mad_i64_i32 v[86:87], s[6:7], v98, s50, v[114:115]
	v_lshl_add_u64 v[86:87], v[86:87], 0, v[116:117]
	global_store_dwordx4 v[86:87], v[82:85], off nt
	v_mov_b32_e32 v100, v78
	v_mov_b32_e32 v101, v74
	v_or_b32_e32 v82, 48, v146
	v_ashrrev_i32_e32 v83, 31, v82
	v_lshlrev_b64 v[84:85], 6, v[82:83]
	v_lshl_add_u64 v[96:97], s[8:9], 0, v[84:85]
	global_load_dwordx4 v[84:87], v[96:97], off
	global_load_dwordx4 v[88:91], v[96:97], off offset:16
	global_load_dwordx4 v[92:95], v[96:97], off offset:32
	s_nop 0
	global_load_dwordx4 v[96:99], v[96:97], off offset:48
	v_mov_b32_e32 v74, v79
	v_mov_b32_e32 v78, v80
	v_mov_b32_e32 v79, v76
	v_mov_b32_e32 v76, v81
	s_waitcnt vmcnt(3)
	v_mov_b32_e32 v80, v85
	v_mov_b32_e32 v81, v86
	v_mov_b32_e32 v85, v87
	s_waitcnt vmcnt(2)
	v_mov_b32_e32 v86, v89
	v_mov_b32_e32 v87, v90
	v_mov_b32_e32 v89, v91
	v_pk_add_f32 v[80:81], v[80:81], v[84:85]
	v_pk_add_f32 v[84:85], v[86:87], v[88:89]
	v_pk_add_f32 v[80:81], v[80:81], v[80:81] op_sel:[0,1] op_sel_hi:[1,0]
	v_pk_add_f32 v[84:85], v[84:85], v[84:85] op_sel:[0,1] op_sel_hi:[1,0]
	s_waitcnt vmcnt(1)
	v_add_f32_e32 v90, v92, v93
	v_add_f32_e32 v92, v94, v95
	s_waitcnt vmcnt(0)
	v_mov_b32_e32 v91, v98
	v_mov_b32_e32 v93, v99
	v_mov_b32_e32 v81, v96
	v_mov_b32_e32 v85, v97
	v_pk_add_f32 v[86:87], v[90:91], v[92:93]
	v_pk_add_f32 v[80:81], v[80:81], v[84:85]
	s_nop 0
	v_pk_add_f32 v[80:81], v[80:81], v[86:87]
	s_nop 0
	v_add_f32_e32 v80, v80, v81
	v_fmamk_f32 v80, v80, 0x3a800000, v152
	v_mul_f32_e32 v81, 0x4f800000, v80
	v_cmp_gt_f32_e32 vcc, s49, v80
	s_nop 1
	v_cndmask_b32_e32 v83, v80, v81, vcc
	v_sqrt_f32_e32 v84, v83
	v_mov_b32_e32 v80, v66
	v_mov_b32_e32 v81, v70
	v_mov_b32_e32 v70, v67
	v_add_u32_e32 v66, -1, v84
	v_add_u32_e32 v67, 1, v84
	v_fma_f32 v85, -v66, v84, v83
	v_fma_f32 v86, -v67, v84, v83
	v_cmp_ge_f32_e64 s[6:7], 0, v85
	s_nop 1
	v_cndmask_b32_e64 v66, v84, v66, s[6:7]
	v_cmp_lt_f32_e64 s[6:7], 0, v86
	s_nop 1
	v_cndmask_b32_e64 v66, v66, v67, s[6:7]
	v_mul_f32_e32 v67, 0x37800000, v66
	v_cndmask_b32_e32 v66, v66, v67, vcc
	v_cmp_class_f32_e32 vcc, v83, v153
	s_nop 1
	v_cndmask_b32_e32 v67, v66, v83, vcc
	v_div_scale_f32 v83, s[6:7], v67, v67, 1.0
	v_rcp_f32_e32 v84, v83
	v_mov_b32_e32 v66, v68
	v_div_scale_f32 v68, vcc, 1.0, v67, 1.0
	v_fma_f32 v85, -v83, v84, 1.0
	v_fmac_f32_e32 v84, v85, v84
	v_mul_f32_e32 v85, v68, v84
	v_fma_f32 v86, -v83, v85, v68
	v_fmac_f32_e32 v85, v86, v84
	v_fma_f32 v68, -v83, v85, v68
	v_div_fmas_f32 v68, v68, v84, v85
	v_div_fixup_f32 v68, v68, v67, 1.0
	v_pk_mul_f32 v[84:85], v[100:101], v[68:69] op_sel_hi:[1,0]
	v_pk_mul_f32 v[74:75], v[74:75], v[68:69] op_sel_hi:[1,0]
	v_mul_f32_e32 v67, 0xbfb8aa3b, v85
	v_mul_f32_e32 v83, 0xbfb8aa3b, v75
	v_exp_f32_e32 v67, v67
	v_pk_mul_f32 v[78:79], v[78:79], v[68:69] op_sel_hi:[1,0]
	v_exp_f32_e32 v83, v83
	v_mul_f32_e32 v86, 0xbfb8aa3b, v79
	v_exp_f32_e32 v86, v86
	v_add_f32_e32 v67, 1.0, v67
	v_add_f32_e32 v83, 1.0, v83
	v_rcp_f32_e32 v67, v67
	v_rcp_f32_e32 v83, v83
	v_add_f32_e32 v86, 1.0, v86
	v_rcp_f32_e32 v86, v86
	v_mul_f32_e32 v67, v85, v67
	v_mul_f32_e32 v75, v75, v83
	v_mul_f32_e32 v83, v84, v67
	v_mov_b32_e32 v67, v72
	v_pk_mul_f32 v[66:67], v[66:67], v[68:69] op_sel_hi:[1,0]
	v_mul_f32_e32 v79, v79, v86
	v_mul_f32_e32 v72, 0xbfb8aa3b, v67
	v_pk_mul_f32 v[70:71], v[70:71], v[68:69] op_sel_hi:[1,0]
	v_mul_f32_e32 v74, v74, v75
	v_mul_f32_e32 v75, v78, v79
	v_exp_f32_e32 v78, v72
	v_mov_b32_e32 v72, v69
	v_pk_mul_f32 v[76:77], v[76:77], v[68:69] op_sel_hi:[1,0]
	v_pk_mul_f32 v[80:81], v[80:81], v[68:69] op_sel_hi:[1,0]
	v_mul_f32_e32 v89, 0xbfb8aa3b, v71
	v_pk_mul_f32 v[68:69], v[72:73], v[68:69] op_sel_hi:[1,0]
	v_exp_f32_e32 v89, v89
	v_mul_f32_e32 v72, 0xbfb8aa3b, v69
	v_mul_f32_e32 v87, 0xbfb8aa3b, v77
	v_mul_f32_e32 v88, 0xbfb8aa3b, v81
	v_exp_f32_e32 v72, v72
	v_exp_f32_e32 v87, v87
	v_exp_f32_e32 v88, v88
	v_add_f32_e32 v89, 1.0, v89
	v_add_f32_e32 v73, 1.0, v78
	v_rcp_f32_e32 v89, v89
	v_rcp_f32_e32 v73, v73
	v_add_f32_e32 v72, 1.0, v72
	v_add_f32_e32 v87, 1.0, v87
	v_add_f32_e32 v88, 1.0, v88
	v_rcp_f32_e32 v72, v72
	v_rcp_f32_e32 v87, v87
	v_rcp_f32_e32 v88, v88
	v_mul_f32_e32 v71, v71, v89
	v_mul_f32_e32 v67, v67, v73
	v_mul_f32_e32 v70, v70, v71
	v_mul_f32_e32 v71, v66, v67
	v_mul_f32_e32 v66, v69, v72
	v_mul_f32_e32 v77, v77, v87
	v_mul_f32_e32 v81, v81, v88
	v_mul_f32_e32 v69, v68, v66
	v_mul_f32_e32 v76, v76, v77
	v_mul_f32_e32 v77, v80, v81
	v_cvt_pk_bf16_f32 v66, v83, v74
	v_cvt_pk_bf16_f32 v67, v75, v76
	v_cvt_pk_bf16_f32 v68, v77, v70
	v_cvt_pk_bf16_f32 v69, v71, v69
	v_mad_i64_i32 v[70:71], s[6:7], v82, s50, v[114:115]
	v_lshl_add_u64 v[70:71], v[70:71], 0, v[116:117]
	global_store_dwordx4 v[70:71], v[66:69], off nt
	v_mov_b32_e32 v85, v58
	v_mov_b32_e32 v58, v63
	v_add_u32_e32 v66, 0x80, v146
	v_ashrrev_i32_e32 v67, 31, v66
	v_lshlrev_b64 v[68:69], 6, v[66:67]
	v_lshl_add_u64 v[80:81], s[8:9], 0, v[68:69]
	global_load_dwordx4 v[68:71], v[80:81], off
	global_load_dwordx4 v[72:75], v[80:81], off offset:16
	global_load_dwordx4 v[76:79], v[80:81], off offset:32
	s_nop 0
	global_load_dwordx4 v[80:83], v[80:81], off offset:48
	v_mov_b32_e32 v63, v60
	v_mov_b32_e32 v84, v62
	v_mov_b32_e32 v62, v64
	s_waitcnt vmcnt(3)
	v_mov_b32_e32 v86, v69
	v_mov_b32_e32 v87, v70
	v_mov_b32_e32 v69, v71
	s_waitcnt vmcnt(2)
	v_mov_b32_e32 v70, v73
	v_mov_b32_e32 v71, v74
	v_mov_b32_e32 v73, v75
	v_pk_add_f32 v[68:69], v[86:87], v[68:69]
	v_pk_add_f32 v[70:71], v[70:71], v[72:73]
	v_pk_add_f32 v[68:69], v[68:69], v[68:69] op_sel:[0,1] op_sel_hi:[1,0]
	v_pk_add_f32 v[70:71], v[70:71], v[70:71] op_sel:[0,1] op_sel_hi:[1,0]
	s_waitcnt vmcnt(1)
	v_add_f32_e32 v74, v76, v77
	v_add_f32_e32 v76, v78, v79
	s_waitcnt vmcnt(0)
	v_mov_b32_e32 v75, v82
	v_mov_b32_e32 v77, v83
	v_mov_b32_e32 v69, v80
	v_mov_b32_e32 v71, v81
	v_pk_add_f32 v[72:73], v[74:75], v[76:77]
	v_pk_add_f32 v[68:69], v[68:69], v[70:71]
	s_nop 0
	v_pk_add_f32 v[68:69], v[68:69], v[72:73]
	s_nop 0
	v_add_f32_e32 v60, v68, v69
	v_fmamk_f32 v60, v60, 0x3a800000, v152
	v_mul_f32_e32 v64, 0x4f800000, v60
	v_cmp_gt_f32_e32 vcc, s49, v60
	s_nop 1
	v_cndmask_b32_e32 v67, v60, v64, vcc
	v_sqrt_f32_e32 v68, v67
	v_mov_b32_e32 v64, v50
	v_mov_b32_e32 v60, v65
	v_mov_b32_e32 v65, v54
	v_add_u32_e32 v50, -1, v68
	v_add_u32_e32 v54, 1, v68
	v_fma_f32 v69, -v50, v68, v67
	v_fma_f32 v70, -v54, v68, v67
	v_cmp_ge_f32_e64 s[6:7], 0, v69
	s_nop 1
	v_cndmask_b32_e64 v50, v68, v50, s[6:7]
	v_cmp_lt_f32_e64 s[6:7], 0, v70
	s_nop 1
	v_cndmask_b32_e64 v50, v50, v54, s[6:7]
	v_mul_f32_e32 v54, 0x37800000, v50
	v_cndmask_b32_e32 v50, v50, v54, vcc
	v_cmp_class_f32_e32 vcc, v67, v153
	v_mov_b32_e32 v54, v51
	s_nop 0
	v_cndmask_b32_e32 v50, v50, v67, vcc
	v_div_scale_f32 v67, s[6:7], v50, v50, 1.0
	v_rcp_f32_e32 v68, v67
	v_div_scale_f32 v51, vcc, 1.0, v50, 1.0
	v_fma_f32 v69, -v67, v68, 1.0
	v_fmac_f32_e32 v68, v69, v68
	v_mul_f32_e32 v69, v51, v68
	v_fma_f32 v70, -v67, v69, v51
	v_fmac_f32_e32 v69, v70, v68
	v_fma_f32 v51, -v67, v69, v51
	v_div_fmas_f32 v51, v51, v68, v69
	v_div_fixup_f32 v50, v51, v50, 1.0
	v_pk_mul_f32 v[68:69], v[84:85], v[50:51] op_sel_hi:[1,0]
	v_pk_mul_f32 v[58:59], v[58:59], v[50:51] op_sel_hi:[1,0]
	v_pk_mul_f32 v[62:63], v[62:63], v[50:51] op_sel_hi:[1,0]
	v_pk_mul_f32 v[60:61], v[60:61], v[50:51] op_sel_hi:[1,0]
	v_pk_mul_f32 v[64:65], v[64:65], v[50:51] op_sel_hi:[1,0]
	v_pk_mul_f32 v[54:55], v[54:55], v[50:51] op_sel_hi:[1,0]
	v_mul_f32_e32 v51, 0xbfb8aa3b, v69
	v_mul_f32_e32 v67, 0xbfb8aa3b, v59
	v_mul_f32_e32 v71, 0xbfb8aa3b, v61
	v_mul_f32_e32 v72, 0xbfb8aa3b, v65
	v_exp_f32_e32 v51, v51
	v_exp_f32_e32 v67, v67
	v_exp_f32_e32 v71, v71
	v_exp_f32_e32 v72, v72
	v_mul_f32_e32 v70, 0xbfb8aa3b, v63
	v_exp_f32_e32 v70, v70
	v_add_f32_e32 v51, 1.0, v51
	v_add_f32_e32 v67, 1.0, v67
	v_add_f32_e32 v71, 1.0, v71
	v_add_f32_e32 v72, 1.0, v72
	v_rcp_f32_e32 v51, v51
	v_mul_f32_e32 v73, 0xbfb8aa3b, v55
	v_rcp_f32_e32 v67, v67
	v_rcp_f32_e32 v71, v71
	v_rcp_f32_e32 v72, v72
	v_exp_f32_e32 v73, v73
	v_add_f32_e32 v70, 1.0, v70
	v_rcp_f32_e32 v70, v70
	v_mul_f32_e32 v51, v69, v51
	v_mul_f32_e32 v59, v59, v67
	v_mul_f32_e32 v61, v61, v71
	v_mul_f32_e32 v67, v68, v51
	v_mul_f32_e32 v51, v65, v72
	v_mul_f32_e32 v68, v58, v59
	v_mul_f32_e32 v60, v60, v61
	v_mul_f32_e32 v61, v64, v51
	v_add_f32_e32 v51, 1.0, v73
	v_mov_b32_e32 v58, v52
	v_mov_b32_e32 v59, v56
	v_mul_f32_e32 v63, v63, v70
	v_pk_mul_f32 v[58:59], v[58:59], v[50:51] op_sel_hi:[1,0]
	v_mul_f32_e32 v62, v62, v63
	v_rcp_f32_e32 v63, v51
	v_mul_f32_e32 v51, 0xbfb8aa3b, v59
	v_mov_b32_e32 v56, v53
	v_exp_f32_e32 v52, v51
	v_pk_mul_f32 v[50:51], v[56:57], v[50:51] op_sel_hi:[1,0]
	v_mul_f32_e32 v55, v55, v63
	v_mul_f32_e32 v53, 0xbfb8aa3b, v51
	v_exp_f32_e32 v53, v53
	v_add_f32_e32 v52, 1.0, v52
	v_rcp_f32_e32 v52, v52
	v_mul_f32_e32 v54, v54, v55
	v_add_f32_e32 v53, 1.0, v53
	v_rcp_f32_e32 v53, v53
	v_mul_f32_e32 v52, v59, v52
	v_mul_f32_e32 v55, v58, v52
	v_mov_b32_e32 v69, v42
	v_mul_f32_e32 v51, v51, v53
	v_mul_f32_e32 v53, v50, v51
	v_cvt_pk_bf16_f32 v50, v67, v68
	v_cvt_pk_bf16_f32 v51, v62, v60
	v_cvt_pk_bf16_f32 v52, v61, v54
	v_cvt_pk_bf16_f32 v53, v55, v53
	v_mad_i64_i32 v[54:55], s[6:7], v66, s50, v[114:115]
	v_add_u32_e32 v66, 0x90, v146
	v_lshl_add_u64 v[54:55], v[54:55], 0, v[116:117]
	v_ashrrev_i32_e32 v67, 31, v66
	global_store_dwordx4 v[54:55], v[50:53], off nt
	v_mov_b32_e32 v42, v47
	v_mov_b32_e32 v68, v46
	v_lshlrev_b64 v[50:51], 6, v[66:67]
	v_lshl_add_u64 v[62:63], s[8:9], 0, v[50:51]
	global_load_dwordx4 v[50:53], v[62:63], off
	global_load_dwordx4 v[54:57], v[62:63], off offset:16
	global_load_dwordx4 v[58:61], v[62:63], off offset:32
	s_nop 0
	global_load_dwordx4 v[62:65], v[62:63], off offset:48
	v_mov_b32_e32 v46, v48
	s_waitcnt vmcnt(3)
	v_mov_b32_e32 v70, v51
	v_mov_b32_e32 v71, v52
	v_mov_b32_e32 v51, v53
	s_waitcnt vmcnt(2)
	v_mov_b32_e32 v52, v55
	v_mov_b32_e32 v53, v56
	v_mov_b32_e32 v55, v57
	v_pk_add_f32 v[50:51], v[70:71], v[50:51]
	v_pk_add_f32 v[52:53], v[52:53], v[54:55]
	v_pk_add_f32 v[50:51], v[50:51], v[50:51] op_sel:[0,1] op_sel_hi:[1,0]
	v_pk_add_f32 v[52:53], v[52:53], v[52:53] op_sel:[0,1] op_sel_hi:[1,0]
	s_waitcnt vmcnt(1)
	v_add_f32_e32 v56, v58, v59
	v_add_f32_e32 v58, v60, v61
	s_waitcnt vmcnt(0)
	v_mov_b32_e32 v57, v64
	v_mov_b32_e32 v59, v65
	v_mov_b32_e32 v51, v62
	v_mov_b32_e32 v53, v63
	v_pk_add_f32 v[54:55], v[56:57], v[58:59]
	v_pk_add_f32 v[50:51], v[50:51], v[52:53]
	s_nop 0
	v_pk_add_f32 v[50:51], v[50:51], v[54:55]
	s_nop 0
	v_add_f32_e32 v47, v50, v51
	v_fmamk_f32 v47, v47, 0x3a800000, v152
	v_mul_f32_e32 v48, 0x4f800000, v47
	v_cmp_gt_f32_e32 vcc, s49, v47
	s_nop 1
	v_cndmask_b32_e32 v50, v47, v48, vcc
	v_sqrt_f32_e32 v51, v50
	v_mov_b32_e32 v48, v34
	v_mov_b32_e32 v47, v44
	v_mov_b32_e32 v44, v49
	v_add_u32_e32 v34, -1, v51
	v_add_u32_e32 v49, 1, v51
	v_fma_f32 v52, -v34, v51, v50
	v_fma_f32 v53, -v49, v51, v50
	v_cmp_ge_f32_e64 s[6:7], 0, v52
	s_nop 1
	v_cndmask_b32_e64 v34, v51, v34, s[6:7]
	v_cmp_lt_f32_e64 s[6:7], 0, v53
	s_nop 1
	v_cndmask_b32_e64 v34, v34, v49, s[6:7]
	v_mul_f32_e32 v49, 0x37800000, v34
	v_cndmask_b32_e32 v34, v34, v49, vcc
	v_cmp_class_f32_e32 vcc, v50, v153
	v_mov_b32_e32 v49, v38
	s_nop 0
	v_cndmask_b32_e32 v34, v34, v50, vcc
	v_div_scale_f32 v50, s[6:7], v34, v34, 1.0
	v_rcp_f32_e32 v51, v50
	v_div_scale_f32 v38, vcc, 1.0, v34, 1.0
	v_fma_f32 v52, -v50, v51, 1.0
	v_fmac_f32_e32 v51, v52, v51
	v_mul_f32_e32 v52, v38, v51
	v_fma_f32 v53, -v50, v52, v38
	v_fmac_f32_e32 v52, v53, v51
	v_fma_f32 v38, -v50, v52, v38
	v_div_fmas_f32 v38, v38, v51, v52
	v_div_fixup_f32 v34, v38, v34, 1.0
	v_pk_mul_f32 v[50:51], v[68:69], v[34:35] op_sel_hi:[1,0]
	v_pk_mul_f32 v[42:43], v[42:43], v[34:35] op_sel_hi:[1,0]
	v_mul_f32_e32 v38, 0xbfb8aa3b, v51
	v_mul_f32_e32 v52, 0xbfb8aa3b, v43
	v_exp_f32_e32 v38, v38
	v_exp_f32_e32 v52, v52
	v_pk_mul_f32 v[48:49], v[48:49], v[34:35] op_sel_hi:[1,0]
	v_pk_mul_f32 v[44:45], v[44:45], v[34:35] op_sel_hi:[1,0]
	v_add_f32_e32 v38, 1.0, v38
	v_mul_f32_e32 v55, 0xbfb8aa3b, v49
	v_add_f32_e32 v52, 1.0, v52
	v_rcp_f32_e32 v38, v38
	v_exp_f32_e32 v55, v55
	v_rcp_f32_e32 v52, v52
	v_mul_f32_e32 v54, 0xbfb8aa3b, v45
	v_pk_mul_f32 v[46:47], v[46:47], v[34:35] op_sel_hi:[1,0]
	v_exp_f32_e32 v54, v54
	v_mul_f32_e32 v53, 0xbfb8aa3b, v47
	v_mul_f32_e32 v38, v51, v38
	v_exp_f32_e32 v53, v53
	v_mul_f32_e32 v43, v43, v52
	v_mul_f32_e32 v50, v50, v38
	v_add_f32_e32 v38, 1.0, v55
	v_mul_f32_e32 v51, v42, v43
	v_rcp_f32_e32 v42, v38
	v_mov_b32_e32 v38, v35
	v_add_f32_e32 v54, 1.0, v54
	v_pk_mul_f32 v[38:39], v[38:39], v[34:35] op_sel_hi:[1,0]
	v_rcp_f32_e32 v54, v54
	v_mul_f32_e32 v35, 0xbfb8aa3b, v39
	v_add_f32_e32 v53, 1.0, v53
	v_exp_f32_e32 v35, v35
	v_rcp_f32_e32 v53, v53
	v_mul_f32_e32 v45, v45, v54
	v_mul_f32_e32 v42, v49, v42
	v_mul_f32_e32 v44, v44, v45
	v_mul_f32_e32 v45, v48, v42
	v_add_f32_e32 v35, 1.0, v35
	v_mov_b32_e32 v42, v36
	v_mov_b32_e32 v43, v40
	v_mul_f32_e32 v47, v47, v53
	v_pk_mul_f32 v[42:43], v[42:43], v[34:35] op_sel_hi:[1,0]
	v_mul_f32_e32 v46, v46, v47
	v_rcp_f32_e32 v47, v35
	v_mul_f32_e32 v35, 0xbfb8aa3b, v43
	v_mov_b32_e32 v40, v37
	v_exp_f32_e32 v36, v35
	v_pk_mul_f32 v[34:35], v[40:41], v[34:35] op_sel_hi:[1,0]
	v_mul_f32_e32 v39, v39, v47
	v_mul_f32_e32 v37, 0xbfb8aa3b, v35
	v_exp_f32_e32 v37, v37
	v_add_f32_e32 v36, 1.0, v36
	v_rcp_f32_e32 v36, v36
	v_mul_f32_e32 v38, v38, v39
	v_add_f32_e32 v37, 1.0, v37
	v_rcp_f32_e32 v37, v37
	v_mul_f32_e32 v36, v43, v36
	v_mul_f32_e32 v39, v42, v36
	v_mov_b32_e32 v53, v26
	v_mul_f32_e32 v35, v35, v37
	v_mul_f32_e32 v37, v34, v35
	v_cvt_pk_bf16_f32 v34, v50, v51
	v_cvt_pk_bf16_f32 v35, v46, v44
	v_cvt_pk_bf16_f32 v36, v45, v38
	v_cvt_pk_bf16_f32 v37, v39, v37
	v_mad_i64_i32 v[38:39], s[6:7], v66, s50, v[114:115]
	v_add_u32_e32 v50, 0xa0, v146
	v_lshl_add_u64 v[38:39], v[38:39], 0, v[116:117]
	v_ashrrev_i32_e32 v51, 31, v50
	global_store_dwordx4 v[38:39], v[34:37], off nt
	v_mov_b32_e32 v26, v31
	v_mov_b32_e32 v52, v30
	v_lshlrev_b64 v[34:35], 6, v[50:51]
	v_lshl_add_u64 v[46:47], s[8:9], 0, v[34:35]
	global_load_dwordx4 v[34:37], v[46:47], off
	global_load_dwordx4 v[38:41], v[46:47], off offset:16
	global_load_dwordx4 v[42:45], v[46:47], off offset:32
	s_nop 0
	global_load_dwordx4 v[46:49], v[46:47], off offset:48
	v_mov_b32_e32 v30, v32
	s_waitcnt vmcnt(3)
	v_mov_b32_e32 v54, v35
	v_mov_b32_e32 v55, v36
	v_mov_b32_e32 v35, v37
	s_waitcnt vmcnt(2)
	v_mov_b32_e32 v36, v39
	v_mov_b32_e32 v37, v40
	v_mov_b32_e32 v39, v41
	v_pk_add_f32 v[34:35], v[54:55], v[34:35]
	v_pk_add_f32 v[36:37], v[36:37], v[38:39]
	v_pk_add_f32 v[34:35], v[34:35], v[34:35] op_sel:[0,1] op_sel_hi:[1,0]
	v_pk_add_f32 v[36:37], v[36:37], v[36:37] op_sel:[0,1] op_sel_hi:[1,0]
	s_waitcnt vmcnt(1)
	v_add_f32_e32 v40, v42, v43
	v_add_f32_e32 v42, v44, v45
	s_waitcnt vmcnt(0)
	v_mov_b32_e32 v41, v48
	v_mov_b32_e32 v43, v49
	v_mov_b32_e32 v35, v46
	v_mov_b32_e32 v37, v47
	v_pk_add_f32 v[38:39], v[40:41], v[42:43]
	v_pk_add_f32 v[34:35], v[34:35], v[36:37]
	s_nop 0
	v_pk_add_f32 v[34:35], v[34:35], v[38:39]
	s_nop 0
	v_add_f32_e32 v31, v34, v35
	v_fmamk_f32 v31, v31, 0x3a800000, v152
	v_mul_f32_e32 v32, 0x4f800000, v31
	v_cmp_gt_f32_e32 vcc, s49, v31
	s_nop 1
	v_cndmask_b32_e32 v34, v31, v32, vcc
	v_sqrt_f32_e32 v35, v34
	v_mov_b32_e32 v32, v18
	v_mov_b32_e32 v31, v28
	v_mov_b32_e32 v28, v33
	v_add_u32_e32 v18, -1, v35
	v_add_u32_e32 v33, 1, v35
	v_fma_f32 v36, -v18, v35, v34
	v_fma_f32 v37, -v33, v35, v34
	v_cmp_ge_f32_e64 s[6:7], 0, v36
	s_nop 1
	v_cndmask_b32_e64 v18, v35, v18, s[6:7]
	v_cmp_lt_f32_e64 s[6:7], 0, v37
	s_nop 1
	v_cndmask_b32_e64 v18, v18, v33, s[6:7]
	v_mul_f32_e32 v33, 0x37800000, v18
	v_cndmask_b32_e32 v18, v18, v33, vcc
	v_cmp_class_f32_e32 vcc, v34, v153
	v_mov_b32_e32 v33, v22
	s_nop 0
	v_cndmask_b32_e32 v18, v18, v34, vcc
	v_div_scale_f32 v34, s[6:7], v18, v18, 1.0
	v_rcp_f32_e32 v35, v34
	v_div_scale_f32 v22, vcc, 1.0, v18, 1.0
	v_fma_f32 v36, -v34, v35, 1.0
	v_fmac_f32_e32 v35, v36, v35
	v_mul_f32_e32 v36, v22, v35
	v_fma_f32 v37, -v34, v36, v22
	v_fmac_f32_e32 v36, v37, v35
	v_fma_f32 v22, -v34, v36, v22
	v_div_fmas_f32 v22, v22, v35, v36
	v_div_fixup_f32 v18, v22, v18, 1.0
	v_pk_mul_f32 v[26:27], v[26:27], v[18:19] op_sel_hi:[1,0]
	v_pk_mul_f32 v[34:35], v[52:53], v[18:19] op_sel_hi:[1,0]
	v_mul_f32_e32 v36, 0xbfb8aa3b, v27
	v_mul_f32_e32 v22, 0xbfb8aa3b, v35
	v_exp_f32_e32 v36, v36
	v_exp_f32_e32 v22, v22
	v_pk_mul_f32 v[30:31], v[30:31], v[18:19] op_sel_hi:[1,0]
	v_pk_mul_f32 v[28:29], v[28:29], v[18:19] op_sel_hi:[1,0]
	v_add_f32_e32 v36, 1.0, v36
	v_add_f32_e32 v22, 1.0, v22
	v_rcp_f32_e32 v36, v36
	v_mul_f32_e32 v37, 0xbfb8aa3b, v31
	v_rcp_f32_e32 v22, v22
	v_exp_f32_e32 v37, v37
	v_mul_f32_e32 v27, v27, v36
	v_mul_f32_e32 v38, 0xbfb8aa3b, v29
	v_mul_f32_e32 v22, v35, v22
	v_mul_f32_e32 v35, v26, v27
	v_pk_mul_f32 v[26:27], v[32:33], v[18:19] op_sel_hi:[1,0]
	v_add_f32_e32 v37, 1.0, v37
	v_mul_f32_e32 v34, v34, v22
	v_mul_f32_e32 v22, 0xbfb8aa3b, v27
	v_rcp_f32_e32 v37, v37
	v_exp_f32_e32 v22, v22
	v_exp_f32_e32 v38, v38
	v_mov_b32_e32 v36, v10
	v_mul_f32_e32 v31, v31, v37
	v_add_f32_e32 v22, 1.0, v22
	v_mul_f32_e32 v30, v30, v31
	v_rcp_f32_e32 v31, v22
	v_mov_b32_e32 v22, v19
	v_add_f32_e32 v38, 1.0, v38
	v_pk_mul_f32 v[22:23], v[22:23], v[18:19] op_sel_hi:[1,0]
	v_rcp_f32_e32 v38, v38
	v_mul_f32_e32 v19, 0xbfb8aa3b, v23
	v_exp_f32_e32 v19, v19
	v_mul_f32_e32 v27, v27, v31
	v_mul_f32_e32 v29, v29, v38
	v_mul_f32_e32 v28, v28, v29
	v_mul_f32_e32 v29, v26, v27
	v_add_f32_e32 v19, 1.0, v19
	v_mov_b32_e32 v26, v20
	v_mov_b32_e32 v27, v24
	v_pk_mul_f32 v[26:27], v[26:27], v[18:19] op_sel_hi:[1,0]
	v_rcp_f32_e32 v31, v19
	v_mul_f32_e32 v19, 0xbfb8aa3b, v27
	v_mov_b32_e32 v24, v21
	v_exp_f32_e32 v20, v19
	v_pk_mul_f32 v[18:19], v[24:25], v[18:19] op_sel_hi:[1,0]
	v_mul_f32_e32 v23, v23, v31
	v_mul_f32_e32 v21, 0xbfb8aa3b, v19
	v_exp_f32_e32 v21, v21
	v_add_f32_e32 v20, 1.0, v20
	v_rcp_f32_e32 v20, v20
	v_mul_f32_e32 v22, v22, v23
	v_add_f32_e32 v21, 1.0, v21
	v_rcp_f32_e32 v21, v21
	v_mul_f32_e32 v20, v27, v20
	v_mul_f32_e32 v23, v26, v20
	v_mov_b32_e32 v37, v14
	v_mul_f32_e32 v19, v19, v21
	v_mul_f32_e32 v21, v18, v19
	v_cvt_pk_bf16_f32 v18, v34, v35
	v_cvt_pk_bf16_f32 v19, v30, v28
	v_cvt_pk_bf16_f32 v20, v29, v22
	v_cvt_pk_bf16_f32 v21, v23, v21
	v_mad_i64_i32 v[22:23], s[6:7], v50, s50, v[114:115]
	v_add_u32_e32 v34, 0xb0, v146
	v_lshl_add_u64 v[22:23], v[22:23], 0, v[116:117]
	v_ashrrev_i32_e32 v35, 31, v34
	global_store_dwordx4 v[22:23], v[18:21], off nt
	s_nop 1
	v_lshlrev_b64 v[18:19], 6, v[34:35]
	v_lshl_add_u64 v[30:31], s[8:9], 0, v[18:19]
	global_load_dwordx4 v[18:21], v[30:31], off
	global_load_dwordx4 v[22:25], v[30:31], off offset:16
	global_load_dwordx4 v[26:29], v[30:31], off offset:32
	s_nop 0
	global_load_dwordx4 v[30:33], v[30:31], off offset:48
	s_waitcnt vmcnt(3)
	v_mov_b32_e32 v38, v19
	v_mov_b32_e32 v39, v20
	v_mov_b32_e32 v19, v21
	s_waitcnt vmcnt(2)
	v_mov_b32_e32 v20, v23
	v_mov_b32_e32 v21, v24
	v_mov_b32_e32 v23, v25
	v_pk_add_f32 v[18:19], v[38:39], v[18:19]
	v_pk_add_f32 v[20:21], v[20:21], v[22:23]
	v_pk_add_f32 v[18:19], v[18:19], v[18:19] op_sel:[0,1] op_sel_hi:[1,0]
	v_pk_add_f32 v[20:21], v[20:21], v[20:21] op_sel:[0,1] op_sel_hi:[1,0]
	s_waitcnt vmcnt(1)
	v_add_f32_e32 v24, v26, v27
	v_add_f32_e32 v26, v28, v29
	s_waitcnt vmcnt(0)
	v_mov_b32_e32 v25, v32
	v_mov_b32_e32 v27, v33
	v_mov_b32_e32 v19, v30
	v_mov_b32_e32 v21, v31
	v_pk_add_f32 v[22:23], v[24:25], v[26:27]
	v_pk_add_f32 v[18:19], v[18:19], v[20:21]
	s_nop 0
	v_pk_add_f32 v[18:19], v[18:19], v[22:23]
	s_nop 0
	v_add_f32_e32 v10, v18, v19
	v_fmamk_f32 v10, v10, 0x3a800000, v152
	v_mul_f32_e32 v14, 0x4f800000, v10
	v_cmp_gt_f32_e32 vcc, s49, v10
	s_nop 1
	v_cndmask_b32_e32 v18, v10, v14, vcc
	v_sqrt_f32_e32 v19, v18
	v_mov_b32_e32 v10, v12
	v_mov_b32_e32 v14, v11
	v_mov_b32_e32 v11, v16
	v_add_u32_e32 v12, -1, v19
	v_add_u32_e32 v16, 1, v19
	v_fma_f32 v20, -v12, v19, v18
	v_fma_f32 v21, -v16, v19, v18
	v_cmp_ge_f32_e64 s[6:7], 0, v20
	s_nop 1
	v_cndmask_b32_e64 v12, v19, v12, s[6:7]
	v_cmp_lt_f32_e64 s[6:7], 0, v21
	s_nop 1
	v_cndmask_b32_e64 v12, v12, v16, s[6:7]
	v_mul_f32_e32 v16, 0x37800000, v12
	v_cndmask_b32_e32 v12, v12, v16, vcc
	v_cmp_class_f32_e32 vcc, v18, v153
	v_mov_b32_e32 v16, v13
	s_nop 0
	v_cndmask_b32_e32 v12, v12, v18, vcc
	v_div_scale_f32 v18, s[6:7], v12, v12, 1.0
	v_rcp_f32_e32 v19, v18
	v_div_scale_f32 v13, vcc, 1.0, v12, 1.0
	v_fma_f32 v20, -v18, v19, 1.0
	v_fmac_f32_e32 v19, v20, v19
	v_mul_f32_e32 v20, v13, v19
	v_fma_f32 v21, -v18, v20, v13
	v_fmac_f32_e32 v20, v21, v19
	v_fma_f32 v13, -v18, v20, v13
	v_div_fmas_f32 v13, v13, v19, v20
	v_div_fixup_f32 v12, v13, v12, 1.0
	v_pk_mul_f32 v[18:19], v[36:37], v[12:13] op_sel_hi:[1,0]
	v_pk_mul_f32 v[14:15], v[14:15], v[12:13] op_sel_hi:[1,0]
	v_pk_mul_f32 v[10:11], v[10:11], v[12:13] op_sel_hi:[1,0]
	v_pk_mul_f32 v[16:17], v[16:17], v[12:13] op_sel_hi:[1,0]
	v_mul_f32_e32 v13, 0xbfb8aa3b, v19
	v_mul_f32_e32 v20, 0xbfb8aa3b, v15
	v_exp_f32_e32 v13, v13
	v_exp_f32_e32 v20, v20
	v_mul_f32_e32 v21, 0xbfb8aa3b, v11
	v_mul_f32_e32 v22, 0xbfb8aa3b, v17
	v_add_f32_e32 v13, 1.0, v13
	v_add_f32_e32 v20, 1.0, v20
	v_rcp_f32_e32 v13, v13
	v_rcp_f32_e32 v20, v20
	v_exp_f32_e32 v21, v21
	v_exp_f32_e32 v22, v22
	v_mul_f32_e32 v13, v19, v13
	v_mul_f32_e32 v15, v15, v20
	v_mul_f32_e32 v13, v18, v13
	v_mul_f32_e32 v18, v14, v15
	v_add_f32_e32 v14, 1.0, v21
	v_rcp_f32_e32 v19, v14
	v_add_f32_e32 v14, 1.0, v22
	v_rcp_f32_e32 v20, v14
	v_mov_b32_e32 v14, v2
	v_mov_b32_e32 v15, v6
	v_pk_mul_f32 v[14:15], v[14:15], v[12:13] op_sel_hi:[1,0]
	v_mul_f32_e32 v6, v11, v19
	v_mul_f32_e32 v2, 0xbfb8aa3b, v15
	v_exp_f32_e32 v2, v2
	v_mul_f32_e32 v10, v10, v6
	v_mov_b32_e32 v6, v3
	v_mul_f32_e32 v11, v17, v20
	v_add_f32_e32 v2, 1.0, v2
	v_rcp_f32_e32 v17, v2
	v_pk_mul_f32 v[2:3], v[6:7], v[12:13] op_sel_hi:[1,0]
	v_mul_f32_e32 v11, v16, v11
	v_mul_f32_e32 v6, 0xbfb8aa3b, v3
	v_exp_f32_e32 v6, v6
	v_mul_f32_e32 v7, v15, v17
	v_mul_f32_e32 v14, v14, v7
	v_mov_b32_e32 v7, v8
	v_add_f32_e32 v6, 1.0, v6
	v_rcp_f32_e32 v15, v6
	v_mov_b32_e32 v6, v4
	v_pk_mul_f32 v[6:7], v[6:7], v[12:13] op_sel_hi:[1,0]
	v_mov_b32_e32 v8, v5
	v_mul_f32_e32 v4, 0xbfb8aa3b, v7
	v_exp_f32_e32 v16, v4
	v_pk_mul_f32 v[4:5], v[8:9], v[12:13] op_sel_hi:[1,0]
	v_mul_f32_e32 v3, v3, v15
	v_mul_f32_e32 v8, 0xbfb8aa3b, v5
	v_exp_f32_e32 v8, v8
	v_add_f32_e32 v9, 1.0, v16
	v_rcp_f32_e32 v9, v9
	v_mul_f32_e32 v12, v2, v3
	v_add_f32_e32 v8, 1.0, v8
	v_rcp_f32_e32 v8, v8
	v_mul_f32_e32 v2, v7, v9
	v_mul_f32_e32 v6, v6, v2
	s_andn2_b64 vcc, exec, s[4:5]
	v_mul_f32_e32 v2, v5, v8
	v_mul_f32_e32 v5, v4, v2
	v_cvt_pk_bf16_f32 v2, v13, v18
	v_cvt_pk_bf16_f32 v3, v10, v11
	v_cvt_pk_bf16_f32 v4, v14, v12
	v_cvt_pk_bf16_f32 v5, v6, v5
	v_mad_i64_i32 v[6:7], s[6:7], v34, s50, v[114:115]
	v_lshl_add_u64 v[6:7], v[6:7], 0, v[116:117]
	s_mov_b64 s[4:5], -1
	global_store_dwordx4 v[6:7], v[2:5], off nt
	s_cbranch_vccnz .LBB0_248
	s_andn2_b64 vcc, exec, s[2:3]
	s_cbranch_vccnz .LBB0_247
	s_barrier
	s_branch .LBB0_247

.LBB0_1099:
	s_waitcnt vmcnt(0) lgkmcnt(0)
	s_cmpk_lt_u32 s3, 0x400
	s_cbranch_scc1 .LBB0_1106
	v_lshl_or_b32 v3, v6, 23, v172
	s_waitcnt vmcnt(0) lgkmcnt(0)
	v_cmp_ge_u32_e32 vcc, v19, v3
	s_bcnt1_i32_b64 s4, vcc
	v_cmp_ge_u32_e32 vcc, v13, v3
	s_bcnt1_i32_b64 s5, vcc
	v_cmp_ge_u32_e32 vcc, v20, v3
	s_add_i32 s4, s5, s4
	s_bcnt1_i32_b64 s5, vcc
	v_cmp_ge_u32_e32 vcc, v12, v3
	s_add_i32 s4, s4, s5
	s_bcnt1_i32_b64 s5, vcc
	v_cmp_ge_u32_e32 vcc, v18, v3
	s_add_i32 s4, s4, s5
	s_bcnt1_i32_b64 s5, vcc
	v_cmp_ge_u32_e32 vcc, v10, v3
	s_add_i32 s4, s4, s5
	s_bcnt1_i32_b64 s5, vcc
	v_cmp_ge_u32_e32 vcc, v17, v3
	s_add_i32 s4, s4, s5
	s_bcnt1_i32_b64 s5, vcc
	v_cmp_ge_u32_e32 vcc, v9, v3
	s_add_i32 s4, s4, s5
	s_bcnt1_i32_b64 s5, vcc
	v_cmp_ge_u32_e32 vcc, v16, v3
	s_add_i32 s4, s4, s5
	s_bcnt1_i32_b64 s5, vcc
	v_cmp_ge_u32_e32 vcc, v8, v3
	s_add_i32 s4, s4, s5
	s_bcnt1_i32_b64 s5, vcc
	v_cmp_ge_u32_e32 vcc, v15, v3
	s_add_i32 s4, s4, s5
	s_bcnt1_i32_b64 s5, vcc
	v_cmp_ge_u32_e32 vcc, v7, v3
	s_add_i32 s4, s4, s5
	s_bcnt1_i32_b64 s5, vcc
	v_cmp_ge_u32_e32 vcc, v14, v3
	s_add_i32 s4, s4, s5
	s_bcnt1_i32_b64 s5, vcc
	v_cmp_ge_u32_e32 vcc, v5, v3
	s_add_i32 s4, s4, s5
	s_bcnt1_i32_b64 s5, vcc
	v_cmp_ge_u32_e32 vcc, v11, v3
	s_add_i32 s4, s4, s5
	s_bcnt1_i32_b64 s5, vcc
	v_cmp_ge_u32_e32 vcc, v4, v3
	s_add_i32 s4, s4, s5
	s_bcnt1_i32_b64 s5, vcc
	v_cmp_ge_u32_e32 vcc, v22, v3
	s_add_i32 s4, s4, s5
	s_bcnt1_i32_b64 s5, vcc
	v_cmp_ge_u32_e32 vcc, v21, v3
	s_add_i32 s4, s4, s5
	s_bcnt1_i32_b64 s5, vcc
	v_cmp_ge_u32_e32 vcc, v24, v3
	s_add_i32 s4, s4, s5
	s_bcnt1_i32_b64 s5, vcc
	v_cmp_ge_u32_e32 vcc, v23, v3
	s_add_i32 s4, s4, s5
	s_bcnt1_i32_b64 s5, vcc
	v_cmp_ge_u32_e32 vcc, v26, v3
	s_add_i32 s4, s4, s5
	s_bcnt1_i32_b64 s5, vcc
	v_cmp_ge_u32_e32 vcc, v25, v3
	s_add_i32 s4, s4, s5
	s_bcnt1_i32_b64 s5, vcc
	v_cmp_ge_u32_e32 vcc, v28, v3
	s_add_i32 s4, s4, s5
	s_bcnt1_i32_b64 s5, vcc
	v_cmp_ge_u32_e32 vcc, v27, v3
	s_add_i32 s4, s4, s5
	s_bcnt1_i32_b64 s5, vcc
	v_cmp_ge_u32_e32 vcc, v31, v3
	s_add_i32 s4, s4, s5
	s_bcnt1_i32_b64 s5, vcc
	v_cmp_ge_u32_e32 vcc, v29, v3
	s_add_i32 s4, s4, s5
	s_bcnt1_i32_b64 s5, vcc
	v_cmp_ge_u32_e32 vcc, v33, v3
	s_add_i32 s4, s4, s5
	s_bcnt1_i32_b64 s5, vcc
	v_cmp_ge_u32_e32 vcc, v32, v3
	s_add_i32 s4, s4, s5
	s_bcnt1_i32_b64 s5, vcc
	v_cmp_ge_u32_e32 vcc, v35, v3
	s_add_i32 s4, s4, s5
	s_bcnt1_i32_b64 s5, vcc
	v_cmp_ge_u32_e32 vcc, v34, v3
	s_add_i32 s4, s4, s5
	s_bcnt1_i32_b64 s5, vcc
	v_cmp_ge_u32_e32 vcc, v37, v3
	s_add_i32 s4, s4, s5
	s_bcnt1_i32_b64 s5, vcc
	v_cmp_ge_u32_e32 vcc, v36, v3
	s_add_i32 s4, s4, s5
	s_bcnt1_i32_b64 s5, vcc
	s_add_i32 s4, s4, s5
	s_cmpk_gt_u32 s3, 0x7ff
	s_cselect_b64 s[6:7], -1, 0
	s_cmpk_lt_u32 s3, 0x800
	s_cbranch_scc1 .LBB0_1331
	v_cmp_ge_u32_e32 vcc, v39, v3
	s_bcnt1_i32_b64 s5, vcc
	v_cmp_ge_u32_e32 vcc, v38, v3
	s_add_i32 s4, s4, s5
	s_bcnt1_i32_b64 s5, vcc
	v_cmp_ge_u32_e32 vcc, v41, v3
	s_add_i32 s4, s4, s5
	s_bcnt1_i32_b64 s5, vcc
	v_cmp_ge_u32_e32 vcc, v40, v3
	s_add_i32 s4, s4, s5
	s_bcnt1_i32_b64 s5, vcc
	v_cmp_ge_u32_e32 vcc, v43, v3
	s_add_i32 s4, s4, s5
	s_bcnt1_i32_b64 s5, vcc
	v_cmp_ge_u32_e32 vcc, v42, v3
	s_add_i32 s4, s4, s5
	s_bcnt1_i32_b64 s5, vcc
	v_cmp_ge_u32_e32 vcc, v45, v3
	s_add_i32 s4, s4, s5
	s_bcnt1_i32_b64 s5, vcc
	v_cmp_ge_u32_e32 vcc, v44, v3
	s_add_i32 s4, s4, s5
	s_bcnt1_i32_b64 s5, vcc
	v_cmp_ge_u32_e32 vcc, v47, v3
	s_add_i32 s4, s4, s5
	s_bcnt1_i32_b64 s5, vcc
	v_cmp_ge_u32_e32 vcc, v46, v3
	s_add_i32 s4, s4, s5
	s_bcnt1_i32_b64 s5, vcc
	v_cmp_ge_u32_e32 vcc, v49, v3
	s_add_i32 s4, s4, s5
	s_bcnt1_i32_b64 s5, vcc
	v_cmp_ge_u32_e32 vcc, v48, v3
	s_add_i32 s4, s4, s5
	s_bcnt1_i32_b64 s5, vcc
	v_cmp_ge_u32_e32 vcc, v51, v3
	s_add_i32 s4, s4, s5
	s_bcnt1_i32_b64 s5, vcc
	v_cmp_ge_u32_e32 vcc, v50, v3
	s_add_i32 s4, s4, s5
	s_bcnt1_i32_b64 s5, vcc
	v_cmp_ge_u32_e32 vcc, v53, v3
	s_add_i32 s4, s4, s5
	s_bcnt1_i32_b64 s5, vcc
	v_cmp_ge_u32_e32 vcc, v52, v3
	s_add_i32 s4, s4, s5
	s_bcnt1_i32_b64 s5, vcc
	s_add_i32 s4, s4, s5
	s_cmpk_gt_u32 s3, 0xbff
	s_cselect_b64 s[8:9], -1, 0
	s_cmpk_lt_u32 s3, 0xc00
	s_cbranch_scc0 .LBB0_1332

.LBB0_1103:
	v_cmp_ge_u32_e32 vcc, v71, v3
	s_bcnt1_i32_b64 s5, vcc
	v_cmp_ge_u32_e32 vcc, v70, v3
	s_add_i32 s4, s4, s5
	s_bcnt1_i32_b64 s5, vcc
	v_cmp_ge_u32_e32 vcc, v73, v3
	s_add_i32 s4, s4, s5
	s_bcnt1_i32_b64 s5, vcc
	v_cmp_ge_u32_e32 vcc, v72, v3
	s_add_i32 s4, s4, s5
	s_bcnt1_i32_b64 s5, vcc
	v_cmp_ge_u32_e32 vcc, v75, v3
	s_add_i32 s4, s4, s5
	s_bcnt1_i32_b64 s5, vcc
	v_cmp_ge_u32_e32 vcc, v74, v3
	s_add_i32 s4, s4, s5
	s_bcnt1_i32_b64 s5, vcc
	v_cmp_ge_u32_e32 vcc, v77, v3
	s_add_i32 s4, s4, s5
	s_bcnt1_i32_b64 s5, vcc
	v_cmp_ge_u32_e32 vcc, v76, v3
	s_add_i32 s4, s4, s5
	s_bcnt1_i32_b64 s5, vcc
	v_cmp_ge_u32_e32 vcc, v79, v3
	s_add_i32 s4, s4, s5
	s_bcnt1_i32_b64 s5, vcc
	v_cmp_ge_u32_e32 vcc, v78, v3
	s_add_i32 s4, s4, s5
	s_bcnt1_i32_b64 s5, vcc
	v_cmp_ge_u32_e32 vcc, v81, v3
	s_add_i32 s4, s4, s5
	s_bcnt1_i32_b64 s5, vcc
	v_cmp_ge_u32_e32 vcc, v80, v3
	s_add_i32 s4, s4, s5
	s_bcnt1_i32_b64 s5, vcc
	v_cmp_ge_u32_e32 vcc, v83, v3
	s_add_i32 s4, s4, s5
	s_bcnt1_i32_b64 s5, vcc
	v_cmp_ge_u32_e32 vcc, v82, v3
	s_add_i32 s4, s4, s5
	s_bcnt1_i32_b64 s5, vcc
	v_cmp_ge_u32_e32 vcc, v85, v3
	s_add_i32 s4, s4, s5
	s_bcnt1_i32_b64 s5, vcc
	v_cmp_ge_u32_e32 vcc, v84, v3
	s_add_i32 s4, s4, s5
	s_bcnt1_i32_b64 s5, vcc
	s_add_i32 s4, s4, s5
	s_cmpk_gt_u32 s3, 0x13ff
	s_cselect_b64 s[12:13], -1, 0
	s_cmpk_lt_u32 s3, 0x1400
	s_cbranch_scc0 .LBB0_1334

.LBB0_1105:
	v_cmp_ge_u32_e32 vcc, v103, v3
	s_bcnt1_i32_b64 s5, vcc
	v_cmp_ge_u32_e32 vcc, v102, v3
	s_add_i32 s4, s4, s5
	s_bcnt1_i32_b64 s5, vcc
	v_cmp_ge_u32_e32 vcc, v105, v3
	s_add_i32 s4, s4, s5
	s_bcnt1_i32_b64 s5, vcc
	v_cmp_ge_u32_e32 vcc, v104, v3
	s_add_i32 s4, s4, s5
	s_bcnt1_i32_b64 s5, vcc
	v_cmp_ge_u32_e32 vcc, v107, v3
	s_add_i32 s4, s4, s5
	s_bcnt1_i32_b64 s5, vcc
	v_cmp_ge_u32_e32 vcc, v106, v3
	s_add_i32 s4, s4, s5
	s_bcnt1_i32_b64 s5, vcc
	v_cmp_ge_u32_e32 vcc, v109, v3
	s_add_i32 s4, s4, s5
	s_bcnt1_i32_b64 s5, vcc
	v_cmp_ge_u32_e32 vcc, v108, v3
	s_add_i32 s4, s4, s5
	s_bcnt1_i32_b64 s5, vcc
	v_cmp_ge_u32_e32 vcc, v111, v3
	s_add_i32 s4, s4, s5
	s_bcnt1_i32_b64 s5, vcc
	v_cmp_ge_u32_e32 vcc, v110, v3
	s_add_i32 s4, s4, s5
	s_bcnt1_i32_b64 s5, vcc
	v_cmp_ge_u32_e32 vcc, v113, v3
	s_add_i32 s4, s4, s5
	s_bcnt1_i32_b64 s5, vcc
	v_cmp_ge_u32_e32 vcc, v112, v3
	s_add_i32 s4, s4, s5
	s_bcnt1_i32_b64 s5, vcc
	v_cmp_ge_u32_e32 vcc, v115, v3
	s_add_i32 s4, s4, s5
	s_bcnt1_i32_b64 s5, vcc
	v_cmp_ge_u32_e32 vcc, v114, v3
	s_add_i32 s4, s4, s5
	s_bcnt1_i32_b64 s5, vcc
	v_cmp_ge_u32_e32 vcc, v117, v3
	s_add_i32 s4, s4, s5
	s_bcnt1_i32_b64 s5, vcc
	v_cmp_ge_u32_e32 vcc, v116, v3
	s_add_i32 s4, s4, s5
	s_bcnt1_i32_b64 s5, vcc
	s_add_i32 s4, s4, s5
	s_cmpk_gt_u32 s3, 0x1bff
	s_cselect_b64 s[18:19], -1, 0
	s_cmpk_lt_u32 s3, 0x1c00
	s_cbranch_scc0 .LBB0_1336
	s_branch .LBB0_1337

.LBB0_1109:
	s_cmp_gt_i32 s30, -1
	s_cselect_b64 s[6:7], -1, 0
	s_xor_b64 s[8:9], s[14:15], -1
	s_and_b64 s[6:7], s[8:9], s[6:7]
	s_sub_i32 s4, s24, s5
	s_cmpk_gt_i32 s4, 0x200
	s_cselect_b64 s[8:9], -1, 0
	s_and_b64 s[6:7], s[6:7], s[8:9]
	s_andn2_b64 vcc, exec, s[6:7]
	s_mov_b64 s[6:7], -1
	s_cbranch_vccnz .LBB0_1108
	v_lshl_or_b32 v3, 1, s30, v2
	s_waitcnt vmcnt(0) lgkmcnt(0)
	v_cmp_ge_u32_e32 vcc, v19, v3
	s_bcnt1_i32_b64 s4, vcc
	v_cmp_ge_u32_e32 vcc, v13, v3
	s_bcnt1_i32_b64 s6, vcc
	v_cmp_ge_u32_e32 vcc, v20, v3
	s_add_i32 s4, s6, s4
	s_bcnt1_i32_b64 s6, vcc
	v_cmp_ge_u32_e32 vcc, v12, v3
	s_add_i32 s4, s4, s6
	s_bcnt1_i32_b64 s6, vcc
	v_cmp_ge_u32_e32 vcc, v18, v3
	s_add_i32 s4, s4, s6
	s_bcnt1_i32_b64 s6, vcc
	v_cmp_ge_u32_e32 vcc, v10, v3
	s_add_i32 s4, s4, s6
	s_bcnt1_i32_b64 s6, vcc
	v_cmp_ge_u32_e32 vcc, v17, v3
	s_add_i32 s4, s4, s6
	s_bcnt1_i32_b64 s6, vcc
	v_cmp_ge_u32_e32 vcc, v9, v3
	s_add_i32 s4, s4, s6
	s_bcnt1_i32_b64 s6, vcc
	v_cmp_ge_u32_e32 vcc, v16, v3
	s_add_i32 s4, s4, s6
	s_bcnt1_i32_b64 s6, vcc
	v_cmp_ge_u32_e32 vcc, v8, v3
	s_add_i32 s4, s4, s6
	s_bcnt1_i32_b64 s6, vcc
	v_cmp_ge_u32_e32 vcc, v15, v3
	s_add_i32 s4, s4, s6
	s_bcnt1_i32_b64 s6, vcc
	v_cmp_ge_u32_e32 vcc, v7, v3
	s_add_i32 s4, s4, s6
	s_bcnt1_i32_b64 s6, vcc
	v_cmp_ge_u32_e32 vcc, v14, v3
	s_add_i32 s4, s4, s6
	s_bcnt1_i32_b64 s6, vcc
	v_cmp_ge_u32_e32 vcc, v5, v3
	s_add_i32 s4, s4, s6
	s_bcnt1_i32_b64 s6, vcc
	v_cmp_ge_u32_e32 vcc, v11, v3
	s_add_i32 s4, s4, s6
	s_bcnt1_i32_b64 s6, vcc
	v_cmp_ge_u32_e32 vcc, v4, v3
	s_add_i32 s4, s4, s6
	s_bcnt1_i32_b64 s6, vcc
	s_andn2_b64 vcc, exec, s[88:89]
	s_add_i32 s4, s4, s6
	s_cbranch_vccnz .LBB0_1119
	v_cmp_ge_u32_e32 vcc, v22, v3
	s_bcnt1_i32_b64 s6, vcc
	v_cmp_ge_u32_e32 vcc, v21, v3
	s_add_i32 s4, s4, s6
	s_bcnt1_i32_b64 s6, vcc
	v_cmp_ge_u32_e32 vcc, v24, v3
	s_add_i32 s4, s4, s6
	s_bcnt1_i32_b64 s6, vcc
	v_cmp_ge_u32_e32 vcc, v23, v3
	s_add_i32 s4, s4, s6
	s_bcnt1_i32_b64 s6, vcc
	v_cmp_ge_u32_e32 vcc, v26, v3
	s_add_i32 s4, s4, s6
	s_bcnt1_i32_b64 s6, vcc
	v_cmp_ge_u32_e32 vcc, v25, v3
	s_add_i32 s4, s4, s6
	s_bcnt1_i32_b64 s6, vcc
	v_cmp_ge_u32_e32 vcc, v28, v3
	s_add_i32 s4, s4, s6
	s_bcnt1_i32_b64 s6, vcc
	v_cmp_ge_u32_e32 vcc, v27, v3
	s_add_i32 s4, s4, s6
	s_bcnt1_i32_b64 s6, vcc
	v_cmp_ge_u32_e32 vcc, v31, v3
	s_add_i32 s4, s4, s6
	s_bcnt1_i32_b64 s6, vcc
	v_cmp_ge_u32_e32 vcc, v29, v3
	s_add_i32 s4, s4, s6
	s_bcnt1_i32_b64 s6, vcc
	v_cmp_ge_u32_e32 vcc, v33, v3
	s_add_i32 s4, s4, s6
	s_bcnt1_i32_b64 s6, vcc
	v_cmp_ge_u32_e32 vcc, v32, v3
	s_add_i32 s4, s4, s6
	s_bcnt1_i32_b64 s6, vcc
	v_cmp_ge_u32_e32 vcc, v35, v3
	s_add_i32 s4, s4, s6
	s_bcnt1_i32_b64 s6, vcc
	v_cmp_ge_u32_e32 vcc, v34, v3
	s_add_i32 s4, s4, s6
	s_bcnt1_i32_b64 s6, vcc
	v_cmp_ge_u32_e32 vcc, v37, v3
	s_add_i32 s4, s4, s6
	s_bcnt1_i32_b64 s6, vcc
	v_cmp_ge_u32_e32 vcc, v36, v3
	s_add_i32 s4, s4, s6
	s_bcnt1_i32_b64 s6, vcc
	s_add_i32 s4, s4, s6
	s_andn2_b64 vcc, exec, s[66:67]
	s_cbranch_vccz .LBB0_1120

.LBB0_1113:
	v_cmp_ge_u32_e32 vcc, v55, v3
	s_bcnt1_i32_b64 s6, vcc
	v_cmp_ge_u32_e32 vcc, v54, v3
	s_add_i32 s4, s4, s6
	s_bcnt1_i32_b64 s6, vcc
	v_cmp_ge_u32_e32 vcc, v57, v3
	s_add_i32 s4, s4, s6
	s_bcnt1_i32_b64 s6, vcc
	v_cmp_ge_u32_e32 vcc, v56, v3
	s_add_i32 s4, s4, s6
	s_bcnt1_i32_b64 s6, vcc
	v_cmp_ge_u32_e32 vcc, v59, v3
	s_add_i32 s4, s4, s6
	s_bcnt1_i32_b64 s6, vcc
	v_cmp_ge_u32_e32 vcc, v58, v3
	s_add_i32 s4, s4, s6
	s_bcnt1_i32_b64 s6, vcc
	v_cmp_ge_u32_e32 vcc, v61, v3
	s_add_i32 s4, s4, s6
	s_bcnt1_i32_b64 s6, vcc
	v_cmp_ge_u32_e32 vcc, v60, v3
	s_add_i32 s4, s4, s6
	s_bcnt1_i32_b64 s6, vcc
	v_cmp_ge_u32_e32 vcc, v63, v3
	s_add_i32 s4, s4, s6
	s_bcnt1_i32_b64 s6, vcc
	v_cmp_ge_u32_e32 vcc, v62, v3
	s_add_i32 s4, s4, s6
	s_bcnt1_i32_b64 s6, vcc
	v_cmp_ge_u32_e32 vcc, v65, v3
	s_add_i32 s4, s4, s6
	s_bcnt1_i32_b64 s6, vcc
	v_cmp_ge_u32_e32 vcc, v64, v3
	s_add_i32 s4, s4, s6
	s_bcnt1_i32_b64 s6, vcc
	v_cmp_ge_u32_e32 vcc, v67, v3
	s_add_i32 s4, s4, s6
	s_bcnt1_i32_b64 s6, vcc
	v_cmp_ge_u32_e32 vcc, v66, v3
	s_add_i32 s4, s4, s6
	s_bcnt1_i32_b64 s6, vcc
	v_cmp_ge_u32_e32 vcc, v69, v3
	s_add_i32 s4, s4, s6
	s_bcnt1_i32_b64 s6, vcc
	v_cmp_ge_u32_e32 vcc, v68, v3
	s_add_i32 s4, s4, s6
	s_bcnt1_i32_b64 s6, vcc
	s_add_i32 s4, s4, s6
	s_andn2_b64 vcc, exec, s[62:63]
	s_cbranch_vccz .LBB0_1122

.LBB0_1115:
	v_cmp_ge_u32_e32 vcc, v87, v3
	s_bcnt1_i32_b64 s6, vcc
	v_cmp_ge_u32_e32 vcc, v86, v3
	s_add_i32 s4, s4, s6
	s_bcnt1_i32_b64 s6, vcc
	v_cmp_ge_u32_e32 vcc, v89, v3
	s_add_i32 s4, s4, s6
	s_bcnt1_i32_b64 s6, vcc
	v_cmp_ge_u32_e32 vcc, v88, v3
	s_add_i32 s4, s4, s6
	s_bcnt1_i32_b64 s6, vcc
	v_cmp_ge_u32_e32 vcc, v91, v3
	s_add_i32 s4, s4, s6
	s_bcnt1_i32_b64 s6, vcc
	v_cmp_ge_u32_e32 vcc, v90, v3
	s_add_i32 s4, s4, s6
	s_bcnt1_i32_b64 s6, vcc
	v_cmp_ge_u32_e32 vcc, v93, v3
	s_add_i32 s4, s4, s6
	s_bcnt1_i32_b64 s6, vcc
	v_cmp_ge_u32_e32 vcc, v92, v3
	s_add_i32 s4, s4, s6
	s_bcnt1_i32_b64 s6, vcc
	v_cmp_ge_u32_e32 vcc, v95, v3
	s_add_i32 s4, s4, s6
	s_bcnt1_i32_b64 s6, vcc
	v_cmp_ge_u32_e32 vcc, v94, v3
	s_add_i32 s4, s4, s6
	s_bcnt1_i32_b64 s6, vcc
	v_cmp_ge_u32_e32 vcc, v97, v3
	s_add_i32 s4, s4, s6
	s_bcnt1_i32_b64 s6, vcc
	v_cmp_ge_u32_e32 vcc, v96, v3
	s_add_i32 s4, s4, s6
	s_bcnt1_i32_b64 s6, vcc
	v_cmp_ge_u32_e32 vcc, v99, v3
	s_add_i32 s4, s4, s6
	s_bcnt1_i32_b64 s6, vcc
	v_cmp_ge_u32_e32 vcc, v98, v3
	s_add_i32 s4, s4, s6
	s_bcnt1_i32_b64 s6, vcc
	v_cmp_ge_u32_e32 vcc, v101, v3
	s_add_i32 s4, s4, s6
	s_bcnt1_i32_b64 s6, vcc
	v_cmp_ge_u32_e32 vcc, v100, v3
	s_add_i32 s4, s4, s6
	s_bcnt1_i32_b64 s6, vcc
	s_add_i32 s4, s4, s6
	s_andn2_b64 vcc, exec, s[58:59]
	s_cbranch_vccz .LBB0_1124

.LBB0_1117:
	v_cmp_ge_u32_e32 vcc, v119, v3
	s_bcnt1_i32_b64 s6, vcc
	v_cmp_ge_u32_e32 vcc, v118, v3
	s_add_i32 s4, s4, s6
	s_bcnt1_i32_b64 s6, vcc
	v_cmp_ge_u32_e32 vcc, v123, v3
	s_add_i32 s4, s4, s6
	s_bcnt1_i32_b64 s6, vcc
	v_cmp_ge_u32_e32 vcc, v120, v3
	s_add_i32 s4, s4, s6
	s_bcnt1_i32_b64 s6, vcc
	v_cmp_ge_u32_e32 vcc, v125, v3
	s_add_i32 s4, s4, s6
	s_bcnt1_i32_b64 s6, vcc
	v_cmp_ge_u32_e32 vcc, v121, v3
	s_add_i32 s4, s4, s6
	s_bcnt1_i32_b64 s6, vcc
	v_cmp_ge_u32_e32 vcc, v127, v3
	s_add_i32 s4, s4, s6
	s_bcnt1_i32_b64 s6, vcc
	v_cmp_ge_u32_e32 vcc, v122, v3
	s_add_i32 s4, s4, s6
	s_bcnt1_i32_b64 s6, vcc
	v_cmp_ge_u32_e32 vcc, v129, v3
	s_add_i32 s4, s4, s6
	s_bcnt1_i32_b64 s6, vcc
	v_cmp_ge_u32_e32 vcc, v124, v3
	s_add_i32 s4, s4, s6
	s_bcnt1_i32_b64 s6, vcc
	v_cmp_ge_u32_e32 vcc, v131, v3
	s_add_i32 s4, s4, s6
	s_bcnt1_i32_b64 s6, vcc
	v_cmp_ge_u32_e32 vcc, v126, v3
	s_add_i32 s4, s4, s6
	s_bcnt1_i32_b64 s6, vcc
	v_cmp_ge_u32_e32 vcc, v132, v3
	s_add_i32 s4, s4, s6
	s_bcnt1_i32_b64 s6, vcc
	v_cmp_ge_u32_e32 vcc, v128, v3
	s_add_i32 s4, s4, s6
	s_bcnt1_i32_b64 s6, vcc
	v_cmp_ge_u32_e32 vcc, v133, v3
	s_add_i32 s4, s4, s6
	s_bcnt1_i32_b64 s6, vcc
	v_cmp_ge_u32_e32 vcc, v130, v3
	s_add_i32 s4, s4, s6
	s_bcnt1_i32_b64 s6, vcc
	s_add_i32 s4, s4, s6
	s_cmpk_lt_u32 s4, 0x100
	s_cbranch_scc0 .LBB0_1126

.LBB0_1120:
	v_cmp_ge_u32_e32 vcc, v39, v3
	s_bcnt1_i32_b64 s6, vcc
	v_cmp_ge_u32_e32 vcc, v38, v3
	s_add_i32 s4, s4, s6
	s_bcnt1_i32_b64 s6, vcc
	v_cmp_ge_u32_e32 vcc, v41, v3
	s_add_i32 s4, s4, s6
	s_bcnt1_i32_b64 s6, vcc
	v_cmp_ge_u32_e32 vcc, v40, v3
	s_add_i32 s4, s4, s6
	s_bcnt1_i32_b64 s6, vcc
	v_cmp_ge_u32_e32 vcc, v43, v3
	s_add_i32 s4, s4, s6
	s_bcnt1_i32_b64 s6, vcc
	v_cmp_ge_u32_e32 vcc, v42, v3
	s_add_i32 s4, s4, s6
	s_bcnt1_i32_b64 s6, vcc
	v_cmp_ge_u32_e32 vcc, v45, v3
	s_add_i32 s4, s4, s6
	s_bcnt1_i32_b64 s6, vcc
	v_cmp_ge_u32_e32 vcc, v44, v3
	s_add_i32 s4, s4, s6
	s_bcnt1_i32_b64 s6, vcc
	v_cmp_ge_u32_e32 vcc, v47, v3
	s_add_i32 s4, s4, s6
	s_bcnt1_i32_b64 s6, vcc
	v_cmp_ge_u32_e32 vcc, v46, v3
	s_add_i32 s4, s4, s6
	s_bcnt1_i32_b64 s6, vcc
	v_cmp_ge_u32_e32 vcc, v49, v3
	s_add_i32 s4, s4, s6
	s_bcnt1_i32_b64 s6, vcc
	v_cmp_ge_u32_e32 vcc, v48, v3
	s_add_i32 s4, s4, s6
	s_bcnt1_i32_b64 s6, vcc
	v_cmp_ge_u32_e32 vcc, v51, v3
	s_add_i32 s4, s4, s6
	s_bcnt1_i32_b64 s6, vcc
	v_cmp_ge_u32_e32 vcc, v50, v3
	s_add_i32 s4, s4, s6
	s_bcnt1_i32_b64 s6, vcc
	v_cmp_ge_u32_e32 vcc, v53, v3
	s_add_i32 s4, s4, s6
	s_bcnt1_i32_b64 s6, vcc
	v_cmp_ge_u32_e32 vcc, v52, v3
	s_add_i32 s4, s4, s6
	s_bcnt1_i32_b64 s6, vcc
	s_add_i32 s4, s4, s6
	s_andn2_b64 vcc, exec, s[64:65]
	s_cbranch_vccz .LBB0_1113

.LBB0_1122:
	v_cmp_ge_u32_e32 vcc, v71, v3
	s_bcnt1_i32_b64 s6, vcc
	v_cmp_ge_u32_e32 vcc, v70, v3
	s_add_i32 s4, s4, s6
	s_bcnt1_i32_b64 s6, vcc
	v_cmp_ge_u32_e32 vcc, v73, v3
	s_add_i32 s4, s4, s6
	s_bcnt1_i32_b64 s6, vcc
	v_cmp_ge_u32_e32 vcc, v72, v3
	s_add_i32 s4, s4, s6
	s_bcnt1_i32_b64 s6, vcc
	v_cmp_ge_u32_e32 vcc, v75, v3
	s_add_i32 s4, s4, s6
	s_bcnt1_i32_b64 s6, vcc
	v_cmp_ge_u32_e32 vcc, v74, v3
	s_add_i32 s4, s4, s6
	s_bcnt1_i32_b64 s6, vcc
	v_cmp_ge_u32_e32 vcc, v77, v3
	s_add_i32 s4, s4, s6
	s_bcnt1_i32_b64 s6, vcc
	v_cmp_ge_u32_e32 vcc, v76, v3
	s_add_i32 s4, s4, s6
	s_bcnt1_i32_b64 s6, vcc
	v_cmp_ge_u32_e32 vcc, v79, v3
	s_add_i32 s4, s4, s6
	s_bcnt1_i32_b64 s6, vcc
	v_cmp_ge_u32_e32 vcc, v78, v3
	s_add_i32 s4, s4, s6
	s_bcnt1_i32_b64 s6, vcc
	v_cmp_ge_u32_e32 vcc, v81, v3
	s_add_i32 s4, s4, s6
	s_bcnt1_i32_b64 s6, vcc
	v_cmp_ge_u32_e32 vcc, v80, v3
	s_add_i32 s4, s4, s6
	s_bcnt1_i32_b64 s6, vcc
	v_cmp_ge_u32_e32 vcc, v83, v3
	s_add_i32 s4, s4, s6
	s_bcnt1_i32_b64 s6, vcc
	v_cmp_ge_u32_e32 vcc, v82, v3
	s_add_i32 s4, s4, s6
	s_bcnt1_i32_b64 s6, vcc
	v_cmp_ge_u32_e32 vcc, v85, v3
	s_add_i32 s4, s4, s6
	s_bcnt1_i32_b64 s6, vcc
	v_cmp_ge_u32_e32 vcc, v84, v3
	s_add_i32 s4, s4, s6
	s_bcnt1_i32_b64 s6, vcc
	s_add_i32 s4, s4, s6
	s_andn2_b64 vcc, exec, s[60:61]
	s_cbranch_vccz .LBB0_1115

.LBB0_1124:
	v_cmp_ge_u32_e32 vcc, v103, v3
	s_bcnt1_i32_b64 s6, vcc
	v_cmp_ge_u32_e32 vcc, v102, v3
	s_add_i32 s4, s4, s6
	s_bcnt1_i32_b64 s6, vcc
	v_cmp_ge_u32_e32 vcc, v105, v3
	s_add_i32 s4, s4, s6
	s_bcnt1_i32_b64 s6, vcc
	v_cmp_ge_u32_e32 vcc, v104, v3
	s_add_i32 s4, s4, s6
	s_bcnt1_i32_b64 s6, vcc
	v_cmp_ge_u32_e32 vcc, v107, v3
	s_add_i32 s4, s4, s6
	s_bcnt1_i32_b64 s6, vcc
	v_cmp_ge_u32_e32 vcc, v106, v3
	s_add_i32 s4, s4, s6
	s_bcnt1_i32_b64 s6, vcc
	v_cmp_ge_u32_e32 vcc, v109, v3
	s_add_i32 s4, s4, s6
	s_bcnt1_i32_b64 s6, vcc
	v_cmp_ge_u32_e32 vcc, v108, v3
	s_add_i32 s4, s4, s6
	s_bcnt1_i32_b64 s6, vcc
	v_cmp_ge_u32_e32 vcc, v111, v3
	s_add_i32 s4, s4, s6
	s_bcnt1_i32_b64 s6, vcc
	v_cmp_ge_u32_e32 vcc, v110, v3
	s_add_i32 s4, s4, s6
	s_bcnt1_i32_b64 s6, vcc
	v_cmp_ge_u32_e32 vcc, v113, v3
	s_add_i32 s4, s4, s6
	s_bcnt1_i32_b64 s6, vcc
	v_cmp_ge_u32_e32 vcc, v112, v3
	s_add_i32 s4, s4, s6
	s_bcnt1_i32_b64 s6, vcc
	v_cmp_ge_u32_e32 vcc, v115, v3
	s_add_i32 s4, s4, s6
	s_bcnt1_i32_b64 s6, vcc
	v_cmp_ge_u32_e32 vcc, v114, v3
	s_add_i32 s4, s4, s6
	s_bcnt1_i32_b64 s6, vcc
	v_cmp_ge_u32_e32 vcc, v117, v3
	s_add_i32 s4, s4, s6
	s_bcnt1_i32_b64 s6, vcc
	v_cmp_ge_u32_e32 vcc, v116, v3
	s_add_i32 s4, s4, s6
	s_bcnt1_i32_b64 s6, vcc
	s_add_i32 s4, s4, s6
	s_andn2_b64 vcc, exec, s[56:57]
	s_cbranch_vccz .LBB0_1117

.LBB0_1332:
	v_cmp_ge_u32_e32 vcc, v55, v3
	s_bcnt1_i32_b64 s5, vcc
	v_cmp_ge_u32_e32 vcc, v54, v3
	s_add_i32 s4, s4, s5
	s_bcnt1_i32_b64 s5, vcc
	v_cmp_ge_u32_e32 vcc, v57, v3
	s_add_i32 s4, s4, s5
	s_bcnt1_i32_b64 s5, vcc
	v_cmp_ge_u32_e32 vcc, v56, v3
	s_add_i32 s4, s4, s5
	s_bcnt1_i32_b64 s5, vcc
	v_cmp_ge_u32_e32 vcc, v59, v3
	s_add_i32 s4, s4, s5
	s_bcnt1_i32_b64 s5, vcc
	v_cmp_ge_u32_e32 vcc, v58, v3
	s_add_i32 s4, s4, s5
	s_bcnt1_i32_b64 s5, vcc
	v_cmp_ge_u32_e32 vcc, v61, v3
	s_add_i32 s4, s4, s5
	s_bcnt1_i32_b64 s5, vcc
	v_cmp_ge_u32_e32 vcc, v60, v3
	s_add_i32 s4, s4, s5
	s_bcnt1_i32_b64 s5, vcc
	v_cmp_ge_u32_e32 vcc, v63, v3
	s_add_i32 s4, s4, s5
	s_bcnt1_i32_b64 s5, vcc
	v_cmp_ge_u32_e32 vcc, v62, v3
	s_add_i32 s4, s4, s5
	s_bcnt1_i32_b64 s5, vcc
	v_cmp_ge_u32_e32 vcc, v65, v3
	s_add_i32 s4, s4, s5
	s_bcnt1_i32_b64 s5, vcc
	v_cmp_ge_u32_e32 vcc, v64, v3
	s_add_i32 s4, s4, s5
	s_bcnt1_i32_b64 s5, vcc
	v_cmp_ge_u32_e32 vcc, v67, v3
	s_add_i32 s4, s4, s5
	s_bcnt1_i32_b64 s5, vcc
	v_cmp_ge_u32_e32 vcc, v66, v3
	s_add_i32 s4, s4, s5
	s_bcnt1_i32_b64 s5, vcc
	v_cmp_ge_u32_e32 vcc, v69, v3
	s_add_i32 s4, s4, s5
	s_bcnt1_i32_b64 s5, vcc
	v_cmp_ge_u32_e32 vcc, v68, v3
	s_add_i32 s4, s4, s5
	s_bcnt1_i32_b64 s5, vcc
	s_add_i32 s4, s4, s5
	s_cmpk_gt_u32 s3, 0xfff
	s_cselect_b64 s[10:11], -1, 0
	s_cmpk_lt_u32 s3, 0x1000
	s_cbranch_scc0 .LBB0_1103

.LBB0_1334:
	v_cmp_ge_u32_e32 vcc, v87, v3
	s_bcnt1_i32_b64 s5, vcc
	v_cmp_ge_u32_e32 vcc, v86, v3
	s_add_i32 s4, s4, s5
	s_bcnt1_i32_b64 s5, vcc
	v_cmp_ge_u32_e32 vcc, v89, v3
	s_add_i32 s4, s4, s5
	s_bcnt1_i32_b64 s5, vcc
	v_cmp_ge_u32_e32 vcc, v88, v3
	s_add_i32 s4, s4, s5
	s_bcnt1_i32_b64 s5, vcc
	v_cmp_ge_u32_e32 vcc, v91, v3
	s_add_i32 s4, s4, s5
	s_bcnt1_i32_b64 s5, vcc
	v_cmp_ge_u32_e32 vcc, v90, v3
	s_add_i32 s4, s4, s5
	s_bcnt1_i32_b64 s5, vcc
	v_cmp_ge_u32_e32 vcc, v93, v3
	s_add_i32 s4, s4, s5
	s_bcnt1_i32_b64 s5, vcc
	v_cmp_ge_u32_e32 vcc, v92, v3
	s_add_i32 s4, s4, s5
	s_bcnt1_i32_b64 s5, vcc
	v_cmp_ge_u32_e32 vcc, v95, v3
	s_add_i32 s4, s4, s5
	s_bcnt1_i32_b64 s5, vcc
	v_cmp_ge_u32_e32 vcc, v94, v3
	s_add_i32 s4, s4, s5
	s_bcnt1_i32_b64 s5, vcc
	v_cmp_ge_u32_e32 vcc, v97, v3
	s_add_i32 s4, s4, s5
	s_bcnt1_i32_b64 s5, vcc
	v_cmp_ge_u32_e32 vcc, v96, v3
	s_add_i32 s4, s4, s5
	s_bcnt1_i32_b64 s5, vcc
	v_cmp_ge_u32_e32 vcc, v99, v3
	s_add_i32 s4, s4, s5
	s_bcnt1_i32_b64 s5, vcc
	v_cmp_ge_u32_e32 vcc, v98, v3
	s_add_i32 s4, s4, s5
	s_bcnt1_i32_b64 s5, vcc
	v_cmp_ge_u32_e32 vcc, v101, v3
	s_add_i32 s4, s4, s5
	s_bcnt1_i32_b64 s5, vcc
	v_cmp_ge_u32_e32 vcc, v100, v3
	s_add_i32 s4, s4, s5
	s_bcnt1_i32_b64 s5, vcc
	s_add_i32 s4, s4, s5
	s_cmpk_gt_u32 s3, 0x17ff
	s_cselect_b64 s[16:17], -1, 0
	s_cmpk_lt_u32 s3, 0x1800
	s_cbranch_scc0 .LBB0_1105

.LBB0_1336:
	v_cmp_ge_u32_e32 vcc, v119, v3
	s_bcnt1_i32_b64 s5, vcc
	v_cmp_ge_u32_e32 vcc, v118, v3
	s_add_i32 s4, s4, s5
	s_bcnt1_i32_b64 s5, vcc
	v_cmp_ge_u32_e32 vcc, v123, v3
	s_add_i32 s4, s4, s5
	s_bcnt1_i32_b64 s5, vcc
	v_cmp_ge_u32_e32 vcc, v120, v3
	s_add_i32 s4, s4, s5
	s_bcnt1_i32_b64 s5, vcc
	v_cmp_ge_u32_e32 vcc, v125, v3
	s_add_i32 s4, s4, s5
	s_bcnt1_i32_b64 s5, vcc
	v_cmp_ge_u32_e32 vcc, v121, v3
	s_add_i32 s4, s4, s5
	s_bcnt1_i32_b64 s5, vcc
	v_cmp_ge_u32_e32 vcc, v127, v3
	s_add_i32 s4, s4, s5
	s_bcnt1_i32_b64 s5, vcc
	v_cmp_ge_u32_e32 vcc, v122, v3
	s_add_i32 s4, s4, s5
	s_bcnt1_i32_b64 s5, vcc
	v_cmp_ge_u32_e32 vcc, v129, v3
	s_add_i32 s4, s4, s5
	s_bcnt1_i32_b64 s5, vcc
	v_cmp_ge_u32_e32 vcc, v124, v3
	s_add_i32 s4, s4, s5
	s_bcnt1_i32_b64 s5, vcc
	v_cmp_ge_u32_e32 vcc, v131, v3
	s_add_i32 s4, s4, s5
	s_bcnt1_i32_b64 s5, vcc
	v_cmp_ge_u32_e32 vcc, v126, v3
	s_add_i32 s4, s4, s5
	s_bcnt1_i32_b64 s5, vcc
	v_cmp_ge_u32_e32 vcc, v132, v3
	s_add_i32 s4, s4, s5
	s_bcnt1_i32_b64 s5, vcc
	v_cmp_ge_u32_e32 vcc, v128, v3
	s_add_i32 s4, s4, s5
	s_bcnt1_i32_b64 s5, vcc
	v_cmp_ge_u32_e32 vcc, v133, v3
	s_add_i32 s4, s4, s5
	s_bcnt1_i32_b64 s5, vcc
	v_cmp_ge_u32_e32 vcc, v130, v3
	s_add_i32 s4, s4, s5
	s_bcnt1_i32_b64 s5, vcc
	s_add_i32 s4, s4, s5

.LBB0_1338:
	v_add_u32_e32 v135, s26, v3
	v_cmp_ge_u32_e32 vcc, v19, v135
	s_bcnt1_i32_b64 s5, vcc
	v_cmp_ge_u32_e32 vcc, v13, v135
	s_bcnt1_i32_b64 s22, vcc
	v_cmp_ge_u32_e32 vcc, v20, v135
	s_add_i32 s5, s22, s5
	s_bcnt1_i32_b64 s22, vcc
	v_cmp_ge_u32_e32 vcc, v12, v135
	s_add_i32 s5, s5, s22
	s_bcnt1_i32_b64 s22, vcc
	v_cmp_ge_u32_e32 vcc, v18, v135
	s_add_i32 s5, s5, s22
	s_bcnt1_i32_b64 s22, vcc
	v_cmp_ge_u32_e32 vcc, v10, v135
	s_add_i32 s5, s5, s22
	s_bcnt1_i32_b64 s22, vcc
	v_cmp_ge_u32_e32 vcc, v17, v135
	s_add_i32 s5, s5, s22
	s_bcnt1_i32_b64 s22, vcc
	v_cmp_ge_u32_e32 vcc, v9, v135
	s_add_i32 s5, s5, s22
	s_bcnt1_i32_b64 s22, vcc
	v_cmp_ge_u32_e32 vcc, v16, v135
	s_add_i32 s5, s5, s22
	s_bcnt1_i32_b64 s22, vcc
	v_cmp_ge_u32_e32 vcc, v8, v135
	s_add_i32 s5, s5, s22
	s_bcnt1_i32_b64 s22, vcc
	v_cmp_ge_u32_e32 vcc, v15, v135
	s_add_i32 s5, s5, s22
	s_bcnt1_i32_b64 s22, vcc
	v_cmp_ge_u32_e32 vcc, v7, v135
	s_add_i32 s5, s5, s22
	s_bcnt1_i32_b64 s22, vcc
	v_cmp_ge_u32_e32 vcc, v14, v135
	s_add_i32 s5, s5, s22
	s_bcnt1_i32_b64 s22, vcc
	v_cmp_ge_u32_e32 vcc, v5, v135
	s_add_i32 s5, s5, s22
	s_bcnt1_i32_b64 s22, vcc
	v_cmp_ge_u32_e32 vcc, v11, v135
	s_add_i32 s5, s5, s22
	s_bcnt1_i32_b64 s22, vcc
	v_cmp_ge_u32_e32 vcc, v4, v135
	s_add_i32 s5, s5, s22
	s_bcnt1_i32_b64 s22, vcc
	v_cmp_ge_u32_e32 vcc, v22, v135
	s_add_i32 s5, s5, s22
	s_bcnt1_i32_b64 s22, vcc
	v_cmp_ge_u32_e32 vcc, v21, v135
	s_add_i32 s5, s5, s22
	s_bcnt1_i32_b64 s22, vcc
	v_cmp_ge_u32_e32 vcc, v24, v135
	s_add_i32 s5, s5, s22
	s_bcnt1_i32_b64 s22, vcc
	v_cmp_ge_u32_e32 vcc, v23, v135
	s_add_i32 s5, s5, s22
	s_bcnt1_i32_b64 s22, vcc
	v_cmp_ge_u32_e32 vcc, v26, v135
	s_add_i32 s5, s5, s22
	s_bcnt1_i32_b64 s22, vcc
	v_cmp_ge_u32_e32 vcc, v25, v135
	s_add_i32 s5, s5, s22
	s_bcnt1_i32_b64 s22, vcc
	v_cmp_ge_u32_e32 vcc, v28, v135
	s_add_i32 s5, s5, s22
	s_bcnt1_i32_b64 s22, vcc
	v_cmp_ge_u32_e32 vcc, v27, v135
	s_add_i32 s5, s5, s22
	s_bcnt1_i32_b64 s22, vcc
	v_cmp_ge_u32_e32 vcc, v31, v135
	s_add_i32 s5, s5, s22
	s_bcnt1_i32_b64 s22, vcc
	v_cmp_ge_u32_e32 vcc, v29, v135
	s_add_i32 s5, s5, s22
	s_bcnt1_i32_b64 s22, vcc
	v_cmp_ge_u32_e32 vcc, v33, v135
	s_add_i32 s5, s5, s22
	s_bcnt1_i32_b64 s22, vcc
	v_cmp_ge_u32_e32 vcc, v32, v135
	s_add_i32 s5, s5, s22
	s_bcnt1_i32_b64 s22, vcc
	v_cmp_ge_u32_e32 vcc, v35, v135
	s_add_i32 s5, s5, s22
	s_bcnt1_i32_b64 s22, vcc
	v_cmp_ge_u32_e32 vcc, v34, v135
	s_add_i32 s5, s5, s22
	s_bcnt1_i32_b64 s22, vcc
	v_cmp_ge_u32_e32 vcc, v37, v135
	s_add_i32 s5, s5, s22
	s_bcnt1_i32_b64 s22, vcc
	v_cmp_ge_u32_e32 vcc, v36, v135
	s_add_i32 s5, s5, s22
	s_bcnt1_i32_b64 s22, vcc
	s_andn2_b64 vcc, exec, s[6:7]
	s_add_i32 s31, s5, s22
	s_cbranch_vccnz .LBB0_1346
	v_cmp_ge_u32_e32 vcc, v39, v135
	s_bcnt1_i32_b64 s5, vcc
	v_cmp_ge_u32_e32 vcc, v38, v135
	s_add_i32 s5, s31, s5
	s_bcnt1_i32_b64 s22, vcc
	v_cmp_ge_u32_e32 vcc, v41, v135
	s_add_i32 s5, s5, s22
	s_bcnt1_i32_b64 s22, vcc
	v_cmp_ge_u32_e32 vcc, v40, v135
	s_add_i32 s5, s5, s22
	s_bcnt1_i32_b64 s22, vcc
	v_cmp_ge_u32_e32 vcc, v43, v135
	s_add_i32 s5, s5, s22
	s_bcnt1_i32_b64 s22, vcc
	v_cmp_ge_u32_e32 vcc, v42, v135
	s_add_i32 s5, s5, s22
	s_bcnt1_i32_b64 s22, vcc
	v_cmp_ge_u32_e32 vcc, v45, v135
	s_add_i32 s5, s5, s22
	s_bcnt1_i32_b64 s22, vcc
	v_cmp_ge_u32_e32 vcc, v44, v135
	s_add_i32 s5, s5, s22
	s_bcnt1_i32_b64 s22, vcc
	v_cmp_ge_u32_e32 vcc, v47, v135
	s_add_i32 s5, s5, s22
	s_bcnt1_i32_b64 s22, vcc
	v_cmp_ge_u32_e32 vcc, v46, v135
	s_add_i32 s5, s5, s22
	s_bcnt1_i32_b64 s22, vcc
	v_cmp_ge_u32_e32 vcc, v49, v135
	s_add_i32 s5, s5, s22
	s_bcnt1_i32_b64 s22, vcc
	v_cmp_ge_u32_e32 vcc, v48, v135
	s_add_i32 s5, s5, s22
	s_bcnt1_i32_b64 s22, vcc
	v_cmp_ge_u32_e32 vcc, v51, v135
	s_add_i32 s5, s5, s22
	s_bcnt1_i32_b64 s22, vcc
	v_cmp_ge_u32_e32 vcc, v50, v135
	s_add_i32 s5, s5, s22
	s_bcnt1_i32_b64 s22, vcc
	v_cmp_ge_u32_e32 vcc, v53, v135
	s_add_i32 s5, s5, s22
	s_bcnt1_i32_b64 s22, vcc
	v_cmp_ge_u32_e32 vcc, v52, v135
	s_add_i32 s5, s5, s22
	s_bcnt1_i32_b64 s22, vcc
	s_add_i32 s31, s5, s22
	s_andn2_b64 vcc, exec, s[8:9]
	s_cbranch_vccz .LBB0_1347

.LBB0_1857:
	v_lshl_or_b32 v161, 1, v160, v134
	s_waitcnt lgkmcnt(0)
	v_cmp_ge_u32_e32 vcc, v159, v161
	s_bcnt1_i32_b64 s4, vcc
	v_cmp_ge_u32_e32 vcc, v156, v161
	s_bcnt1_i32_b64 s5, vcc
	v_cmp_ge_u32_e32 vcc, v155, v161
	s_add_i32 s4, s5, s4
	s_bcnt1_i32_b64 s5, vcc
	v_cmp_ge_u32_e32 vcc, v152, v161
	s_add_i32 s4, s4, s5
	s_bcnt1_i32_b64 s5, vcc
	v_cmp_ge_u32_e32 vcc, v151, v161
	s_add_i32 s4, s4, s5
	s_bcnt1_i32_b64 s5, vcc
	v_cmp_ge_u32_e32 vcc, v145, v161
	s_add_i32 s4, s4, s5
	s_bcnt1_i32_b64 s5, vcc
	v_cmp_ge_u32_e32 vcc, v144, v161
	s_add_i32 s4, s4, s5
	s_bcnt1_i32_b64 s5, vcc
	v_cmp_ge_u32_e32 vcc, v141, v161
	s_add_i32 s4, s4, s5
	s_bcnt1_i32_b64 s5, vcc
	v_cmp_ge_u32_e32 vcc, v140, v161
	s_add_i32 s4, s4, s5
	s_bcnt1_i32_b64 s5, vcc
	v_cmp_ge_u32_e32 vcc, v137, v161
	s_add_i32 s4, s4, s5
	s_bcnt1_i32_b64 s5, vcc
	v_cmp_ge_u32_e32 vcc, v136, v161
	s_add_i32 s4, s4, s5
	s_bcnt1_i32_b64 s5, vcc
	v_cmp_ge_u32_e32 vcc, v3, v161
	s_add_i32 s4, s4, s5
	s_bcnt1_i32_b64 s5, vcc
	s_add_i32 s4, s4, s5
	s_cmpk_gt_u32 s4, 0xff
	s_cselect_b64 vcc, -1, 0
	s_cmpk_eq_i32 s4, 0x100
	s_cselect_b64 s[30:31], -1, 0
	v_cndmask_b32_e32 v134, v134, v161, vcc
	v_subrev_co_u32_e32 v160, vcc, 1, v160
	s_or_b64 s[4:5], s[30:31], vcc
	s_or_b64 s[72:73], s[30:31], s[72:73]
	s_andn2_b64 vcc, exec, s[4:5]
	s_cbranch_vccnz .LBB0_1857
	s_branch .LBB0_1859

.LBB0_2432:
	v_lshl_add_u32 v146, s6, 8, v1
	v_ashrrev_i32_e32 v147, 31, v146
	v_lshlrev_b64 v[156:157], 6, v[146:147]
	v_lshl_add_u64 v[168:169], s[10:11], 0, v[156:157]
	global_load_dwordx4 v[156:159], v[168:169], off
	global_load_dwordx4 v[160:163], v[168:169], off offset:16
	global_load_dwordx4 v[164:167], v[168:169], off offset:32
	s_nop 0
	global_load_dwordx4 v[168:171], v[168:169], off offset:48
	v_mov_b32_e32 v174, v126
	v_mov_b32_e32 v175, v122
	v_mov_b32_e32 v122, v127
	v_mov_b32_e32 v126, v128
	v_mov_b32_e32 v127, v124
	v_mov_b32_e32 v124, v129
	v_mov_b32_e32 v128, v118
	v_mov_b32_e32 v129, v114
	v_mov_b32_e32 v114, v119
	v_lshl_or_b32 v172, s7, 7, v148
	v_ashrrev_i32_e32 v173, 31, v172
	s_waitcnt vmcnt(0)
	v_mov_b32_e32 v118, v157
	v_mov_b32_e32 v119, v158
	v_mov_b32_e32 v157, v159
	v_mov_b32_e32 v158, v161
	v_mov_b32_e32 v159, v162
	v_mov_b32_e32 v161, v163
	v_pk_add_f32 v[118:119], v[118:119], v[156:157]
	v_pk_add_f32 v[156:157], v[158:159], v[160:161]
	v_pk_add_f32 v[118:119], v[118:119], v[118:119] op_sel:[0,1] op_sel_hi:[1,0]
	v_pk_add_f32 v[156:157], v[156:157], v[156:157] op_sel:[0,1] op_sel_hi:[1,0]
	v_add_f32_e32 v162, v164, v165
	v_add_f32_e32 v164, v166, v167
	v_mov_b32_e32 v163, v170
	v_mov_b32_e32 v165, v171
	v_mov_b32_e32 v119, v168
	v_mov_b32_e32 v157, v169
	v_pk_add_f32 v[158:159], v[162:163], v[164:165]
	v_pk_add_f32 v[118:119], v[118:119], v[156:157]
	s_nop 0
	v_pk_add_f32 v[118:119], v[118:119], v[158:159]
	s_nop 0
	v_add_f32_e32 v118, v118, v119
	v_fmamk_f32 v118, v118, 0x3a800000, v152
	v_mul_f32_e32 v119, 0x4f800000, v118
	v_cmp_gt_f32_e32 vcc, s49, v118
	s_nop 1
	v_cndmask_b32_e32 v147, v118, v119, vcc
	v_sqrt_f32_e32 v156, v147
	v_mov_b32_e32 v118, v120
	v_mov_b32_e32 v119, v116
	v_mov_b32_e32 v116, v121
	v_add_u32_e32 v120, -1, v156
	v_add_u32_e32 v121, 1, v156
	v_fma_f32 v157, -v120, v156, v147
	v_fma_f32 v158, -v121, v156, v147
	v_cmp_ge_f32_e64 s[6:7], 0, v157
	s_nop 1
	v_cndmask_b32_e64 v120, v156, v120, s[6:7]
	v_cmp_lt_f32_e64 s[6:7], 0, v158
	s_nop 1
	v_cndmask_b32_e64 v120, v120, v121, s[6:7]
	v_mul_f32_e32 v121, 0x37800000, v120
	v_cndmask_b32_e32 v120, v120, v121, vcc
	v_cmp_class_f32_e32 vcc, v147, v153
	s_nop 1
	v_cndmask_b32_e32 v120, v120, v147, vcc
	v_div_scale_f32 v121, s[6:7], v120, v120, 1.0
	v_rcp_f32_e32 v147, v121
	v_div_scale_f32 v156, vcc, 1.0, v120, 1.0
	v_fma_f32 v157, -v121, v147, 1.0
	v_fmac_f32_e32 v147, v157, v147
	v_mul_f32_e32 v157, v156, v147
	v_fma_f32 v158, -v121, v157, v156
	v_fmac_f32_e32 v157, v158, v147
	v_fma_f32 v121, -v121, v157, v156
	v_div_fmas_f32 v121, v121, v147, v157
	v_div_fixup_f32 v120, v121, v120, 1.0
	v_pk_mul_f32 v[156:157], v[174:175], v[120:121] op_sel_hi:[1,0]
	v_pk_mul_f32 v[122:123], v[122:123], v[120:121] op_sel_hi:[1,0]
	v_pk_mul_f32 v[114:115], v[114:115], v[120:121] op_sel_hi:[1,0]
	v_pk_mul_f32 v[118:119], v[118:119], v[120:121] op_sel_hi:[1,0]
	v_pk_mul_f32 v[126:127], v[126:127], v[120:121] op_sel_hi:[1,0]
	v_pk_mul_f32 v[124:125], v[124:125], v[120:121] op_sel_hi:[1,0]
	v_pk_mul_f32 v[128:129], v[128:129], v[120:121] op_sel_hi:[1,0]
	v_pk_mul_f32 v[116:117], v[116:117], v[120:121] op_sel_hi:[1,0]
	v_mul_f32_e32 v120, 0xbfb8aa3b, v157
	v_mul_f32_e32 v121, 0xbfb8aa3b, v123
	v_mul_f32_e32 v160, 0xbfb8aa3b, v115
	v_mul_f32_e32 v161, 0xbfb8aa3b, v119
	v_mul_f32_e32 v147, 0xbfb8aa3b, v127
	v_mul_f32_e32 v158, 0xbfb8aa3b, v125
	v_mul_f32_e32 v159, 0xbfb8aa3b, v129
	v_mul_f32_e32 v162, 0xbfb8aa3b, v117
	v_exp_f32_e32 v120, v120
	v_exp_f32_e32 v121, v121
	v_exp_f32_e32 v160, v160
	v_exp_f32_e32 v161, v161
	v_exp_f32_e32 v147, v147
	v_exp_f32_e32 v158, v158
	v_exp_f32_e32 v159, v159
	v_exp_f32_e32 v162, v162
	v_add_f32_e32 v120, 1.0, v120
	v_add_f32_e32 v121, 1.0, v121
	v_add_f32_e32 v160, 1.0, v160
	v_add_f32_e32 v161, 1.0, v161
	v_add_f32_e32 v147, 1.0, v147
	v_add_f32_e32 v158, 1.0, v158
	v_add_f32_e32 v159, 1.0, v159
	v_add_f32_e32 v162, 1.0, v162
	v_rcp_f32_e32 v120, v120
	v_rcp_f32_e32 v121, v121
	v_rcp_f32_e32 v160, v160
	v_rcp_f32_e32 v161, v161
	v_rcp_f32_e32 v147, v147
	v_rcp_f32_e32 v158, v158
	v_rcp_f32_e32 v159, v159
	v_rcp_f32_e32 v162, v162
	v_mul_f32_e32 v120, v157, v120
	v_mul_f32_e32 v121, v123, v121
	v_mul_f32_e32 v115, v115, v160
	v_mul_f32_e32 v119, v119, v161
	v_mul_f32_e32 v123, v127, v147
	v_mul_f32_e32 v125, v125, v158
	v_mul_f32_e32 v127, v129, v159
	v_mul_f32_e32 v117, v117, v162
	v_mul_f32_e32 v120, v156, v120
	v_mul_f32_e32 v121, v122, v121
	v_mul_f32_e32 v114, v114, v115
	v_mul_f32_e32 v115, v118, v119
	v_mul_f32_e32 v122, v126, v123
	v_mul_f32_e32 v123, v124, v125
	v_mul_f32_e32 v124, v128, v127
	v_mul_f32_e32 v116, v116, v117
	v_cvt_pk_bf16_f32 v118, v120, v121
	v_cvt_pk_bf16_f32 v119, v122, v123
	v_cvt_pk_bf16_f32 v120, v124, v114
	v_cvt_pk_bf16_f32 v121, v115, v116
	v_mov_b64_e32 v[114:115], s[8:9]
	v_mad_i64_i32 v[122:123], s[6:7], v146, s50, v[114:115]
	v_lshlrev_b64 v[116:117], 1, v[172:173]
	v_lshl_add_u64 v[122:123], v[122:123], 0, v[116:117]
	global_store_dwordx4 v[122:123], v[118:121], off nt
	s_nop 1
	v_or_b32_e32 v118, 16, v146
	v_ashrrev_i32_e32 v119, 31, v118
	v_lshlrev_b64 v[120:121], 6, v[118:119]
	v_lshl_add_u64 v[128:129], s[10:11], 0, v[120:121]
	global_load_dwordx4 v[120:123], v[128:129], off
	global_load_dwordx4 v[124:127], v[128:129], off offset:16
	global_load_dwordx4 v[156:159], v[128:129], off offset:32
	global_load_dwordx4 v[160:163], v[128:129], off offset:48
	v_mov_b32_e32 v128, v110
	v_mov_b32_e32 v110, v112
	v_mov_b32_e32 v112, v98
	v_mov_b32_e32 v129, v106
	v_mov_b32_e32 v106, v111
	v_mov_b32_e32 v111, v108
	v_mov_b32_e32 v108, v113
	v_mov_b32_e32 v113, v102
	s_waitcnt vmcnt(3)
	v_mov_b32_e32 v164, v121
	v_mov_b32_e32 v165, v122
	v_mov_b32_e32 v121, v123
	s_waitcnt vmcnt(2)
	v_mov_b32_e32 v122, v125
	v_mov_b32_e32 v123, v126
	v_mov_b32_e32 v125, v127
	v_pk_add_f32 v[120:121], v[164:165], v[120:121]
	v_pk_add_f32 v[122:123], v[122:123], v[124:125]
	v_pk_add_f32 v[120:121], v[120:121], v[120:121] op_sel:[0,1] op_sel_hi:[1,0]
	v_pk_add_f32 v[122:123], v[122:123], v[122:123] op_sel:[0,1] op_sel_hi:[1,0]
	s_waitcnt vmcnt(1)
	v_add_f32_e32 v126, v156, v157
	v_add_f32_e32 v156, v158, v159
	s_waitcnt vmcnt(0)
	v_mov_b32_e32 v127, v162
	v_mov_b32_e32 v157, v163
	v_mov_b32_e32 v121, v160
	v_mov_b32_e32 v123, v161
	v_pk_add_f32 v[124:125], v[126:127], v[156:157]
	v_pk_add_f32 v[120:121], v[120:121], v[122:123]
	s_nop 0
	v_pk_add_f32 v[120:121], v[120:121], v[124:125]
	s_nop 0
	v_add_f32_e32 v98, v120, v121
	v_fmamk_f32 v98, v98, 0x3a800000, v152
	v_mul_f32_e32 v102, 0x4f800000, v98
	v_cmp_gt_f32_e32 vcc, s49, v98
	s_nop 1
	v_cndmask_b32_e32 v119, v98, v102, vcc
	v_sqrt_f32_e32 v120, v119
	v_mov_b32_e32 v98, v100
	v_mov_b32_e32 v102, v99
	v_mov_b32_e32 v99, v104
	v_add_u32_e32 v100, -1, v120
	v_add_u32_e32 v104, 1, v120
	v_fma_f32 v121, -v100, v120, v119
	v_fma_f32 v122, -v104, v120, v119
	v_cmp_ge_f32_e64 s[6:7], 0, v121
	s_nop 1
	v_cndmask_b32_e64 v100, v120, v100, s[6:7]
	v_cmp_lt_f32_e64 s[6:7], 0, v122
	s_nop 1
	v_cndmask_b32_e64 v100, v100, v104, s[6:7]
	v_mul_f32_e32 v104, 0x37800000, v100
	v_cndmask_b32_e32 v100, v100, v104, vcc
	v_cmp_class_f32_e32 vcc, v119, v153
	v_mov_b32_e32 v104, v101
	s_nop 0
	v_cndmask_b32_e32 v100, v100, v119, vcc
	v_div_scale_f32 v119, s[6:7], v100, v100, 1.0
	v_rcp_f32_e32 v120, v119
	v_div_scale_f32 v101, vcc, 1.0, v100, 1.0
	v_fma_f32 v121, -v119, v120, 1.0
	v_fmac_f32_e32 v120, v121, v120
	v_mul_f32_e32 v121, v101, v120
	v_fma_f32 v122, -v119, v121, v101
	v_fmac_f32_e32 v121, v122, v120
	v_fma_f32 v101, -v119, v121, v101
	v_div_fmas_f32 v101, v101, v120, v121
	v_div_fixup_f32 v100, v101, v100, 1.0
	v_pk_mul_f32 v[106:107], v[106:107], v[100:101] op_sel_hi:[1,0]
	v_pk_mul_f32 v[110:111], v[110:111], v[100:101] op_sel_hi:[1,0]
	v_pk_mul_f32 v[108:109], v[108:109], v[100:101] op_sel_hi:[1,0]
	v_pk_mul_f32 v[120:121], v[128:129], v[100:101] op_sel_hi:[1,0]
	v_pk_mul_f32 v[112:113], v[112:113], v[100:101] op_sel_hi:[1,0]
	v_pk_mul_f32 v[102:103], v[102:103], v[100:101] op_sel_hi:[1,0]
	v_pk_mul_f32 v[98:99], v[98:99], v[100:101] op_sel_hi:[1,0]
	v_pk_mul_f32 v[100:101], v[104:105], v[100:101] op_sel_hi:[1,0]
	v_mul_f32_e32 v105, 0xbfb8aa3b, v107
	v_mul_f32_e32 v119, 0xbfb8aa3b, v111
	v_mul_f32_e32 v122, 0xbfb8aa3b, v109
	v_exp_f32_e32 v105, v105
	v_exp_f32_e32 v119, v119
	v_exp_f32_e32 v122, v122
	v_mul_f32_e32 v124, 0xbfb8aa3b, v103
	v_mul_f32_e32 v125, 0xbfb8aa3b, v99
	v_mul_f32_e32 v126, 0xbfb8aa3b, v101
	v_exp_f32_e32 v124, v124
	v_exp_f32_e32 v125, v125
	v_add_f32_e32 v105, 1.0, v105
	v_add_f32_e32 v119, 1.0, v119
	v_add_f32_e32 v122, 1.0, v122
	v_mul_f32_e32 v104, 0xbfb8aa3b, v121
	v_mul_f32_e32 v123, 0xbfb8aa3b, v113
	v_exp_f32_e32 v126, v126
	v_rcp_f32_e32 v105, v105
	v_rcp_f32_e32 v119, v119
	v_rcp_f32_e32 v122, v122
	v_exp_f32_e32 v104, v104
	v_exp_f32_e32 v123, v123
	v_add_f32_e32 v124, 1.0, v124
	v_add_f32_e32 v125, 1.0, v125
	v_add_f32_e32 v126, 1.0, v126
	v_rcp_f32_e32 v124, v124
	v_rcp_f32_e32 v125, v125
	v_mul_f32_e32 v105, v107, v105
	v_mul_f32_e32 v107, v111, v119
	v_mul_f32_e32 v109, v109, v122
	v_add_f32_e32 v104, 1.0, v104
	v_add_f32_e32 v123, 1.0, v123
	v_mul_f32_e32 v105, v106, v105
	v_mul_f32_e32 v106, v110, v107
	v_mul_f32_e32 v107, v108, v109
	v_rcp_f32_e32 v109, v126
	v_rcp_f32_e32 v104, v104
	v_rcp_f32_e32 v123, v123
	v_mul_f32_e32 v103, v103, v124
	v_mul_f32_e32 v99, v99, v125
	v_mul_f32_e32 v102, v102, v103
	v_mul_f32_e32 v103, v98, v99
	v_mul_f32_e32 v98, v101, v109
	v_mul_f32_e32 v104, v121, v104
	v_mul_f32_e32 v111, v113, v123
	v_mul_f32_e32 v101, v100, v98
	v_mul_f32_e32 v104, v120, v104
	v_mul_f32_e32 v108, v112, v111
	v_cvt_pk_bf16_f32 v98, v104, v105
	v_cvt_pk_bf16_f32 v99, v106, v107
	v_cvt_pk_bf16_f32 v100, v108, v102
	v_cvt_pk_bf16_f32 v101, v103, v101
	v_mad_i64_i32 v[102:103], s[6:7], v118, s50, v[114:115]
	v_lshl_add_u64 v[102:103], v[102:103], 0, v[116:117]
	global_store_dwordx4 v[102:103], v[98:101], off nt
	s_nop 1
	v_or_b32_e32 v98, 32, v146
	v_ashrrev_i32_e32 v99, 31, v98
	v_lshlrev_b64 v[100:101], 6, v[98:99]
	v_lshl_add_u64 v[112:113], s[10:11], 0, v[100:101]
	global_load_dwordx4 v[100:103], v[112:113], off
	global_load_dwordx4 v[104:107], v[112:113], off offset:16
	global_load_dwordx4 v[108:111], v[112:113], off offset:32
	global_load_dwordx4 v[118:121], v[112:113], off offset:48
	v_mov_b32_e32 v112, v94
	v_mov_b32_e32 v94, v96
	v_mov_b32_e32 v96, v82
	v_mov_b32_e32 v113, v90
	v_mov_b32_e32 v90, v95
	v_mov_b32_e32 v95, v92
	v_mov_b32_e32 v92, v97
	v_mov_b32_e32 v97, v86
	s_waitcnt vmcnt(3)
	v_mov_b32_e32 v122, v101
	v_mov_b32_e32 v123, v102
	v_mov_b32_e32 v101, v103
	s_waitcnt vmcnt(2)
	v_mov_b32_e32 v102, v105
	v_mov_b32_e32 v103, v106
	v_mov_b32_e32 v105, v107
	v_pk_add_f32 v[100:101], v[122:123], v[100:101]
	v_pk_add_f32 v[102:103], v[102:103], v[104:105]
	v_pk_add_f32 v[100:101], v[100:101], v[100:101] op_sel:[0,1] op_sel_hi:[1,0]
	v_pk_add_f32 v[102:103], v[102:103], v[102:103] op_sel:[0,1] op_sel_hi:[1,0]
	s_waitcnt vmcnt(1)
	v_add_f32_e32 v106, v108, v109
	v_add_f32_e32 v108, v110, v111
	s_waitcnt vmcnt(0)
	v_mov_b32_e32 v107, v120
	v_mov_b32_e32 v109, v121
	v_mov_b32_e32 v101, v118
	v_mov_b32_e32 v103, v119
	v_pk_add_f32 v[104:105], v[106:107], v[108:109]
	v_pk_add_f32 v[100:101], v[100:101], v[102:103]
	s_nop 0
	v_pk_add_f32 v[100:101], v[100:101], v[104:105]
	s_nop 0
	v_add_f32_e32 v82, v100, v101
	v_fmamk_f32 v82, v82, 0x3a800000, v152
	v_mul_f32_e32 v86, 0x4f800000, v82
	v_cmp_gt_f32_e32 vcc, s49, v82
	s_nop 1
	v_cndmask_b32_e32 v99, v82, v86, vcc
	v_sqrt_f32_e32 v100, v99
	v_mov_b32_e32 v82, v84
	v_mov_b32_e32 v86, v83
	v_mov_b32_e32 v83, v88
	v_add_u32_e32 v84, -1, v100
	v_add_u32_e32 v88, 1, v100
	v_fma_f32 v101, -v84, v100, v99
	v_fma_f32 v102, -v88, v100, v99
	v_cmp_ge_f32_e64 s[6:7], 0, v101
	s_nop 1
	v_cndmask_b32_e64 v84, v100, v84, s[6:7]
	v_cmp_lt_f32_e64 s[6:7], 0, v102
	s_nop 1
	v_cndmask_b32_e64 v84, v84, v88, s[6:7]
	v_mul_f32_e32 v88, 0x37800000, v84
	v_cndmask_b32_e32 v84, v84, v88, vcc
	v_cmp_class_f32_e32 vcc, v99, v153
	v_mov_b32_e32 v88, v85
	s_nop 0
	v_cndmask_b32_e32 v84, v84, v99, vcc
	v_div_scale_f32 v99, s[6:7], v84, v84, 1.0
	v_rcp_f32_e32 v100, v99
	v_div_scale_f32 v85, vcc, 1.0, v84, 1.0
	v_fma_f32 v101, -v99, v100, 1.0
	v_fmac_f32_e32 v100, v101, v100
	v_mul_f32_e32 v101, v85, v100
	v_fma_f32 v102, -v99, v101, v85
	v_fmac_f32_e32 v101, v102, v100
	v_fma_f32 v85, -v99, v101, v85
	v_div_fmas_f32 v85, v85, v100, v101
	v_div_fixup_f32 v84, v85, v84, 1.0
	v_pk_mul_f32 v[90:91], v[90:91], v[84:85] op_sel_hi:[1,0]
	v_pk_mul_f32 v[94:95], v[94:95], v[84:85] op_sel_hi:[1,0]
	v_pk_mul_f32 v[92:93], v[92:93], v[84:85] op_sel_hi:[1,0]
	v_pk_mul_f32 v[100:101], v[112:113], v[84:85] op_sel_hi:[1,0]
	v_pk_mul_f32 v[96:97], v[96:97], v[84:85] op_sel_hi:[1,0]
	v_pk_mul_f32 v[86:87], v[86:87], v[84:85] op_sel_hi:[1,0]
	v_pk_mul_f32 v[82:83], v[82:83], v[84:85] op_sel_hi:[1,0]
	v_pk_mul_f32 v[84:85], v[88:89], v[84:85] op_sel_hi:[1,0]
	v_mul_f32_e32 v89, 0xbfb8aa3b, v91
	v_mul_f32_e32 v99, 0xbfb8aa3b, v95
	v_mul_f32_e32 v102, 0xbfb8aa3b, v93
	v_exp_f32_e32 v89, v89
	v_exp_f32_e32 v99, v99
	v_exp_f32_e32 v102, v102
	v_mul_f32_e32 v104, 0xbfb8aa3b, v87
	v_add_f32_e32 v89, 1.0, v89
	v_add_f32_e32 v99, 1.0, v99
	v_add_f32_e32 v102, 1.0, v102
	v_rcp_f32_e32 v89, v89
	v_rcp_f32_e32 v99, v99
	v_rcp_f32_e32 v102, v102
	v_mul_f32_e32 v105, 0xbfb8aa3b, v83
	v_mul_f32_e32 v89, v91, v89
	v_mul_f32_e32 v91, v95, v99
	v_mul_f32_e32 v93, v93, v102
	v_exp_f32_e32 v104, v104
	v_exp_f32_e32 v105, v105
	v_mul_f32_e32 v89, v90, v89
	v_mul_f32_e32 v90, v94, v91
	v_mul_f32_e32 v91, v92, v93
	v_mul_f32_e32 v93, 0xbfb8aa3b, v85
	v_mul_f32_e32 v88, 0xbfb8aa3b, v101
	v_mul_f32_e32 v103, 0xbfb8aa3b, v97
	v_exp_f32_e32 v93, v93
	v_exp_f32_e32 v88, v88
	v_exp_f32_e32 v103, v103
	v_add_f32_e32 v104, 1.0, v104
	v_add_f32_e32 v94, 1.0, v105
	v_rcp_f32_e32 v104, v104
	v_rcp_f32_e32 v94, v94
	v_add_f32_e32 v93, 1.0, v93
	v_add_f32_e32 v88, 1.0, v88
	v_add_f32_e32 v103, 1.0, v103
	v_rcp_f32_e32 v93, v93
	v_rcp_f32_e32 v88, v88
	v_rcp_f32_e32 v103, v103
	v_mul_f32_e32 v87, v87, v104
	v_mul_f32_e32 v83, v83, v94
	v_mul_f32_e32 v86, v86, v87
	v_mul_f32_e32 v87, v82, v83
	v_mul_f32_e32 v82, v85, v93
	v_mul_f32_e32 v88, v101, v88
	v_mul_f32_e32 v95, v97, v103
	v_mul_f32_e32 v85, v84, v82
	v_mul_f32_e32 v88, v100, v88
	v_mul_f32_e32 v92, v96, v95
	v_cvt_pk_bf16_f32 v82, v88, v89
	v_cvt_pk_bf16_f32 v83, v90, v91
	v_cvt_pk_bf16_f32 v84, v92, v86
	v_cvt_pk_bf16_f32 v85, v87, v85
	v_mad_i64_i32 v[86:87], s[6:7], v98, s50, v[114:115]
	v_lshl_add_u64 v[86:87], v[86:87], 0, v[116:117]
	global_store_dwordx4 v[86:87], v[82:85], off nt
	v_mov_b32_e32 v100, v78
	v_mov_b32_e32 v101, v74
	v_or_b32_e32 v82, 48, v146
	v_ashrrev_i32_e32 v83, 31, v82
	v_lshlrev_b64 v[84:85], 6, v[82:83]
	v_lshl_add_u64 v[96:97], s[10:11], 0, v[84:85]
	global_load_dwordx4 v[84:87], v[96:97], off
	global_load_dwordx4 v[88:91], v[96:97], off offset:16
	global_load_dwordx4 v[92:95], v[96:97], off offset:32
	s_nop 0
	global_load_dwordx4 v[96:99], v[96:97], off offset:48
	v_mov_b32_e32 v74, v79
	v_mov_b32_e32 v78, v80
	v_mov_b32_e32 v79, v76
	v_mov_b32_e32 v76, v81
	s_waitcnt vmcnt(3)
	v_mov_b32_e32 v80, v85
	v_mov_b32_e32 v81, v86
	v_mov_b32_e32 v85, v87
	s_waitcnt vmcnt(2)
	v_mov_b32_e32 v86, v89
	v_mov_b32_e32 v87, v90
	v_mov_b32_e32 v89, v91
	v_pk_add_f32 v[80:81], v[80:81], v[84:85]
	v_pk_add_f32 v[84:85], v[86:87], v[88:89]
	v_pk_add_f32 v[80:81], v[80:81], v[80:81] op_sel:[0,1] op_sel_hi:[1,0]
	v_pk_add_f32 v[84:85], v[84:85], v[84:85] op_sel:[0,1] op_sel_hi:[1,0]
	s_waitcnt vmcnt(1)
	v_add_f32_e32 v90, v92, v93
	v_add_f32_e32 v92, v94, v95
	s_waitcnt vmcnt(0)
	v_mov_b32_e32 v91, v98
	v_mov_b32_e32 v93, v99
	v_mov_b32_e32 v81, v96
	v_mov_b32_e32 v85, v97
	v_pk_add_f32 v[86:87], v[90:91], v[92:93]
	v_pk_add_f32 v[80:81], v[80:81], v[84:85]
	s_nop 0
	v_pk_add_f32 v[80:81], v[80:81], v[86:87]
	s_nop 0
	v_add_f32_e32 v80, v80, v81
	v_fmamk_f32 v80, v80, 0x3a800000, v152
	v_mul_f32_e32 v81, 0x4f800000, v80
	v_cmp_gt_f32_e32 vcc, s49, v80
	s_nop 1
	v_cndmask_b32_e32 v83, v80, v81, vcc
	v_sqrt_f32_e32 v84, v83
	v_mov_b32_e32 v80, v66
	v_mov_b32_e32 v81, v70
	v_mov_b32_e32 v70, v67
	v_add_u32_e32 v66, -1, v84
	v_add_u32_e32 v67, 1, v84
	v_fma_f32 v85, -v66, v84, v83
	v_fma_f32 v86, -v67, v84, v83
	v_cmp_ge_f32_e64 s[6:7], 0, v85
	s_nop 1
	v_cndmask_b32_e64 v66, v84, v66, s[6:7]
	v_cmp_lt_f32_e64 s[6:7], 0, v86
	s_nop 1
	v_cndmask_b32_e64 v66, v66, v67, s[6:7]
	v_mul_f32_e32 v67, 0x37800000, v66
	v_cndmask_b32_e32 v66, v66, v67, vcc
	v_cmp_class_f32_e32 vcc, v83, v153
	s_nop 1
	v_cndmask_b32_e32 v67, v66, v83, vcc
	v_div_scale_f32 v83, s[6:7], v67, v67, 1.0
	v_rcp_f32_e32 v84, v83
	v_mov_b32_e32 v66, v68
	v_div_scale_f32 v68, vcc, 1.0, v67, 1.0
	v_fma_f32 v85, -v83, v84, 1.0
	v_fmac_f32_e32 v84, v85, v84
	v_mul_f32_e32 v85, v68, v84
	v_fma_f32 v86, -v83, v85, v68
	v_fmac_f32_e32 v85, v86, v84
	v_fma_f32 v68, -v83, v85, v68
	v_div_fmas_f32 v68, v68, v84, v85
	v_div_fixup_f32 v68, v68, v67, 1.0
	v_pk_mul_f32 v[84:85], v[100:101], v[68:69] op_sel_hi:[1,0]
	v_pk_mul_f32 v[74:75], v[74:75], v[68:69] op_sel_hi:[1,0]
	v_mul_f32_e32 v67, 0xbfb8aa3b, v85
	v_mul_f32_e32 v83, 0xbfb8aa3b, v75
	v_exp_f32_e32 v67, v67
	v_pk_mul_f32 v[78:79], v[78:79], v[68:69] op_sel_hi:[1,0]
	v_exp_f32_e32 v83, v83
	v_mul_f32_e32 v86, 0xbfb8aa3b, v79
	v_exp_f32_e32 v86, v86
	v_add_f32_e32 v67, 1.0, v67
	v_add_f32_e32 v83, 1.0, v83
	v_rcp_f32_e32 v67, v67
	v_rcp_f32_e32 v83, v83
	v_add_f32_e32 v86, 1.0, v86
	v_rcp_f32_e32 v86, v86
	v_mul_f32_e32 v67, v85, v67
	v_mul_f32_e32 v75, v75, v83
	v_mul_f32_e32 v83, v84, v67
	v_mov_b32_e32 v67, v72
	v_pk_mul_f32 v[66:67], v[66:67], v[68:69] op_sel_hi:[1,0]
	v_mul_f32_e32 v79, v79, v86
	v_mul_f32_e32 v72, 0xbfb8aa3b, v67
	v_pk_mul_f32 v[70:71], v[70:71], v[68:69] op_sel_hi:[1,0]
	v_mul_f32_e32 v74, v74, v75
	v_mul_f32_e32 v75, v78, v79
	v_exp_f32_e32 v78, v72
	v_mov_b32_e32 v72, v69
	v_pk_mul_f32 v[76:77], v[76:77], v[68:69] op_sel_hi:[1,0]
	v_pk_mul_f32 v[80:81], v[80:81], v[68:69] op_sel_hi:[1,0]
	v_mul_f32_e32 v89, 0xbfb8aa3b, v71
	v_pk_mul_f32 v[68:69], v[72:73], v[68:69] op_sel_hi:[1,0]
	v_exp_f32_e32 v89, v89
	v_mul_f32_e32 v72, 0xbfb8aa3b, v69
	v_mul_f32_e32 v87, 0xbfb8aa3b, v77
	v_mul_f32_e32 v88, 0xbfb8aa3b, v81
	v_exp_f32_e32 v72, v72
	v_exp_f32_e32 v87, v87
	v_exp_f32_e32 v88, v88
	v_add_f32_e32 v89, 1.0, v89
	v_add_f32_e32 v73, 1.0, v78
	v_rcp_f32_e32 v89, v89
	v_rcp_f32_e32 v73, v73
	v_add_f32_e32 v72, 1.0, v72
	v_add_f32_e32 v87, 1.0, v87
	v_add_f32_e32 v88, 1.0, v88
	v_rcp_f32_e32 v72, v72
	v_rcp_f32_e32 v87, v87
	v_rcp_f32_e32 v88, v88
	v_mul_f32_e32 v71, v71, v89
	v_mul_f32_e32 v67, v67, v73
	v_mul_f32_e32 v70, v70, v71
	v_mul_f32_e32 v71, v66, v67
	v_mul_f32_e32 v66, v69, v72
	v_mul_f32_e32 v77, v77, v87
	v_mul_f32_e32 v81, v81, v88
	v_mul_f32_e32 v69, v68, v66
	v_mul_f32_e32 v76, v76, v77
	v_mul_f32_e32 v77, v80, v81
	v_cvt_pk_bf16_f32 v66, v83, v74
	v_cvt_pk_bf16_f32 v67, v75, v76
	v_cvt_pk_bf16_f32 v68, v77, v70
	v_cvt_pk_bf16_f32 v69, v71, v69
	v_mad_i64_i32 v[70:71], s[6:7], v82, s50, v[114:115]
	v_lshl_add_u64 v[70:71], v[70:71], 0, v[116:117]
	global_store_dwordx4 v[70:71], v[66:69], off nt
	v_mov_b32_e32 v85, v58
	v_mov_b32_e32 v58, v63
	v_add_u32_e32 v66, 0x80, v146
	v_ashrrev_i32_e32 v67, 31, v66
	v_lshlrev_b64 v[68:69], 6, v[66:67]
	v_lshl_add_u64 v[80:81], s[10:11], 0, v[68:69]
	global_load_dwordx4 v[68:71], v[80:81], off
	global_load_dwordx4 v[72:75], v[80:81], off offset:16
	global_load_dwordx4 v[76:79], v[80:81], off offset:32
	s_nop 0
	global_load_dwordx4 v[80:83], v[80:81], off offset:48
	v_mov_b32_e32 v63, v60
	v_mov_b32_e32 v84, v62
	v_mov_b32_e32 v62, v64
	s_waitcnt vmcnt(3)
	v_mov_b32_e32 v86, v69
	v_mov_b32_e32 v87, v70
	v_mov_b32_e32 v69, v71
	s_waitcnt vmcnt(2)
	v_mov_b32_e32 v70, v73
	v_mov_b32_e32 v71, v74
	v_mov_b32_e32 v73, v75
	v_pk_add_f32 v[68:69], v[86:87], v[68:69]
	v_pk_add_f32 v[70:71], v[70:71], v[72:73]
	v_pk_add_f32 v[68:69], v[68:69], v[68:69] op_sel:[0,1] op_sel_hi:[1,0]
	v_pk_add_f32 v[70:71], v[70:71], v[70:71] op_sel:[0,1] op_sel_hi:[1,0]
	s_waitcnt vmcnt(1)
	v_add_f32_e32 v74, v76, v77
	v_add_f32_e32 v76, v78, v79
	s_waitcnt vmcnt(0)
	v_mov_b32_e32 v75, v82
	v_mov_b32_e32 v77, v83
	v_mov_b32_e32 v69, v80
	v_mov_b32_e32 v71, v81
	v_pk_add_f32 v[72:73], v[74:75], v[76:77]
	v_pk_add_f32 v[68:69], v[68:69], v[70:71]
	s_nop 0
	v_pk_add_f32 v[68:69], v[68:69], v[72:73]
	s_nop 0
	v_add_f32_e32 v60, v68, v69
	v_fmamk_f32 v60, v60, 0x3a800000, v152
	v_mul_f32_e32 v64, 0x4f800000, v60
	v_cmp_gt_f32_e32 vcc, s49, v60
	s_nop 1
	v_cndmask_b32_e32 v67, v60, v64, vcc
	v_sqrt_f32_e32 v68, v67
	v_mov_b32_e32 v64, v50
	v_mov_b32_e32 v60, v65
	v_mov_b32_e32 v65, v54
	v_add_u32_e32 v50, -1, v68
	v_add_u32_e32 v54, 1, v68
	v_fma_f32 v69, -v50, v68, v67
	v_fma_f32 v70, -v54, v68, v67
	v_cmp_ge_f32_e64 s[6:7], 0, v69
	s_nop 1
	v_cndmask_b32_e64 v50, v68, v50, s[6:7]
	v_cmp_lt_f32_e64 s[6:7], 0, v70
	s_nop 1
	v_cndmask_b32_e64 v50, v50, v54, s[6:7]
	v_mul_f32_e32 v54, 0x37800000, v50
	v_cndmask_b32_e32 v50, v50, v54, vcc
	v_cmp_class_f32_e32 vcc, v67, v153
	v_mov_b32_e32 v54, v51
	s_nop 0
	v_cndmask_b32_e32 v50, v50, v67, vcc
	v_div_scale_f32 v67, s[6:7], v50, v50, 1.0
	v_rcp_f32_e32 v68, v67
	v_div_scale_f32 v51, vcc, 1.0, v50, 1.0
	v_fma_f32 v69, -v67, v68, 1.0
	v_fmac_f32_e32 v68, v69, v68
	v_mul_f32_e32 v69, v51, v68
	v_fma_f32 v70, -v67, v69, v51
	v_fmac_f32_e32 v69, v70, v68
	v_fma_f32 v51, -v67, v69, v51
	v_div_fmas_f32 v51, v51, v68, v69
	v_div_fixup_f32 v50, v51, v50, 1.0
	v_pk_mul_f32 v[68:69], v[84:85], v[50:51] op_sel_hi:[1,0]
	v_pk_mul_f32 v[58:59], v[58:59], v[50:51] op_sel_hi:[1,0]
	v_pk_mul_f32 v[62:63], v[62:63], v[50:51] op_sel_hi:[1,0]
	v_pk_mul_f32 v[60:61], v[60:61], v[50:51] op_sel_hi:[1,0]
	v_pk_mul_f32 v[64:65], v[64:65], v[50:51] op_sel_hi:[1,0]
	v_pk_mul_f32 v[54:55], v[54:55], v[50:51] op_sel_hi:[1,0]
	v_mul_f32_e32 v51, 0xbfb8aa3b, v69
	v_mul_f32_e32 v67, 0xbfb8aa3b, v59
	v_mul_f32_e32 v71, 0xbfb8aa3b, v61
	v_mul_f32_e32 v72, 0xbfb8aa3b, v65
	v_exp_f32_e32 v51, v51
	v_exp_f32_e32 v67, v67
	v_exp_f32_e32 v71, v71
	v_exp_f32_e32 v72, v72
	v_mul_f32_e32 v70, 0xbfb8aa3b, v63
	v_exp_f32_e32 v70, v70
	v_add_f32_e32 v51, 1.0, v51
	v_add_f32_e32 v67, 1.0, v67
	v_add_f32_e32 v71, 1.0, v71
	v_add_f32_e32 v72, 1.0, v72
	v_rcp_f32_e32 v51, v51
	v_mul_f32_e32 v73, 0xbfb8aa3b, v55
	v_rcp_f32_e32 v67, v67
	v_rcp_f32_e32 v71, v71
	v_rcp_f32_e32 v72, v72
	v_exp_f32_e32 v73, v73
	v_add_f32_e32 v70, 1.0, v70
	v_rcp_f32_e32 v70, v70
	v_mul_f32_e32 v51, v69, v51
	v_mul_f32_e32 v59, v59, v67
	v_mul_f32_e32 v61, v61, v71
	v_mul_f32_e32 v67, v68, v51
	v_mul_f32_e32 v51, v65, v72
	v_mul_f32_e32 v68, v58, v59
	v_mul_f32_e32 v60, v60, v61
	v_mul_f32_e32 v61, v64, v51
	v_add_f32_e32 v51, 1.0, v73
	v_mov_b32_e32 v58, v52
	v_mov_b32_e32 v59, v56
	v_mul_f32_e32 v63, v63, v70
	v_pk_mul_f32 v[58:59], v[58:59], v[50:51] op_sel_hi:[1,0]
	v_mul_f32_e32 v62, v62, v63
	v_rcp_f32_e32 v63, v51
	v_mul_f32_e32 v51, 0xbfb8aa3b, v59
	v_mov_b32_e32 v56, v53
	v_exp_f32_e32 v52, v51
	v_pk_mul_f32 v[50:51], v[56:57], v[50:51] op_sel_hi:[1,0]
	v_mul_f32_e32 v55, v55, v63
	v_mul_f32_e32 v53, 0xbfb8aa3b, v51
	v_exp_f32_e32 v53, v53
	v_add_f32_e32 v52, 1.0, v52
	v_rcp_f32_e32 v52, v52
	v_mul_f32_e32 v54, v54, v55
	v_add_f32_e32 v53, 1.0, v53
	v_rcp_f32_e32 v53, v53
	v_mul_f32_e32 v52, v59, v52
	v_mul_f32_e32 v55, v58, v52
	v_mov_b32_e32 v69, v42
	v_mul_f32_e32 v51, v51, v53
	v_mul_f32_e32 v53, v50, v51
	v_cvt_pk_bf16_f32 v50, v67, v68
	v_cvt_pk_bf16_f32 v51, v62, v60
	v_cvt_pk_bf16_f32 v52, v61, v54
	v_cvt_pk_bf16_f32 v53, v55, v53
	v_mad_i64_i32 v[54:55], s[6:7], v66, s50, v[114:115]
	v_add_u32_e32 v66, 0x90, v146
	v_lshl_add_u64 v[54:55], v[54:55], 0, v[116:117]
	v_ashrrev_i32_e32 v67, 31, v66
	global_store_dwordx4 v[54:55], v[50:53], off nt
	v_mov_b32_e32 v42, v47
	v_mov_b32_e32 v68, v46
	v_lshlrev_b64 v[50:51], 6, v[66:67]
	v_lshl_add_u64 v[62:63], s[10:11], 0, v[50:51]
	global_load_dwordx4 v[50:53], v[62:63], off
	global_load_dwordx4 v[54:57], v[62:63], off offset:16
	global_load_dwordx4 v[58:61], v[62:63], off offset:32
	s_nop 0
	global_load_dwordx4 v[62:65], v[62:63], off offset:48
	v_mov_b32_e32 v46, v48
	s_waitcnt vmcnt(3)
	v_mov_b32_e32 v70, v51
	v_mov_b32_e32 v71, v52
	v_mov_b32_e32 v51, v53
	s_waitcnt vmcnt(2)
	v_mov_b32_e32 v52, v55
	v_mov_b32_e32 v53, v56
	v_mov_b32_e32 v55, v57
	v_pk_add_f32 v[50:51], v[70:71], v[50:51]
	v_pk_add_f32 v[52:53], v[52:53], v[54:55]
	v_pk_add_f32 v[50:51], v[50:51], v[50:51] op_sel:[0,1] op_sel_hi:[1,0]
	v_pk_add_f32 v[52:53], v[52:53], v[52:53] op_sel:[0,1] op_sel_hi:[1,0]
	s_waitcnt vmcnt(1)
	v_add_f32_e32 v56, v58, v59
	v_add_f32_e32 v58, v60, v61
	s_waitcnt vmcnt(0)
	v_mov_b32_e32 v57, v64
	v_mov_b32_e32 v59, v65
	v_mov_b32_e32 v51, v62
	v_mov_b32_e32 v53, v63
	v_pk_add_f32 v[54:55], v[56:57], v[58:59]
	v_pk_add_f32 v[50:51], v[50:51], v[52:53]
	s_nop 0
	v_pk_add_f32 v[50:51], v[50:51], v[54:55]
	s_nop 0
	v_add_f32_e32 v47, v50, v51
	v_fmamk_f32 v47, v47, 0x3a800000, v152
	v_mul_f32_e32 v48, 0x4f800000, v47
	v_cmp_gt_f32_e32 vcc, s49, v47
	s_nop 1
	v_cndmask_b32_e32 v50, v47, v48, vcc
	v_sqrt_f32_e32 v51, v50
	v_mov_b32_e32 v48, v34
	v_mov_b32_e32 v47, v44
	v_mov_b32_e32 v44, v49
	v_add_u32_e32 v34, -1, v51
	v_add_u32_e32 v49, 1, v51
	v_fma_f32 v52, -v34, v51, v50
	v_fma_f32 v53, -v49, v51, v50
	v_cmp_ge_f32_e64 s[6:7], 0, v52
	s_nop 1
	v_cndmask_b32_e64 v34, v51, v34, s[6:7]
	v_cmp_lt_f32_e64 s[6:7], 0, v53
	s_nop 1
	v_cndmask_b32_e64 v34, v34, v49, s[6:7]
	v_mul_f32_e32 v49, 0x37800000, v34
	v_cndmask_b32_e32 v34, v34, v49, vcc
	v_cmp_class_f32_e32 vcc, v50, v153
	v_mov_b32_e32 v49, v38
	s_nop 0
	v_cndmask_b32_e32 v34, v34, v50, vcc
	v_div_scale_f32 v50, s[6:7], v34, v34, 1.0
	v_rcp_f32_e32 v51, v50
	v_div_scale_f32 v38, vcc, 1.0, v34, 1.0
	v_fma_f32 v52, -v50, v51, 1.0
	v_fmac_f32_e32 v51, v52, v51
	v_mul_f32_e32 v52, v38, v51
	v_fma_f32 v53, -v50, v52, v38
	v_fmac_f32_e32 v52, v53, v51
	v_fma_f32 v38, -v50, v52, v38
	v_div_fmas_f32 v38, v38, v51, v52
	v_div_fixup_f32 v34, v38, v34, 1.0
	v_pk_mul_f32 v[50:51], v[68:69], v[34:35] op_sel_hi:[1,0]
	v_pk_mul_f32 v[42:43], v[42:43], v[34:35] op_sel_hi:[1,0]
	v_mul_f32_e32 v38, 0xbfb8aa3b, v51
	v_mul_f32_e32 v52, 0xbfb8aa3b, v43
	v_exp_f32_e32 v38, v38
	v_exp_f32_e32 v52, v52
	v_pk_mul_f32 v[48:49], v[48:49], v[34:35] op_sel_hi:[1,0]
	v_pk_mul_f32 v[44:45], v[44:45], v[34:35] op_sel_hi:[1,0]
	v_add_f32_e32 v38, 1.0, v38
	v_mul_f32_e32 v55, 0xbfb8aa3b, v49
	v_add_f32_e32 v52, 1.0, v52
	v_rcp_f32_e32 v38, v38
	v_exp_f32_e32 v55, v55
	v_rcp_f32_e32 v52, v52
	v_mul_f32_e32 v54, 0xbfb8aa3b, v45
	v_pk_mul_f32 v[46:47], v[46:47], v[34:35] op_sel_hi:[1,0]
	v_exp_f32_e32 v54, v54
	v_mul_f32_e32 v53, 0xbfb8aa3b, v47
	v_mul_f32_e32 v38, v51, v38
	v_exp_f32_e32 v53, v53
	v_mul_f32_e32 v43, v43, v52
	v_mul_f32_e32 v50, v50, v38
	v_add_f32_e32 v38, 1.0, v55
	v_mul_f32_e32 v51, v42, v43
	v_rcp_f32_e32 v42, v38
	v_mov_b32_e32 v38, v35
	v_add_f32_e32 v54, 1.0, v54
	v_pk_mul_f32 v[38:39], v[38:39], v[34:35] op_sel_hi:[1,0]
	v_rcp_f32_e32 v54, v54
	v_mul_f32_e32 v35, 0xbfb8aa3b, v39
	v_add_f32_e32 v53, 1.0, v53
	v_exp_f32_e32 v35, v35
	v_rcp_f32_e32 v53, v53
	v_mul_f32_e32 v45, v45, v54
	v_mul_f32_e32 v42, v49, v42
	v_mul_f32_e32 v44, v44, v45
	v_mul_f32_e32 v45, v48, v42
	v_add_f32_e32 v35, 1.0, v35
	v_mov_b32_e32 v42, v36
	v_mov_b32_e32 v43, v40
	v_mul_f32_e32 v47, v47, v53
	v_pk_mul_f32 v[42:43], v[42:43], v[34:35] op_sel_hi:[1,0]
	v_mul_f32_e32 v46, v46, v47
	v_rcp_f32_e32 v47, v35
	v_mul_f32_e32 v35, 0xbfb8aa3b, v43
	v_mov_b32_e32 v40, v37
	v_exp_f32_e32 v36, v35
	v_pk_mul_f32 v[34:35], v[40:41], v[34:35] op_sel_hi:[1,0]
	v_mul_f32_e32 v39, v39, v47
	v_mul_f32_e32 v37, 0xbfb8aa3b, v35
	v_exp_f32_e32 v37, v37
	v_add_f32_e32 v36, 1.0, v36
	v_rcp_f32_e32 v36, v36
	v_mul_f32_e32 v38, v38, v39
	v_add_f32_e32 v37, 1.0, v37
	v_rcp_f32_e32 v37, v37
	v_mul_f32_e32 v36, v43, v36
	v_mul_f32_e32 v39, v42, v36
	v_mov_b32_e32 v53, v26
	v_mul_f32_e32 v35, v35, v37
	v_mul_f32_e32 v37, v34, v35
	v_cvt_pk_bf16_f32 v34, v50, v51
	v_cvt_pk_bf16_f32 v35, v46, v44
	v_cvt_pk_bf16_f32 v36, v45, v38
	v_cvt_pk_bf16_f32 v37, v39, v37
	v_mad_i64_i32 v[38:39], s[6:7], v66, s50, v[114:115]
	v_add_u32_e32 v50, 0xa0, v146
	v_lshl_add_u64 v[38:39], v[38:39], 0, v[116:117]
	v_ashrrev_i32_e32 v51, 31, v50
	global_store_dwordx4 v[38:39], v[34:37], off nt
	v_mov_b32_e32 v26, v31
	v_mov_b32_e32 v52, v30
	v_lshlrev_b64 v[34:35], 6, v[50:51]
	v_lshl_add_u64 v[46:47], s[10:11], 0, v[34:35]
	global_load_dwordx4 v[34:37], v[46:47], off
	global_load_dwordx4 v[38:41], v[46:47], off offset:16
	global_load_dwordx4 v[42:45], v[46:47], off offset:32
	s_nop 0
	global_load_dwordx4 v[46:49], v[46:47], off offset:48
	v_mov_b32_e32 v30, v32
	s_waitcnt vmcnt(3)
	v_mov_b32_e32 v54, v35
	v_mov_b32_e32 v55, v36
	v_mov_b32_e32 v35, v37
	s_waitcnt vmcnt(2)
	v_mov_b32_e32 v36, v39
	v_mov_b32_e32 v37, v40
	v_mov_b32_e32 v39, v41
	v_pk_add_f32 v[34:35], v[54:55], v[34:35]
	v_pk_add_f32 v[36:37], v[36:37], v[38:39]
	v_pk_add_f32 v[34:35], v[34:35], v[34:35] op_sel:[0,1] op_sel_hi:[1,0]
	v_pk_add_f32 v[36:37], v[36:37], v[36:37] op_sel:[0,1] op_sel_hi:[1,0]
	s_waitcnt vmcnt(1)
	v_add_f32_e32 v40, v42, v43
	v_add_f32_e32 v42, v44, v45
	s_waitcnt vmcnt(0)
	v_mov_b32_e32 v41, v48
	v_mov_b32_e32 v43, v49
	v_mov_b32_e32 v35, v46
	v_mov_b32_e32 v37, v47
	v_pk_add_f32 v[38:39], v[40:41], v[42:43]
	v_pk_add_f32 v[34:35], v[34:35], v[36:37]
	s_nop 0
	v_pk_add_f32 v[34:35], v[34:35], v[38:39]
	s_nop 0
	v_add_f32_e32 v31, v34, v35
	v_fmamk_f32 v31, v31, 0x3a800000, v152
	v_mul_f32_e32 v32, 0x4f800000, v31
	v_cmp_gt_f32_e32 vcc, s49, v31
	s_nop 1
	v_cndmask_b32_e32 v34, v31, v32, vcc
	v_sqrt_f32_e32 v35, v34
	v_mov_b32_e32 v32, v18
	v_mov_b32_e32 v31, v28
	v_mov_b32_e32 v28, v33
	v_add_u32_e32 v18, -1, v35
	v_add_u32_e32 v33, 1, v35
	v_fma_f32 v36, -v18, v35, v34
	v_fma_f32 v37, -v33, v35, v34
	v_cmp_ge_f32_e64 s[6:7], 0, v36
	s_nop 1
	v_cndmask_b32_e64 v18, v35, v18, s[6:7]
	v_cmp_lt_f32_e64 s[6:7], 0, v37
	s_nop 1
	v_cndmask_b32_e64 v18, v18, v33, s[6:7]
	v_mul_f32_e32 v33, 0x37800000, v18
	v_cndmask_b32_e32 v18, v18, v33, vcc
	v_cmp_class_f32_e32 vcc, v34, v153
	v_mov_b32_e32 v33, v22
	s_nop 0
	v_cndmask_b32_e32 v18, v18, v34, vcc
	v_div_scale_f32 v34, s[6:7], v18, v18, 1.0
	v_rcp_f32_e32 v35, v34
	v_div_scale_f32 v22, vcc, 1.0, v18, 1.0
	v_fma_f32 v36, -v34, v35, 1.0
	v_fmac_f32_e32 v35, v36, v35
	v_mul_f32_e32 v36, v22, v35
	v_fma_f32 v37, -v34, v36, v22
	v_fmac_f32_e32 v36, v37, v35
	v_fma_f32 v22, -v34, v36, v22
	v_div_fmas_f32 v22, v22, v35, v36
	v_div_fixup_f32 v18, v22, v18, 1.0
	v_pk_mul_f32 v[26:27], v[26:27], v[18:19] op_sel_hi:[1,0]
	v_pk_mul_f32 v[34:35], v[52:53], v[18:19] op_sel_hi:[1,0]
	v_mul_f32_e32 v36, 0xbfb8aa3b, v27
	v_mul_f32_e32 v22, 0xbfb8aa3b, v35
	v_exp_f32_e32 v36, v36
	v_exp_f32_e32 v22, v22
	v_pk_mul_f32 v[30:31], v[30:31], v[18:19] op_sel_hi:[1,0]
	v_pk_mul_f32 v[28:29], v[28:29], v[18:19] op_sel_hi:[1,0]
	v_add_f32_e32 v36, 1.0, v36
	v_add_f32_e32 v22, 1.0, v22
	v_rcp_f32_e32 v36, v36
	v_mul_f32_e32 v37, 0xbfb8aa3b, v31
	v_rcp_f32_e32 v22, v22
	v_exp_f32_e32 v37, v37
	v_mul_f32_e32 v27, v27, v36
	v_mul_f32_e32 v38, 0xbfb8aa3b, v29
	v_mul_f32_e32 v22, v35, v22
	v_mul_f32_e32 v35, v26, v27
	v_pk_mul_f32 v[26:27], v[32:33], v[18:19] op_sel_hi:[1,0]
	v_add_f32_e32 v37, 1.0, v37
	v_mul_f32_e32 v34, v34, v22
	v_mul_f32_e32 v22, 0xbfb8aa3b, v27
	v_rcp_f32_e32 v37, v37
	v_exp_f32_e32 v22, v22
	v_exp_f32_e32 v38, v38
	v_mov_b32_e32 v36, v10
	v_mul_f32_e32 v31, v31, v37
	v_add_f32_e32 v22, 1.0, v22
	v_mul_f32_e32 v30, v30, v31
	v_rcp_f32_e32 v31, v22
	v_mov_b32_e32 v22, v19
	v_add_f32_e32 v38, 1.0, v38
	v_pk_mul_f32 v[22:23], v[22:23], v[18:19] op_sel_hi:[1,0]
	v_rcp_f32_e32 v38, v38
	v_mul_f32_e32 v19, 0xbfb8aa3b, v23
	v_exp_f32_e32 v19, v19
	v_mul_f32_e32 v27, v27, v31
	v_mul_f32_e32 v29, v29, v38
	v_mul_f32_e32 v28, v28, v29
	v_mul_f32_e32 v29, v26, v27
	v_add_f32_e32 v19, 1.0, v19
	v_mov_b32_e32 v26, v20
	v_mov_b32_e32 v27, v24
	v_pk_mul_f32 v[26:27], v[26:27], v[18:19] op_sel_hi:[1,0]
	v_rcp_f32_e32 v31, v19
	v_mul_f32_e32 v19, 0xbfb8aa3b, v27
	v_mov_b32_e32 v24, v21
	v_exp_f32_e32 v20, v19
	v_pk_mul_f32 v[18:19], v[24:25], v[18:19] op_sel_hi:[1,0]
	v_mul_f32_e32 v23, v23, v31
	v_mul_f32_e32 v21, 0xbfb8aa3b, v19
	v_exp_f32_e32 v21, v21
	v_add_f32_e32 v20, 1.0, v20
	v_rcp_f32_e32 v20, v20
	v_mul_f32_e32 v22, v22, v23
	v_add_f32_e32 v21, 1.0, v21
	v_rcp_f32_e32 v21, v21
	v_mul_f32_e32 v20, v27, v20
	v_mul_f32_e32 v23, v26, v20
	v_mov_b32_e32 v37, v14
	v_mul_f32_e32 v19, v19, v21
	v_mul_f32_e32 v21, v18, v19
	v_cvt_pk_bf16_f32 v18, v34, v35
	v_cvt_pk_bf16_f32 v19, v30, v28
	v_cvt_pk_bf16_f32 v20, v29, v22
	v_cvt_pk_bf16_f32 v21, v23, v21
	v_mad_i64_i32 v[22:23], s[6:7], v50, s50, v[114:115]
	v_add_u32_e32 v34, 0xb0, v146
	v_lshl_add_u64 v[22:23], v[22:23], 0, v[116:117]
	v_ashrrev_i32_e32 v35, 31, v34
	global_store_dwordx4 v[22:23], v[18:21], off nt
	s_nop 1
	v_lshlrev_b64 v[18:19], 6, v[34:35]
	v_lshl_add_u64 v[30:31], s[10:11], 0, v[18:19]
	global_load_dwordx4 v[18:21], v[30:31], off
	global_load_dwordx4 v[22:25], v[30:31], off offset:16
	global_load_dwordx4 v[26:29], v[30:31], off offset:32
	s_nop 0
	global_load_dwordx4 v[30:33], v[30:31], off offset:48
	s_waitcnt vmcnt(3)
	v_mov_b32_e32 v38, v19
	v_mov_b32_e32 v39, v20
	v_mov_b32_e32 v19, v21
	s_waitcnt vmcnt(2)
	v_mov_b32_e32 v20, v23
	v_mov_b32_e32 v21, v24
	v_mov_b32_e32 v23, v25
	v_pk_add_f32 v[18:19], v[38:39], v[18:19]
	v_pk_add_f32 v[20:21], v[20:21], v[22:23]
	v_pk_add_f32 v[18:19], v[18:19], v[18:19] op_sel:[0,1] op_sel_hi:[1,0]
	v_pk_add_f32 v[20:21], v[20:21], v[20:21] op_sel:[0,1] op_sel_hi:[1,0]
	s_waitcnt vmcnt(1)
	v_add_f32_e32 v24, v26, v27
	v_add_f32_e32 v26, v28, v29
	s_waitcnt vmcnt(0)
	v_mov_b32_e32 v25, v32
	v_mov_b32_e32 v27, v33
	v_mov_b32_e32 v19, v30
	v_mov_b32_e32 v21, v31
	v_pk_add_f32 v[22:23], v[24:25], v[26:27]
	v_pk_add_f32 v[18:19], v[18:19], v[20:21]
	s_nop 0
	v_pk_add_f32 v[18:19], v[18:19], v[22:23]
	s_nop 0
	v_add_f32_e32 v10, v18, v19
	v_fmamk_f32 v10, v10, 0x3a800000, v152
	v_mul_f32_e32 v14, 0x4f800000, v10
	v_cmp_gt_f32_e32 vcc, s49, v10
	s_nop 1
	v_cndmask_b32_e32 v18, v10, v14, vcc
	v_sqrt_f32_e32 v19, v18
	v_mov_b32_e32 v10, v12
	v_mov_b32_e32 v14, v11
	v_mov_b32_e32 v11, v16
	v_add_u32_e32 v12, -1, v19
	v_add_u32_e32 v16, 1, v19
	v_fma_f32 v20, -v12, v19, v18
	v_fma_f32 v21, -v16, v19, v18
	v_cmp_ge_f32_e64 s[6:7], 0, v20
	s_nop 1
	v_cndmask_b32_e64 v12, v19, v12, s[6:7]
	v_cmp_lt_f32_e64 s[6:7], 0, v21
	s_nop 1
	v_cndmask_b32_e64 v12, v12, v16, s[6:7]
	v_mul_f32_e32 v16, 0x37800000, v12
	v_cndmask_b32_e32 v12, v12, v16, vcc
	v_cmp_class_f32_e32 vcc, v18, v153
	v_mov_b32_e32 v16, v13
	s_nop 0
	v_cndmask_b32_e32 v12, v12, v18, vcc
	v_div_scale_f32 v18, s[6:7], v12, v12, 1.0
	v_rcp_f32_e32 v19, v18
	v_div_scale_f32 v13, vcc, 1.0, v12, 1.0
	v_fma_f32 v20, -v18, v19, 1.0
	v_fmac_f32_e32 v19, v20, v19
	v_mul_f32_e32 v20, v13, v19
	v_fma_f32 v21, -v18, v20, v13
	v_fmac_f32_e32 v20, v21, v19
	v_fma_f32 v13, -v18, v20, v13
	v_div_fmas_f32 v13, v13, v19, v20
	v_div_fixup_f32 v12, v13, v12, 1.0
	v_pk_mul_f32 v[18:19], v[36:37], v[12:13] op_sel_hi:[1,0]
	v_pk_mul_f32 v[14:15], v[14:15], v[12:13] op_sel_hi:[1,0]
	v_pk_mul_f32 v[10:11], v[10:11], v[12:13] op_sel_hi:[1,0]
	v_pk_mul_f32 v[16:17], v[16:17], v[12:13] op_sel_hi:[1,0]
	v_mul_f32_e32 v13, 0xbfb8aa3b, v19
	v_mul_f32_e32 v20, 0xbfb8aa3b, v15
	v_exp_f32_e32 v13, v13
	v_exp_f32_e32 v20, v20
	v_mul_f32_e32 v21, 0xbfb8aa3b, v11
	v_mul_f32_e32 v22, 0xbfb8aa3b, v17
	v_add_f32_e32 v13, 1.0, v13
	v_add_f32_e32 v20, 1.0, v20
	v_rcp_f32_e32 v13, v13
	v_rcp_f32_e32 v20, v20
	v_exp_f32_e32 v21, v21
	v_exp_f32_e32 v22, v22
	v_mul_f32_e32 v13, v19, v13
	v_mul_f32_e32 v15, v15, v20
	v_mul_f32_e32 v13, v18, v13
	v_mul_f32_e32 v18, v14, v15
	v_add_f32_e32 v14, 1.0, v21
	v_rcp_f32_e32 v19, v14
	v_add_f32_e32 v14, 1.0, v22
	v_rcp_f32_e32 v20, v14
	v_mov_b32_e32 v14, v2
	v_mov_b32_e32 v15, v6
	v_pk_mul_f32 v[14:15], v[14:15], v[12:13] op_sel_hi:[1,0]
	v_mul_f32_e32 v6, v11, v19
	v_mul_f32_e32 v2, 0xbfb8aa3b, v15
	v_exp_f32_e32 v2, v2
	v_mul_f32_e32 v10, v10, v6
	v_mov_b32_e32 v6, v3
	v_mul_f32_e32 v11, v17, v20
	v_add_f32_e32 v2, 1.0, v2
	v_rcp_f32_e32 v17, v2
	v_pk_mul_f32 v[2:3], v[6:7], v[12:13] op_sel_hi:[1,0]
	v_mul_f32_e32 v11, v16, v11
	v_mul_f32_e32 v6, 0xbfb8aa3b, v3
	v_exp_f32_e32 v6, v6
	v_mul_f32_e32 v7, v15, v17
	v_mul_f32_e32 v14, v14, v7
	v_mov_b32_e32 v7, v8
	v_add_f32_e32 v6, 1.0, v6
	v_rcp_f32_e32 v15, v6
	v_mov_b32_e32 v6, v4
	v_pk_mul_f32 v[6:7], v[6:7], v[12:13] op_sel_hi:[1,0]
	v_mov_b32_e32 v8, v5
	v_mul_f32_e32 v4, 0xbfb8aa3b, v7
	v_exp_f32_e32 v16, v4
	v_pk_mul_f32 v[4:5], v[8:9], v[12:13] op_sel_hi:[1,0]
	v_mul_f32_e32 v3, v3, v15
	v_mul_f32_e32 v8, 0xbfb8aa3b, v5
	v_exp_f32_e32 v8, v8
	v_add_f32_e32 v9, 1.0, v16
	v_rcp_f32_e32 v9, v9
	v_mul_f32_e32 v12, v2, v3
	v_add_f32_e32 v8, 1.0, v8
	v_rcp_f32_e32 v8, v8
	v_mul_f32_e32 v2, v7, v9
	v_mul_f32_e32 v6, v6, v2
	s_andn2_b64 vcc, exec, s[4:5]
	v_mul_f32_e32 v2, v5, v8
	v_mul_f32_e32 v5, v4, v2
	v_cvt_pk_bf16_f32 v2, v13, v18
	v_cvt_pk_bf16_f32 v3, v10, v11
	v_cvt_pk_bf16_f32 v4, v14, v12
	v_cvt_pk_bf16_f32 v5, v6, v5
	v_mad_i64_i32 v[6:7], s[6:7], v34, s50, v[114:115]
	v_lshl_add_u64 v[6:7], v[6:7], 0, v[116:117]
	s_mov_b64 s[4:5], -1
	global_store_dwordx4 v[6:7], v[2:5], off nt
	s_cbranch_vccnz .LBB0_2425
	s_andn2_b64 vcc, exec, s[2:3]
	s_cbranch_vccnz .LBB0_2424
	s_barrier
	s_branch .LBB0_2424

.LBB0_3358:
	s_waitcnt vmcnt(0) lgkmcnt(0)
	s_cmpk_lt_u32 s61, 0x400
	s_cbranch_scc1 .LBB0_3365
	v_lshl_or_b32 v3, v6, 23, v172
	s_waitcnt vmcnt(0) lgkmcnt(0)
	v_cmp_ge_u32_e32 vcc, v19, v3
	s_bcnt1_i32_b64 s0, vcc
	v_cmp_ge_u32_e32 vcc, v13, v3
	s_bcnt1_i32_b64 s1, vcc
	v_cmp_ge_u32_e32 vcc, v20, v3
	s_add_i32 s0, s1, s0
	s_bcnt1_i32_b64 s1, vcc
	v_cmp_ge_u32_e32 vcc, v12, v3
	s_add_i32 s0, s0, s1
	s_bcnt1_i32_b64 s1, vcc
	v_cmp_ge_u32_e32 vcc, v18, v3
	s_add_i32 s0, s0, s1
	s_bcnt1_i32_b64 s1, vcc
	v_cmp_ge_u32_e32 vcc, v10, v3
	s_add_i32 s0, s0, s1
	s_bcnt1_i32_b64 s1, vcc
	v_cmp_ge_u32_e32 vcc, v17, v3
	s_add_i32 s0, s0, s1
	s_bcnt1_i32_b64 s1, vcc
	v_cmp_ge_u32_e32 vcc, v9, v3
	s_add_i32 s0, s0, s1
	s_bcnt1_i32_b64 s1, vcc
	v_cmp_ge_u32_e32 vcc, v16, v3
	s_add_i32 s0, s0, s1
	s_bcnt1_i32_b64 s1, vcc
	v_cmp_ge_u32_e32 vcc, v8, v3
	s_add_i32 s0, s0, s1
	s_bcnt1_i32_b64 s1, vcc
	v_cmp_ge_u32_e32 vcc, v15, v3
	s_add_i32 s0, s0, s1
	s_bcnt1_i32_b64 s1, vcc
	v_cmp_ge_u32_e32 vcc, v7, v3
	s_add_i32 s0, s0, s1
	s_bcnt1_i32_b64 s1, vcc
	v_cmp_ge_u32_e32 vcc, v14, v3
	s_add_i32 s0, s0, s1
	s_bcnt1_i32_b64 s1, vcc
	v_cmp_ge_u32_e32 vcc, v5, v3
	s_add_i32 s0, s0, s1
	s_bcnt1_i32_b64 s1, vcc
	v_cmp_ge_u32_e32 vcc, v11, v3
	s_add_i32 s0, s0, s1
	s_bcnt1_i32_b64 s1, vcc
	v_cmp_ge_u32_e32 vcc, v4, v3
	s_add_i32 s0, s0, s1
	s_bcnt1_i32_b64 s1, vcc
	v_cmp_ge_u32_e32 vcc, v22, v3
	s_add_i32 s0, s0, s1
	s_bcnt1_i32_b64 s1, vcc
	v_cmp_ge_u32_e32 vcc, v21, v3
	s_add_i32 s0, s0, s1
	s_bcnt1_i32_b64 s1, vcc
	v_cmp_ge_u32_e32 vcc, v24, v3
	s_add_i32 s0, s0, s1
	s_bcnt1_i32_b64 s1, vcc
	v_cmp_ge_u32_e32 vcc, v23, v3
	s_add_i32 s0, s0, s1
	s_bcnt1_i32_b64 s1, vcc
	v_cmp_ge_u32_e32 vcc, v26, v3
	s_add_i32 s0, s0, s1
	s_bcnt1_i32_b64 s1, vcc
	v_cmp_ge_u32_e32 vcc, v25, v3
	s_add_i32 s0, s0, s1
	s_bcnt1_i32_b64 s1, vcc
	v_cmp_ge_u32_e32 vcc, v28, v3
	s_add_i32 s0, s0, s1
	s_bcnt1_i32_b64 s1, vcc
	v_cmp_ge_u32_e32 vcc, v27, v3
	s_add_i32 s0, s0, s1
	s_bcnt1_i32_b64 s1, vcc
	v_cmp_ge_u32_e32 vcc, v31, v3
	s_add_i32 s0, s0, s1
	s_bcnt1_i32_b64 s1, vcc
	v_cmp_ge_u32_e32 vcc, v29, v3
	s_add_i32 s0, s0, s1
	s_bcnt1_i32_b64 s1, vcc
	v_cmp_ge_u32_e32 vcc, v33, v3
	s_add_i32 s0, s0, s1
	s_bcnt1_i32_b64 s1, vcc
	v_cmp_ge_u32_e32 vcc, v32, v3
	s_add_i32 s0, s0, s1
	s_bcnt1_i32_b64 s1, vcc
	v_cmp_ge_u32_e32 vcc, v35, v3
	s_add_i32 s0, s0, s1
	s_bcnt1_i32_b64 s1, vcc
	v_cmp_ge_u32_e32 vcc, v34, v3
	s_add_i32 s0, s0, s1
	s_bcnt1_i32_b64 s1, vcc
	v_cmp_ge_u32_e32 vcc, v37, v3
	s_add_i32 s0, s0, s1
	s_bcnt1_i32_b64 s1, vcc
	v_cmp_ge_u32_e32 vcc, v36, v3
	s_add_i32 s0, s0, s1
	s_bcnt1_i32_b64 s1, vcc
	s_add_i32 s4, s0, s1
	s_cmpk_gt_u32 s61, 0x7ff
	s_cselect_b64 s[0:1], -1, 0
	s_cmpk_lt_u32 s61, 0x800
	s_cbranch_scc1 .LBB0_3590
	v_cmp_ge_u32_e32 vcc, v39, v3
	s_bcnt1_i32_b64 s5, vcc
	v_cmp_ge_u32_e32 vcc, v38, v3
	s_add_i32 s4, s4, s5
	s_bcnt1_i32_b64 s5, vcc
	v_cmp_ge_u32_e32 vcc, v41, v3
	s_add_i32 s4, s4, s5
	s_bcnt1_i32_b64 s5, vcc
	v_cmp_ge_u32_e32 vcc, v40, v3
	s_add_i32 s4, s4, s5
	s_bcnt1_i32_b64 s5, vcc
	v_cmp_ge_u32_e32 vcc, v43, v3
	s_add_i32 s4, s4, s5
	s_bcnt1_i32_b64 s5, vcc
	v_cmp_ge_u32_e32 vcc, v42, v3
	s_add_i32 s4, s4, s5
	s_bcnt1_i32_b64 s5, vcc
	v_cmp_ge_u32_e32 vcc, v45, v3
	s_add_i32 s4, s4, s5
	s_bcnt1_i32_b64 s5, vcc
	v_cmp_ge_u32_e32 vcc, v44, v3
	s_add_i32 s4, s4, s5
	s_bcnt1_i32_b64 s5, vcc
	v_cmp_ge_u32_e32 vcc, v47, v3
	s_add_i32 s4, s4, s5
	s_bcnt1_i32_b64 s5, vcc
	v_cmp_ge_u32_e32 vcc, v46, v3
	s_add_i32 s4, s4, s5
	s_bcnt1_i32_b64 s5, vcc
	v_cmp_ge_u32_e32 vcc, v49, v3
	s_add_i32 s4, s4, s5
	s_bcnt1_i32_b64 s5, vcc
	v_cmp_ge_u32_e32 vcc, v48, v3
	s_add_i32 s4, s4, s5
	s_bcnt1_i32_b64 s5, vcc
	v_cmp_ge_u32_e32 vcc, v51, v3
	s_add_i32 s4, s4, s5
	s_bcnt1_i32_b64 s5, vcc
	v_cmp_ge_u32_e32 vcc, v50, v3
	s_add_i32 s4, s4, s5
	s_bcnt1_i32_b64 s5, vcc
	v_cmp_ge_u32_e32 vcc, v53, v3
	s_add_i32 s4, s4, s5
	s_bcnt1_i32_b64 s5, vcc
	v_cmp_ge_u32_e32 vcc, v52, v3
	s_add_i32 s4, s4, s5
	s_bcnt1_i32_b64 s5, vcc
	s_add_i32 s4, s4, s5
	s_cmpk_gt_u32 s61, 0xbff
	s_cselect_b64 s[6:7], -1, 0
	s_cmpk_lt_u32 s61, 0xc00
	s_cbranch_scc0 .LBB0_3591

.LBB0_3362:
	v_cmp_ge_u32_e32 vcc, v71, v3
	s_bcnt1_i32_b64 s5, vcc
	v_cmp_ge_u32_e32 vcc, v70, v3
	s_add_i32 s4, s4, s5
	s_bcnt1_i32_b64 s5, vcc
	v_cmp_ge_u32_e32 vcc, v73, v3
	s_add_i32 s4, s4, s5
	s_bcnt1_i32_b64 s5, vcc
	v_cmp_ge_u32_e32 vcc, v72, v3
	s_add_i32 s4, s4, s5
	s_bcnt1_i32_b64 s5, vcc
	v_cmp_ge_u32_e32 vcc, v75, v3
	s_add_i32 s4, s4, s5
	s_bcnt1_i32_b64 s5, vcc
	v_cmp_ge_u32_e32 vcc, v74, v3
	s_add_i32 s4, s4, s5
	s_bcnt1_i32_b64 s5, vcc
	v_cmp_ge_u32_e32 vcc, v77, v3
	s_add_i32 s4, s4, s5
	s_bcnt1_i32_b64 s5, vcc
	v_cmp_ge_u32_e32 vcc, v76, v3
	s_add_i32 s4, s4, s5
	s_bcnt1_i32_b64 s5, vcc
	v_cmp_ge_u32_e32 vcc, v79, v3
	s_add_i32 s4, s4, s5
	s_bcnt1_i32_b64 s5, vcc
	v_cmp_ge_u32_e32 vcc, v78, v3
	s_add_i32 s4, s4, s5
	s_bcnt1_i32_b64 s5, vcc
	v_cmp_ge_u32_e32 vcc, v81, v3
	s_add_i32 s4, s4, s5
	s_bcnt1_i32_b64 s5, vcc
	v_cmp_ge_u32_e32 vcc, v80, v3
	s_add_i32 s4, s4, s5
	s_bcnt1_i32_b64 s5, vcc
	v_cmp_ge_u32_e32 vcc, v83, v3
	s_add_i32 s4, s4, s5
	s_bcnt1_i32_b64 s5, vcc
	v_cmp_ge_u32_e32 vcc, v82, v3
	s_add_i32 s4, s4, s5
	s_bcnt1_i32_b64 s5, vcc
	v_cmp_ge_u32_e32 vcc, v85, v3
	s_add_i32 s4, s4, s5
	s_bcnt1_i32_b64 s5, vcc
	v_cmp_ge_u32_e32 vcc, v84, v3
	s_add_i32 s4, s4, s5
	s_bcnt1_i32_b64 s5, vcc
	s_add_i32 s4, s4, s5
	s_cmpk_gt_u32 s61, 0x13ff
	s_cselect_b64 s[10:11], -1, 0
	s_cmpk_lt_u32 s61, 0x1400
	s_cbranch_scc0 .LBB0_3593

.LBB0_3364:
	v_cmp_ge_u32_e32 vcc, v103, v3
	s_bcnt1_i32_b64 s5, vcc
	v_cmp_ge_u32_e32 vcc, v102, v3
	s_add_i32 s4, s4, s5
	s_bcnt1_i32_b64 s5, vcc
	v_cmp_ge_u32_e32 vcc, v105, v3
	s_add_i32 s4, s4, s5
	s_bcnt1_i32_b64 s5, vcc
	v_cmp_ge_u32_e32 vcc, v104, v3
	s_add_i32 s4, s4, s5
	s_bcnt1_i32_b64 s5, vcc
	v_cmp_ge_u32_e32 vcc, v107, v3
	s_add_i32 s4, s4, s5
	s_bcnt1_i32_b64 s5, vcc
	v_cmp_ge_u32_e32 vcc, v106, v3
	s_add_i32 s4, s4, s5
	s_bcnt1_i32_b64 s5, vcc
	v_cmp_ge_u32_e32 vcc, v109, v3
	s_add_i32 s4, s4, s5
	s_bcnt1_i32_b64 s5, vcc
	v_cmp_ge_u32_e32 vcc, v108, v3
	s_add_i32 s4, s4, s5
	s_bcnt1_i32_b64 s5, vcc
	v_cmp_ge_u32_e32 vcc, v111, v3
	s_add_i32 s4, s4, s5
	s_bcnt1_i32_b64 s5, vcc
	v_cmp_ge_u32_e32 vcc, v110, v3
	s_add_i32 s4, s4, s5
	s_bcnt1_i32_b64 s5, vcc
	v_cmp_ge_u32_e32 vcc, v113, v3
	s_add_i32 s4, s4, s5
	s_bcnt1_i32_b64 s5, vcc
	v_cmp_ge_u32_e32 vcc, v112, v3
	s_add_i32 s4, s4, s5
	s_bcnt1_i32_b64 s5, vcc
	v_cmp_ge_u32_e32 vcc, v115, v3
	s_add_i32 s4, s4, s5
	s_bcnt1_i32_b64 s5, vcc
	v_cmp_ge_u32_e32 vcc, v114, v3
	s_add_i32 s4, s4, s5
	s_bcnt1_i32_b64 s5, vcc
	v_cmp_ge_u32_e32 vcc, v117, v3
	s_add_i32 s4, s4, s5
	s_bcnt1_i32_b64 s5, vcc
	v_cmp_ge_u32_e32 vcc, v116, v3
	s_add_i32 s4, s4, s5
	s_bcnt1_i32_b64 s5, vcc
	s_add_i32 s4, s4, s5
	s_cmpk_gt_u32 s61, 0x1bff
	s_cselect_b64 s[16:17], -1, 0
	s_cmpk_lt_u32 s61, 0x1c00
	s_cbranch_scc0 .LBB0_3595
	s_branch .LBB0_3596

.LBB0_3368:
	s_cmp_gt_i32 s30, -1
	s_cselect_b64 s[6:7], -1, 0
	s_xor_b64 s[8:9], s[12:13], -1
	s_and_b64 s[6:7], s[8:9], s[6:7]
	s_sub_i32 s4, s22, s5
	s_cmpk_gt_i32 s4, 0x200
	s_cselect_b64 s[8:9], -1, 0
	s_and_b64 s[6:7], s[6:7], s[8:9]
	s_andn2_b64 vcc, exec, s[6:7]
	s_mov_b64 s[6:7], -1
	s_cbranch_vccnz .LBB0_3367
	v_lshl_or_b32 v3, 1, s30, v2
	s_waitcnt vmcnt(0) lgkmcnt(0)
	v_cmp_ge_u32_e32 vcc, v19, v3
	s_bcnt1_i32_b64 s4, vcc
	v_cmp_ge_u32_e32 vcc, v13, v3
	s_bcnt1_i32_b64 s6, vcc
	v_cmp_ge_u32_e32 vcc, v20, v3
	s_add_i32 s4, s6, s4
	s_bcnt1_i32_b64 s6, vcc
	v_cmp_ge_u32_e32 vcc, v12, v3
	s_add_i32 s4, s4, s6
	s_bcnt1_i32_b64 s6, vcc
	v_cmp_ge_u32_e32 vcc, v18, v3
	s_add_i32 s4, s4, s6
	s_bcnt1_i32_b64 s6, vcc
	v_cmp_ge_u32_e32 vcc, v10, v3
	s_add_i32 s4, s4, s6
	s_bcnt1_i32_b64 s6, vcc
	v_cmp_ge_u32_e32 vcc, v17, v3
	s_add_i32 s4, s4, s6
	s_bcnt1_i32_b64 s6, vcc
	v_cmp_ge_u32_e32 vcc, v9, v3
	s_add_i32 s4, s4, s6
	s_bcnt1_i32_b64 s6, vcc
	v_cmp_ge_u32_e32 vcc, v16, v3
	s_add_i32 s4, s4, s6
	s_bcnt1_i32_b64 s6, vcc
	v_cmp_ge_u32_e32 vcc, v8, v3
	s_add_i32 s4, s4, s6
	s_bcnt1_i32_b64 s6, vcc
	v_cmp_ge_u32_e32 vcc, v15, v3
	s_add_i32 s4, s4, s6
	s_bcnt1_i32_b64 s6, vcc
	v_cmp_ge_u32_e32 vcc, v7, v3
	s_add_i32 s4, s4, s6
	s_bcnt1_i32_b64 s6, vcc
	v_cmp_ge_u32_e32 vcc, v14, v3
	s_add_i32 s4, s4, s6
	s_bcnt1_i32_b64 s6, vcc
	v_cmp_ge_u32_e32 vcc, v5, v3
	s_add_i32 s4, s4, s6
	s_bcnt1_i32_b64 s6, vcc
	v_cmp_ge_u32_e32 vcc, v11, v3
	s_add_i32 s4, s4, s6
	s_bcnt1_i32_b64 s6, vcc
	v_cmp_ge_u32_e32 vcc, v4, v3
	s_add_i32 s4, s4, s6
	s_bcnt1_i32_b64 s6, vcc
	s_andn2_b64 vcc, exec, s[68:69]
	s_add_i32 s4, s4, s6
	s_cbranch_vccnz .LBB0_3378
	v_cmp_ge_u32_e32 vcc, v22, v3
	s_bcnt1_i32_b64 s6, vcc
	v_cmp_ge_u32_e32 vcc, v21, v3
	s_add_i32 s4, s4, s6
	s_bcnt1_i32_b64 s6, vcc
	v_cmp_ge_u32_e32 vcc, v24, v3
	s_add_i32 s4, s4, s6
	s_bcnt1_i32_b64 s6, vcc
	v_cmp_ge_u32_e32 vcc, v23, v3
	s_add_i32 s4, s4, s6
	s_bcnt1_i32_b64 s6, vcc
	v_cmp_ge_u32_e32 vcc, v26, v3
	s_add_i32 s4, s4, s6
	s_bcnt1_i32_b64 s6, vcc
	v_cmp_ge_u32_e32 vcc, v25, v3
	s_add_i32 s4, s4, s6
	s_bcnt1_i32_b64 s6, vcc
	v_cmp_ge_u32_e32 vcc, v28, v3
	s_add_i32 s4, s4, s6
	s_bcnt1_i32_b64 s6, vcc
	v_cmp_ge_u32_e32 vcc, v27, v3
	s_add_i32 s4, s4, s6
	s_bcnt1_i32_b64 s6, vcc
	v_cmp_ge_u32_e32 vcc, v31, v3
	s_add_i32 s4, s4, s6
	s_bcnt1_i32_b64 s6, vcc
	v_cmp_ge_u32_e32 vcc, v29, v3
	s_add_i32 s4, s4, s6
	s_bcnt1_i32_b64 s6, vcc
	v_cmp_ge_u32_e32 vcc, v33, v3
	s_add_i32 s4, s4, s6
	s_bcnt1_i32_b64 s6, vcc
	v_cmp_ge_u32_e32 vcc, v32, v3
	s_add_i32 s4, s4, s6
	s_bcnt1_i32_b64 s6, vcc
	v_cmp_ge_u32_e32 vcc, v35, v3
	s_add_i32 s4, s4, s6
	s_bcnt1_i32_b64 s6, vcc
	v_cmp_ge_u32_e32 vcc, v34, v3
	s_add_i32 s4, s4, s6
	s_bcnt1_i32_b64 s6, vcc
	v_cmp_ge_u32_e32 vcc, v37, v3
	s_add_i32 s4, s4, s6
	s_bcnt1_i32_b64 s6, vcc
	v_cmp_ge_u32_e32 vcc, v36, v3
	s_add_i32 s4, s4, s6
	s_bcnt1_i32_b64 s6, vcc
	s_add_i32 s4, s4, s6
	s_andn2_b64 vcc, exec, s[54:55]
	s_cbranch_vccz .LBB0_3379

.LBB0_3372:
	v_cmp_ge_u32_e32 vcc, v55, v3
	s_bcnt1_i32_b64 s6, vcc
	v_cmp_ge_u32_e32 vcc, v54, v3
	s_add_i32 s4, s4, s6
	s_bcnt1_i32_b64 s6, vcc
	v_cmp_ge_u32_e32 vcc, v57, v3
	s_add_i32 s4, s4, s6
	s_bcnt1_i32_b64 s6, vcc
	v_cmp_ge_u32_e32 vcc, v56, v3
	s_add_i32 s4, s4, s6
	s_bcnt1_i32_b64 s6, vcc
	v_cmp_ge_u32_e32 vcc, v59, v3
	s_add_i32 s4, s4, s6
	s_bcnt1_i32_b64 s6, vcc
	v_cmp_ge_u32_e32 vcc, v58, v3
	s_add_i32 s4, s4, s6
	s_bcnt1_i32_b64 s6, vcc
	v_cmp_ge_u32_e32 vcc, v61, v3
	s_add_i32 s4, s4, s6
	s_bcnt1_i32_b64 s6, vcc
	v_cmp_ge_u32_e32 vcc, v60, v3
	s_add_i32 s4, s4, s6
	s_bcnt1_i32_b64 s6, vcc
	v_cmp_ge_u32_e32 vcc, v63, v3
	s_add_i32 s4, s4, s6
	s_bcnt1_i32_b64 s6, vcc
	v_cmp_ge_u32_e32 vcc, v62, v3
	s_add_i32 s4, s4, s6
	s_bcnt1_i32_b64 s6, vcc
	v_cmp_ge_u32_e32 vcc, v65, v3
	s_add_i32 s4, s4, s6
	s_bcnt1_i32_b64 s6, vcc
	v_cmp_ge_u32_e32 vcc, v64, v3
	s_add_i32 s4, s4, s6
	s_bcnt1_i32_b64 s6, vcc
	v_cmp_ge_u32_e32 vcc, v67, v3
	s_add_i32 s4, s4, s6
	s_bcnt1_i32_b64 s6, vcc
	v_cmp_ge_u32_e32 vcc, v66, v3
	s_add_i32 s4, s4, s6
	s_bcnt1_i32_b64 s6, vcc
	v_cmp_ge_u32_e32 vcc, v69, v3
	s_add_i32 s4, s4, s6
	s_bcnt1_i32_b64 s6, vcc
	v_cmp_ge_u32_e32 vcc, v68, v3
	s_add_i32 s4, s4, s6
	s_bcnt1_i32_b64 s6, vcc
	s_add_i32 s4, s4, s6
	s_andn2_b64 vcc, exec, s[96:97]
	s_cbranch_vccz .LBB0_3381

.LBB0_3374:
	v_cmp_ge_u32_e32 vcc, v87, v3
	s_bcnt1_i32_b64 s6, vcc
	v_cmp_ge_u32_e32 vcc, v86, v3
	s_add_i32 s4, s4, s6
	s_bcnt1_i32_b64 s6, vcc
	v_cmp_ge_u32_e32 vcc, v89, v3
	s_add_i32 s4, s4, s6
	s_bcnt1_i32_b64 s6, vcc
	v_cmp_ge_u32_e32 vcc, v88, v3
	s_add_i32 s4, s4, s6
	s_bcnt1_i32_b64 s6, vcc
	v_cmp_ge_u32_e32 vcc, v91, v3
	s_add_i32 s4, s4, s6
	s_bcnt1_i32_b64 s6, vcc
	v_cmp_ge_u32_e32 vcc, v90, v3
	s_add_i32 s4, s4, s6
	s_bcnt1_i32_b64 s6, vcc
	v_cmp_ge_u32_e32 vcc, v93, v3
	s_add_i32 s4, s4, s6
	s_bcnt1_i32_b64 s6, vcc
	v_cmp_ge_u32_e32 vcc, v92, v3
	s_add_i32 s4, s4, s6
	s_bcnt1_i32_b64 s6, vcc
	v_cmp_ge_u32_e32 vcc, v95, v3
	s_add_i32 s4, s4, s6
	s_bcnt1_i32_b64 s6, vcc
	v_cmp_ge_u32_e32 vcc, v94, v3
	s_add_i32 s4, s4, s6
	s_bcnt1_i32_b64 s6, vcc
	v_cmp_ge_u32_e32 vcc, v97, v3
	s_add_i32 s4, s4, s6
	s_bcnt1_i32_b64 s6, vcc
	v_cmp_ge_u32_e32 vcc, v96, v3
	s_add_i32 s4, s4, s6
	s_bcnt1_i32_b64 s6, vcc
	v_cmp_ge_u32_e32 vcc, v99, v3
	s_add_i32 s4, s4, s6
	s_bcnt1_i32_b64 s6, vcc
	v_cmp_ge_u32_e32 vcc, v98, v3
	s_add_i32 s4, s4, s6
	s_bcnt1_i32_b64 s6, vcc
	v_cmp_ge_u32_e32 vcc, v101, v3
	s_add_i32 s4, s4, s6
	s_bcnt1_i32_b64 s6, vcc
	v_cmp_ge_u32_e32 vcc, v100, v3
	s_add_i32 s4, s4, s6
	s_bcnt1_i32_b64 s6, vcc
	s_add_i32 s4, s4, s6
	s_andn2_b64 vcc, exec, s[66:67]
	s_cbranch_vccz .LBB0_3383

.LBB0_3379:
	v_cmp_ge_u32_e32 vcc, v39, v3
	s_bcnt1_i32_b64 s6, vcc
	v_cmp_ge_u32_e32 vcc, v38, v3
	s_add_i32 s4, s4, s6
	s_bcnt1_i32_b64 s6, vcc
	v_cmp_ge_u32_e32 vcc, v41, v3
	s_add_i32 s4, s4, s6
	s_bcnt1_i32_b64 s6, vcc
	v_cmp_ge_u32_e32 vcc, v40, v3
	s_add_i32 s4, s4, s6
	s_bcnt1_i32_b64 s6, vcc
	v_cmp_ge_u32_e32 vcc, v43, v3
	s_add_i32 s4, s4, s6
	s_bcnt1_i32_b64 s6, vcc
	v_cmp_ge_u32_e32 vcc, v42, v3
	s_add_i32 s4, s4, s6
	s_bcnt1_i32_b64 s6, vcc
	v_cmp_ge_u32_e32 vcc, v45, v3
	s_add_i32 s4, s4, s6
	s_bcnt1_i32_b64 s6, vcc
	v_cmp_ge_u32_e32 vcc, v44, v3
	s_add_i32 s4, s4, s6
	s_bcnt1_i32_b64 s6, vcc
	v_cmp_ge_u32_e32 vcc, v47, v3
	s_add_i32 s4, s4, s6
	s_bcnt1_i32_b64 s6, vcc
	v_cmp_ge_u32_e32 vcc, v46, v3
	s_add_i32 s4, s4, s6
	s_bcnt1_i32_b64 s6, vcc
	v_cmp_ge_u32_e32 vcc, v49, v3
	s_add_i32 s4, s4, s6
	s_bcnt1_i32_b64 s6, vcc
	v_cmp_ge_u32_e32 vcc, v48, v3
	s_add_i32 s4, s4, s6
	s_bcnt1_i32_b64 s6, vcc
	v_cmp_ge_u32_e32 vcc, v51, v3
	s_add_i32 s4, s4, s6
	s_bcnt1_i32_b64 s6, vcc
	v_cmp_ge_u32_e32 vcc, v50, v3
	s_add_i32 s4, s4, s6
	s_bcnt1_i32_b64 s6, vcc
	v_cmp_ge_u32_e32 vcc, v53, v3
	s_add_i32 s4, s4, s6
	s_bcnt1_i32_b64 s6, vcc
	v_cmp_ge_u32_e32 vcc, v52, v3
	s_add_i32 s4, s4, s6
	s_bcnt1_i32_b64 s6, vcc
	s_add_i32 s4, s4, s6
	s_andn2_b64 vcc, exec, s[0:1]
	s_cbranch_vccz .LBB0_3372

.LBB0_3381:
	v_cmp_ge_u32_e32 vcc, v71, v3
	s_bcnt1_i32_b64 s6, vcc
	v_cmp_ge_u32_e32 vcc, v70, v3
	s_add_i32 s4, s4, s6
	s_bcnt1_i32_b64 s6, vcc
	v_cmp_ge_u32_e32 vcc, v73, v3
	s_add_i32 s4, s4, s6
	s_bcnt1_i32_b64 s6, vcc
	v_cmp_ge_u32_e32 vcc, v72, v3
	s_add_i32 s4, s4, s6
	s_bcnt1_i32_b64 s6, vcc
	v_cmp_ge_u32_e32 vcc, v75, v3
	s_add_i32 s4, s4, s6
	s_bcnt1_i32_b64 s6, vcc
	v_cmp_ge_u32_e32 vcc, v74, v3
	s_add_i32 s4, s4, s6
	s_bcnt1_i32_b64 s6, vcc
	v_cmp_ge_u32_e32 vcc, v77, v3
	s_add_i32 s4, s4, s6
	s_bcnt1_i32_b64 s6, vcc
	v_cmp_ge_u32_e32 vcc, v76, v3
	s_add_i32 s4, s4, s6
	s_bcnt1_i32_b64 s6, vcc
	v_cmp_ge_u32_e32 vcc, v79, v3
	s_add_i32 s4, s4, s6
	s_bcnt1_i32_b64 s6, vcc
	v_cmp_ge_u32_e32 vcc, v78, v3
	s_add_i32 s4, s4, s6
	s_bcnt1_i32_b64 s6, vcc
	v_cmp_ge_u32_e32 vcc, v81, v3
	s_add_i32 s4, s4, s6
	s_bcnt1_i32_b64 s6, vcc
	v_cmp_ge_u32_e32 vcc, v80, v3
	s_add_i32 s4, s4, s6
	s_bcnt1_i32_b64 s6, vcc
	v_cmp_ge_u32_e32 vcc, v83, v3
	s_add_i32 s4, s4, s6
	s_bcnt1_i32_b64 s6, vcc
	v_cmp_ge_u32_e32 vcc, v82, v3
	s_add_i32 s4, s4, s6
	s_bcnt1_i32_b64 s6, vcc
	v_cmp_ge_u32_e32 vcc, v85, v3
	s_add_i32 s4, s4, s6
	s_bcnt1_i32_b64 s6, vcc
	v_cmp_ge_u32_e32 vcc, v84, v3
	s_add_i32 s4, s4, s6
	s_bcnt1_i32_b64 s6, vcc
	s_add_i32 s4, s4, s6
	s_andn2_b64 vcc, exec, s[94:95]
	s_cbranch_vccz .LBB0_3374

.LBB0_3383:
	v_cmp_ge_u32_e32 vcc, v103, v3
	s_bcnt1_i32_b64 s6, vcc
	v_cmp_ge_u32_e32 vcc, v102, v3
	s_add_i32 s4, s4, s6
	s_bcnt1_i32_b64 s6, vcc
	v_cmp_ge_u32_e32 vcc, v105, v3
	s_add_i32 s4, s4, s6
	s_bcnt1_i32_b64 s6, vcc
	v_cmp_ge_u32_e32 vcc, v104, v3
	s_add_i32 s4, s4, s6
	s_bcnt1_i32_b64 s6, vcc
	v_cmp_ge_u32_e32 vcc, v107, v3
	s_add_i32 s4, s4, s6
	s_bcnt1_i32_b64 s6, vcc
	v_cmp_ge_u32_e32 vcc, v106, v3
	s_add_i32 s4, s4, s6
	s_bcnt1_i32_b64 s6, vcc
	v_cmp_ge_u32_e32 vcc, v109, v3
	s_add_i32 s4, s4, s6
	s_bcnt1_i32_b64 s6, vcc
	v_cmp_ge_u32_e32 vcc, v108, v3
	s_add_i32 s4, s4, s6
	s_bcnt1_i32_b64 s6, vcc
	v_cmp_ge_u32_e32 vcc, v111, v3
	s_add_i32 s4, s4, s6
	s_bcnt1_i32_b64 s6, vcc
	v_cmp_ge_u32_e32 vcc, v110, v3
	s_add_i32 s4, s4, s6
	s_bcnt1_i32_b64 s6, vcc
	v_cmp_ge_u32_e32 vcc, v113, v3
	s_add_i32 s4, s4, s6
	s_bcnt1_i32_b64 s6, vcc
	v_cmp_ge_u32_e32 vcc, v112, v3
	s_add_i32 s4, s4, s6
	s_bcnt1_i32_b64 s6, vcc
	v_cmp_ge_u32_e32 vcc, v115, v3
	s_add_i32 s4, s4, s6
	s_bcnt1_i32_b64 s6, vcc
	v_cmp_ge_u32_e32 vcc, v114, v3
	s_add_i32 s4, s4, s6
	s_bcnt1_i32_b64 s6, vcc
	v_cmp_ge_u32_e32 vcc, v117, v3
	s_add_i32 s4, s4, s6
	s_bcnt1_i32_b64 s6, vcc
	v_cmp_ge_u32_e32 vcc, v116, v3
	s_add_i32 s4, s4, s6
	s_bcnt1_i32_b64 s6, vcc
	s_add_i32 s4, s4, s6
	s_andn2_b64 vcc, exec, s[64:65]
	s_cbranch_vccz .LBB0_3376

.LBB0_3591:
	v_cmp_ge_u32_e32 vcc, v55, v3
	s_bcnt1_i32_b64 s5, vcc
	v_cmp_ge_u32_e32 vcc, v54, v3
	s_add_i32 s4, s4, s5
	s_bcnt1_i32_b64 s5, vcc
	v_cmp_ge_u32_e32 vcc, v57, v3
	s_add_i32 s4, s4, s5
	s_bcnt1_i32_b64 s5, vcc
	v_cmp_ge_u32_e32 vcc, v56, v3
	s_add_i32 s4, s4, s5
	s_bcnt1_i32_b64 s5, vcc
	v_cmp_ge_u32_e32 vcc, v59, v3
	s_add_i32 s4, s4, s5
	s_bcnt1_i32_b64 s5, vcc
	v_cmp_ge_u32_e32 vcc, v58, v3
	s_add_i32 s4, s4, s5
	s_bcnt1_i32_b64 s5, vcc
	v_cmp_ge_u32_e32 vcc, v61, v3
	s_add_i32 s4, s4, s5
	s_bcnt1_i32_b64 s5, vcc
	v_cmp_ge_u32_e32 vcc, v60, v3
	s_add_i32 s4, s4, s5
	s_bcnt1_i32_b64 s5, vcc
	v_cmp_ge_u32_e32 vcc, v63, v3
	s_add_i32 s4, s4, s5
	s_bcnt1_i32_b64 s5, vcc
	v_cmp_ge_u32_e32 vcc, v62, v3
	s_add_i32 s4, s4, s5
	s_bcnt1_i32_b64 s5, vcc
	v_cmp_ge_u32_e32 vcc, v65, v3
	s_add_i32 s4, s4, s5
	s_bcnt1_i32_b64 s5, vcc
	v_cmp_ge_u32_e32 vcc, v64, v3
	s_add_i32 s4, s4, s5
	s_bcnt1_i32_b64 s5, vcc
	v_cmp_ge_u32_e32 vcc, v67, v3
	s_add_i32 s4, s4, s5
	s_bcnt1_i32_b64 s5, vcc
	v_cmp_ge_u32_e32 vcc, v66, v3
	s_add_i32 s4, s4, s5
	s_bcnt1_i32_b64 s5, vcc
	v_cmp_ge_u32_e32 vcc, v69, v3
	s_add_i32 s4, s4, s5
	s_bcnt1_i32_b64 s5, vcc
	v_cmp_ge_u32_e32 vcc, v68, v3
	s_add_i32 s4, s4, s5
	s_bcnt1_i32_b64 s5, vcc
	s_add_i32 s4, s4, s5
	s_cmpk_gt_u32 s61, 0xfff
	s_cselect_b64 s[8:9], -1, 0
	s_cmpk_lt_u32 s61, 0x1000
	s_cbranch_scc0 .LBB0_3362

.LBB0_3593:
	v_cmp_ge_u32_e32 vcc, v87, v3
	s_bcnt1_i32_b64 s5, vcc
	v_cmp_ge_u32_e32 vcc, v86, v3
	s_add_i32 s4, s4, s5
	s_bcnt1_i32_b64 s5, vcc
	v_cmp_ge_u32_e32 vcc, v89, v3
	s_add_i32 s4, s4, s5
	s_bcnt1_i32_b64 s5, vcc
	v_cmp_ge_u32_e32 vcc, v88, v3
	s_add_i32 s4, s4, s5
	s_bcnt1_i32_b64 s5, vcc
	v_cmp_ge_u32_e32 vcc, v91, v3
	s_add_i32 s4, s4, s5
	s_bcnt1_i32_b64 s5, vcc
	v_cmp_ge_u32_e32 vcc, v90, v3
	s_add_i32 s4, s4, s5
	s_bcnt1_i32_b64 s5, vcc
	v_cmp_ge_u32_e32 vcc, v93, v3
	s_add_i32 s4, s4, s5
	s_bcnt1_i32_b64 s5, vcc
	v_cmp_ge_u32_e32 vcc, v92, v3
	s_add_i32 s4, s4, s5
	s_bcnt1_i32_b64 s5, vcc
	v_cmp_ge_u32_e32 vcc, v95, v3
	s_add_i32 s4, s4, s5
	s_bcnt1_i32_b64 s5, vcc
	v_cmp_ge_u32_e32 vcc, v94, v3
	s_add_i32 s4, s4, s5
	s_bcnt1_i32_b64 s5, vcc
	v_cmp_ge_u32_e32 vcc, v97, v3
	s_add_i32 s4, s4, s5
	s_bcnt1_i32_b64 s5, vcc
	v_cmp_ge_u32_e32 vcc, v96, v3
	s_add_i32 s4, s4, s5
	s_bcnt1_i32_b64 s5, vcc
	v_cmp_ge_u32_e32 vcc, v99, v3
	s_add_i32 s4, s4, s5
	s_bcnt1_i32_b64 s5, vcc
	v_cmp_ge_u32_e32 vcc, v98, v3
	s_add_i32 s4, s4, s5
	s_bcnt1_i32_b64 s5, vcc
	v_cmp_ge_u32_e32 vcc, v101, v3
	s_add_i32 s4, s4, s5
	s_bcnt1_i32_b64 s5, vcc
	v_cmp_ge_u32_e32 vcc, v100, v3
	s_add_i32 s4, s4, s5
	s_bcnt1_i32_b64 s5, vcc
	s_add_i32 s4, s4, s5
	s_cmpk_gt_u32 s61, 0x17ff
	s_cselect_b64 s[14:15], -1, 0
	s_cmpk_lt_u32 s61, 0x1800
	s_cbranch_scc0 .LBB0_3364

.LBB0_3597:
	v_add_u32_e32 v135, s24, v3
	v_cmp_ge_u32_e32 vcc, v19, v135
	s_bcnt1_i32_b64 s5, vcc
	v_cmp_ge_u32_e32 vcc, v13, v135
	s_bcnt1_i32_b64 s20, vcc
	v_cmp_ge_u32_e32 vcc, v20, v135
	s_add_i32 s5, s20, s5
	s_bcnt1_i32_b64 s20, vcc
	v_cmp_ge_u32_e32 vcc, v12, v135
	s_add_i32 s5, s5, s20
	s_bcnt1_i32_b64 s20, vcc
	v_cmp_ge_u32_e32 vcc, v18, v135
	s_add_i32 s5, s5, s20
	s_bcnt1_i32_b64 s20, vcc
	v_cmp_ge_u32_e32 vcc, v10, v135
	s_add_i32 s5, s5, s20
	s_bcnt1_i32_b64 s20, vcc
	v_cmp_ge_u32_e32 vcc, v17, v135
	s_add_i32 s5, s5, s20
	s_bcnt1_i32_b64 s20, vcc
	v_cmp_ge_u32_e32 vcc, v9, v135
	s_add_i32 s5, s5, s20
	s_bcnt1_i32_b64 s20, vcc
	v_cmp_ge_u32_e32 vcc, v16, v135
	s_add_i32 s5, s5, s20
	s_bcnt1_i32_b64 s20, vcc
	v_cmp_ge_u32_e32 vcc, v8, v135
	s_add_i32 s5, s5, s20
	s_bcnt1_i32_b64 s20, vcc
	v_cmp_ge_u32_e32 vcc, v15, v135
	s_add_i32 s5, s5, s20
	s_bcnt1_i32_b64 s20, vcc
	v_cmp_ge_u32_e32 vcc, v7, v135
	s_add_i32 s5, s5, s20
	s_bcnt1_i32_b64 s20, vcc
	v_cmp_ge_u32_e32 vcc, v14, v135
	s_add_i32 s5, s5, s20
	s_bcnt1_i32_b64 s20, vcc
	v_cmp_ge_u32_e32 vcc, v5, v135
	s_add_i32 s5, s5, s20
	s_bcnt1_i32_b64 s20, vcc
	v_cmp_ge_u32_e32 vcc, v11, v135
	s_add_i32 s5, s5, s20
	s_bcnt1_i32_b64 s20, vcc
	v_cmp_ge_u32_e32 vcc, v4, v135
	s_add_i32 s5, s5, s20
	s_bcnt1_i32_b64 s20, vcc
	v_cmp_ge_u32_e32 vcc, v22, v135
	s_add_i32 s5, s5, s20
	s_bcnt1_i32_b64 s20, vcc
	v_cmp_ge_u32_e32 vcc, v21, v135
	s_add_i32 s5, s5, s20
	s_bcnt1_i32_b64 s20, vcc
	v_cmp_ge_u32_e32 vcc, v24, v135
	s_add_i32 s5, s5, s20
	s_bcnt1_i32_b64 s20, vcc
	v_cmp_ge_u32_e32 vcc, v23, v135
	s_add_i32 s5, s5, s20
	s_bcnt1_i32_b64 s20, vcc
	v_cmp_ge_u32_e32 vcc, v26, v135
	s_add_i32 s5, s5, s20
	s_bcnt1_i32_b64 s20, vcc
	v_cmp_ge_u32_e32 vcc, v25, v135
	s_add_i32 s5, s5, s20
	s_bcnt1_i32_b64 s20, vcc
	v_cmp_ge_u32_e32 vcc, v28, v135
	s_add_i32 s5, s5, s20
	s_bcnt1_i32_b64 s20, vcc
	v_cmp_ge_u32_e32 vcc, v27, v135
	s_add_i32 s5, s5, s20
	s_bcnt1_i32_b64 s20, vcc
	v_cmp_ge_u32_e32 vcc, v31, v135
	s_add_i32 s5, s5, s20
	s_bcnt1_i32_b64 s20, vcc
	v_cmp_ge_u32_e32 vcc, v29, v135
	s_add_i32 s5, s5, s20
	s_bcnt1_i32_b64 s20, vcc
	v_cmp_ge_u32_e32 vcc, v33, v135
	s_add_i32 s5, s5, s20
	s_bcnt1_i32_b64 s20, vcc
	v_cmp_ge_u32_e32 vcc, v32, v135
	s_add_i32 s5, s5, s20
	s_bcnt1_i32_b64 s20, vcc
	v_cmp_ge_u32_e32 vcc, v35, v135
	s_add_i32 s5, s5, s20
	s_bcnt1_i32_b64 s20, vcc
	v_cmp_ge_u32_e32 vcc, v34, v135
	s_add_i32 s5, s5, s20
	s_bcnt1_i32_b64 s20, vcc
	v_cmp_ge_u32_e32 vcc, v37, v135
	s_add_i32 s5, s5, s20
	s_bcnt1_i32_b64 s20, vcc
	v_cmp_ge_u32_e32 vcc, v36, v135
	s_add_i32 s5, s5, s20
	s_bcnt1_i32_b64 s20, vcc
	s_andn2_b64 vcc, exec, s[0:1]
	s_add_i32 s28, s5, s20
	s_cbranch_vccnz .LBB0_3605
	v_cmp_ge_u32_e32 vcc, v39, v135
	s_bcnt1_i32_b64 s5, vcc
	v_cmp_ge_u32_e32 vcc, v38, v135
	s_add_i32 s5, s28, s5
	s_bcnt1_i32_b64 s20, vcc
	v_cmp_ge_u32_e32 vcc, v41, v135
	s_add_i32 s5, s5, s20
	s_bcnt1_i32_b64 s20, vcc
	v_cmp_ge_u32_e32 vcc, v40, v135
	s_add_i32 s5, s5, s20
	s_bcnt1_i32_b64 s20, vcc
	v_cmp_ge_u32_e32 vcc, v43, v135
	s_add_i32 s5, s5, s20
	s_bcnt1_i32_b64 s20, vcc
	v_cmp_ge_u32_e32 vcc, v42, v135
	s_add_i32 s5, s5, s20
	s_bcnt1_i32_b64 s20, vcc
	v_cmp_ge_u32_e32 vcc, v45, v135
	s_add_i32 s5, s5, s20
	s_bcnt1_i32_b64 s20, vcc
	v_cmp_ge_u32_e32 vcc, v44, v135
	s_add_i32 s5, s5, s20
	s_bcnt1_i32_b64 s20, vcc
	v_cmp_ge_u32_e32 vcc, v47, v135
	s_add_i32 s5, s5, s20
	s_bcnt1_i32_b64 s20, vcc
	v_cmp_ge_u32_e32 vcc, v46, v135
	s_add_i32 s5, s5, s20
	s_bcnt1_i32_b64 s20, vcc
	v_cmp_ge_u32_e32 vcc, v49, v135
	s_add_i32 s5, s5, s20
	s_bcnt1_i32_b64 s20, vcc
	v_cmp_ge_u32_e32 vcc, v48, v135
	s_add_i32 s5, s5, s20
	s_bcnt1_i32_b64 s20, vcc
	v_cmp_ge_u32_e32 vcc, v51, v135
	s_add_i32 s5, s5, s20
	s_bcnt1_i32_b64 s20, vcc
	v_cmp_ge_u32_e32 vcc, v50, v135
	s_add_i32 s5, s5, s20
	s_bcnt1_i32_b64 s20, vcc
	v_cmp_ge_u32_e32 vcc, v53, v135
	s_add_i32 s5, s5, s20
	s_bcnt1_i32_b64 s20, vcc
	v_cmp_ge_u32_e32 vcc, v52, v135
	s_add_i32 s5, s5, s20
	s_bcnt1_i32_b64 s20, vcc
	s_add_i32 s28, s5, s20
	s_andn2_b64 vcc, exec, s[6:7]
	s_cbranch_vccz .LBB0_3606

.LBB0_4116:
	v_lshl_or_b32 v161, 1, v160, v134
	s_waitcnt lgkmcnt(0)
	v_cmp_ge_u32_e32 vcc, v159, v161
	s_bcnt1_i32_b64 s4, vcc
	v_cmp_ge_u32_e32 vcc, v156, v161
	s_bcnt1_i32_b64 s5, vcc
	v_cmp_ge_u32_e32 vcc, v155, v161
	s_add_i32 s4, s5, s4
	s_bcnt1_i32_b64 s5, vcc
	v_cmp_ge_u32_e32 vcc, v152, v161
	s_add_i32 s4, s4, s5
	s_bcnt1_i32_b64 s5, vcc
	v_cmp_ge_u32_e32 vcc, v151, v161
	s_add_i32 s4, s4, s5
	s_bcnt1_i32_b64 s5, vcc
	v_cmp_ge_u32_e32 vcc, v145, v161
	s_add_i32 s4, s4, s5
	s_bcnt1_i32_b64 s5, vcc
	v_cmp_ge_u32_e32 vcc, v144, v161
	s_add_i32 s4, s4, s5
	s_bcnt1_i32_b64 s5, vcc
	v_cmp_ge_u32_e32 vcc, v141, v161
	s_add_i32 s4, s4, s5
	s_bcnt1_i32_b64 s5, vcc
	v_cmp_ge_u32_e32 vcc, v140, v161
	s_add_i32 s4, s4, s5
	s_bcnt1_i32_b64 s5, vcc
	v_cmp_ge_u32_e32 vcc, v137, v161
	s_add_i32 s4, s4, s5
	s_bcnt1_i32_b64 s5, vcc
	v_cmp_ge_u32_e32 vcc, v136, v161
	s_add_i32 s4, s4, s5
	s_bcnt1_i32_b64 s5, vcc
	v_cmp_ge_u32_e32 vcc, v3, v161
	s_add_i32 s4, s4, s5
	s_bcnt1_i32_b64 s5, vcc
	s_add_i32 s4, s4, s5
	s_cmpk_gt_u32 s4, 0xff
	s_cselect_b64 vcc, -1, 0
	s_cmpk_eq_i32 s4, 0x100
	s_cselect_b64 s[30:31], -1, 0
	v_cndmask_b32_e32 v134, v134, v161, vcc
	v_subrev_co_u32_e32 v160, vcc, 1, v160
	s_or_b64 s[4:5], s[30:31], vcc
	s_or_b64 s[88:89], s[30:31], s[88:89]
	s_andn2_b64 vcc, exec, s[4:5]
	s_cbranch_vccnz .LBB0_4116
	s_branch .LBB0_4118

	.amdhsa_kernel _Z10fwd_kernel4Args
		.amdhsa_group_segment_fixed_size 256
		.amdhsa_private_segment_fixed_size 0
		.amdhsa_kernarg_size 432
		.amdhsa_user_sgpr_count 2
		.amdhsa_user_sgpr_dispatch_ptr 0
		.amdhsa_user_sgpr_queue_ptr 0
		.amdhsa_user_sgpr_kernarg_segment_ptr 1
		.amdhsa_user_sgpr_dispatch_id 0
		.amdhsa_user_sgpr_kernarg_preload_length 0
		.amdhsa_user_sgpr_kernarg_preload_offset 0
		.amdhsa_user_sgpr_private_segment_size 0
		.amdhsa_uses_dynamic_stack 0
		.amdhsa_enable_private_segment 0
		.amdhsa_system_sgpr_workgroup_id_x 1
		.amdhsa_system_sgpr_workgroup_id_y 0
		.amdhsa_system_sgpr_workgroup_id_z 0
		.amdhsa_system_sgpr_workgroup_info 0
		.amdhsa_system_vgpr_workitem_id 2
		.amdhsa_next_free_vgpr 256
		.amdhsa_next_free_sgpr 98
		.amdhsa_accum_offset 256
		.amdhsa_reserve_vcc 1
		.amdhsa_float_round_mode_32 0
		.amdhsa_float_round_mode_16_64 0
		.amdhsa_float_denorm_mode_32 3
		.amdhsa_float_denorm_mode_16_64 3
		.amdhsa_dx10_clamp 1
		.amdhsa_ieee_mode 1
		.amdhsa_fp16_overflow 0
		.amdhsa_tg_split 0
		.amdhsa_exception_fp_ieee_invalid_op 0
		.amdhsa_exception_fp_denorm_src 0
		.amdhsa_exception_fp_ieee_div_zero 0
		.amdhsa_exception_fp_ieee_overflow 0
		.amdhsa_exception_fp_ieee_underflow 0
		.amdhsa_exception_fp_ieee_inexact 0
		.amdhsa_exception_int_div_zero 0
	.end_amdhsa_kernel

amdhsa.kernels:
  - .agpr_count:     0
    .args:
      - .offset:         0
        .size:           176
        .value_kind:     by_value
      - .offset:         176
        .size:           4
        .value_kind:     hidden_block_count_x
      - .offset:         180
        .size:           4
        .value_kind:     hidden_block_count_y
      - .offset:         184
        .size:           4
        .value_kind:     hidden_block_count_z
      - .offset:         188
        .size:           2
        .value_kind:     hidden_group_size_x
      - .offset:         190
        .size:           2
        .value_kind:     hidden_group_size_y
      - .offset:         192
        .size:           2
        .value_kind:     hidden_group_size_z
      - .offset:         194
        .size:           2
        .value_kind:     hidden_remainder_x
      - .offset:         196
        .size:           2
        .value_kind:     hidden_remainder_y
      - .offset:         198
        .size:           2
        .value_kind:     hidden_remainder_z
      - .offset:         216
        .size:           8
        .value_kind:     hidden_global_offset_x
      - .offset:         224
        .size:           8
        .value_kind:     hidden_global_offset_y
      - .offset:         232
        .size:           8
        .value_kind:     hidden_global_offset_z
      - .offset:         240
        .size:           2
        .value_kind:     hidden_grid_dims
      - .offset:         264
        .size:           8
        .value_kind:     hidden_multigrid_sync_arg
      - .offset:         296
        .size:           4
        .value_kind:     hidden_dynamic_lds_size
    .group_segment_fixed_size: 256
    .kernarg_segment_align: 8
    .kernarg_segment_size: 432
    .language:       OpenCL C
    .language_version:
      - 2
      - 0
    .max_flat_workgroup_size: 512
    .name:           _Z10fwd_kernel4Args
    .private_segment_fixed_size: 0
    .sgpr_count:     104
    .sgpr_spill_count: 131
    .symbol:         _Z10fwd_kernel4Args.kd
    .uniform_work_group_size: 1
    .uses_dynamic_stack: false
    .vgpr_count:     256
    .vgpr_spill_count: 0
    .wavefront_size: 64
